# both LayerNorm phases: hand-written row loops (4 rows in flight, LN params loaded once, modulation vectors prefetched, DPP wave reductions) when grid is 256 workgroups; compiler loops kept as fallback
# speedup vs baseline: 1.0620x; 1.0116x over previous
.LBB0_537:
	s_or_b64 exec, exec, s[4:5]
	s_add_u32 s36, s28, 0x9c00000
	s_addc_u32 s37, s29, 0
	s_add_u32 s24, s28, 0x90000
	s_addc_u32 s25, s29, 0
	s_mul_i32 s84, s30, 24
	s_and_saveexec_b64 s[0:1], vcc
	s_cbranch_execz .LBB0_550
	v_mbcnt_hi_u32_b32 v1, -1, v186
	v_and_b32_e32 v4, 64, v1
	v_add_u32_e32 v4, 64, v4
	v_xor_b32_e32 v5, 32, v1
	v_cmp_lt_i32_e32 vcc, v5, v4
	s_add_u32 s12, s28, 0x18000
	s_addc_u32 s13, s29, 0
	v_cndmask_b32_e32 v5, v1, v5, vcc
	v_lshlrev_b32_e32 v92, 2, v5
	v_xor_b32_e32 v5, 16, v1
	v_cmp_lt_i32_e32 vcc, v5, v4
	s_lshl_b32 s44, s30, 4
	s_add_i32 s3, s33, s44
	v_cndmask_b32_e32 v5, v1, v5, vcc
	v_lshlrev_b32_e32 v93, 2, v5
	v_xor_b32_e32 v5, 8, v1
	v_cmp_lt_i32_e32 vcc, v5, v4
	v_add_u32_e32 v10, s3, v3
	v_ashrrev_i32_e32 v11, 31, v10
	v_cndmask_b32_e32 v5, v1, v5, vcc
	v_lshlrev_b32_e32 v94, 2, v5
	v_xor_b32_e32 v5, 4, v1
	v_cmp_lt_i32_e32 vcc, v5, v4
	v_lshlrev_b64 v[10:11], 12, v[10:11]
	v_lshlrev_b32_e32 v0, 2, v2
	v_cndmask_b32_e32 v5, v1, v5, vcc
	v_lshlrev_b32_e32 v95, 2, v5
	v_xor_b32_e32 v5, 2, v1
	v_cmp_lt_i32_e32 vcc, v5, v4
	v_mov_b32_e32 v65, 0
	v_lshlrev_b64 v[76:77], 11, v[86:87]
	v_cndmask_b32_e32 v5, v1, v5, vcc
	v_lshlrev_b32_e32 v96, 2, v5
	v_xor_b32_e32 v5, 1, v1
	v_cmp_lt_i32_e32 vcc, v5, v4
	v_lshl_or_b32 v10, v2, 4, v10
	v_lshl_add_u64 v[66:67], s[26:27], 0, v[64:65]
	v_cmp_eq_u32_e64 s[4:5], 0, v2
	v_cndmask_b32_e32 v1, v1, v5, vcc
	v_lshl_add_u64 v[68:69], s[46:47], 0, v[64:65]
	v_lshl_add_u64 v[70:71], s[48:49], 0, v[64:65]
	v_or_b32_e32 v4, 0x100, v0
	v_or_b32_e32 v6, 0x200, v0
	v_or_b32_e32 v8, 0x300, v0
	v_lshlrev_b32_e32 v64, 3, v2
	v_lshl_or_b32 v76, v2, 3, v76
	v_lshl_add_u64 v[2:3], s[26:27], 0, v[10:11]
	s_mov_b64 s[6:7], 0xc00
	v_lshlrev_b32_e32 v97, 2, v1
	v_lshl_add_u64 v[72:73], s[36:37], 0, v[64:65]
	s_ashr_i32 s45, s44, 31
	v_lshl_add_u64 v[78:79], v[2:3], 0, s[6:7]
	v_lshlrev_b32_e32 v64, 2, v0
	v_lshlrev_b32_e32 v80, 2, v4
	v_lshlrev_b32_e32 v82, 2, v6
	v_lshlrev_b32_e32 v84, 2, v8
	s_waitcnt vmcnt(0)
	v_mov_b64_e32 v[0:1], v[48:49]
	v_mov_b64_e32 v[4:5], v[52:53]
	v_mov_b64_e32 v[8:9], v[56:57]
	v_mov_b64_e32 v[12:13], v[60:61]
	v_lshlrev_b64 v[74:75], 3, v[86:87]
	s_lshl_b64 s[50:51], s[44:45], 3
	s_lshl_b64 s[52:53], s[44:45], 11
	s_lshl_b64 s[54:55], s[44:45], 12
	s_mov_b64 s[56:57], 0
	s_mov_b32 s3, 0x8000
	s_movk_i32 s45, 0x7fff
	v_mov_b32_e32 v87, 0x3727c5ac
	s_mov_b32 s64, 0x800000
	s_mov_b64 s[58:59], 0x1000
	s_mov_b32 s65, 0x9c00000
	v_mov_b64_e32 v[2:3], v[50:51]
	v_mov_b64_e32 v[6:7], v[54:55]
	v_mov_b64_e32 v[10:11], v[58:59]
	v_mov_b64_e32 v[14:15], v[62:63]
	s_cmp_lg_u32 s30, 0x100
	s_cbranch_scc1 .Lln5_orig
	v_and_b32_e32 v0, 63, v254
	v_lshrrev_b32_e32 v1, 6, v254
	v_lshlrev_b32_e32 v2, 3, v0
	v_lshlrev_b32_e32 v0, 4, v0
	v_readfirstlane_b32 s7, v1
	v_mov_b32_e32 v3, 0
	s_nop 1
	s_add_i32 s7, s33, s7
	s_lshl_b32 s6, s7, 12
	s_add_u32 s56, s26, s6
	s_addc_u32 s57, s27, 0
	s_lshl_b32 s6, s7, 11
	s_add_u32 s60, s36, s6
	s_addc_u32 s61, s37, 0
	s_lshl_b32 s6, s7, 3
	s_add_u32 s62, s24, s6
	s_addc_u32 s63, s25, 0
	s_mov_b32 s98, s12
	s_mov_b32 s99, s13
	s_add_u32 s100, s12, 0x1000
	s_addc_u32 s101, s13, 0
	global_load_dwordx4 v[188:191], v0, s[46:47]
	global_load_dwordx4 v[192:195], v0, s[46:47] offset:1024
	global_load_dwordx4 v[196:199], v0, s[46:47] offset:2048
	global_load_dwordx4 v[200:203], v0, s[46:47] offset:3072
	global_load_dwordx4 v[204:207], v0, s[48:49]
	global_load_dwordx4 v[208:211], v0, s[48:49] offset:1024
	global_load_dwordx4 v[212:215], v0, s[48:49] offset:2048
	global_load_dwordx4 v[216:219], v0, s[48:49] offset:3072
	global_load_dwordx4 v[4:7], v0, s[98:99]
	global_load_dwordx4 v[8:11], v0, s[98:99] offset:1024
	global_load_dwordx4 v[12:15], v0, s[98:99] offset:2048
	global_load_dwordx4 v[16:19], v0, s[98:99] offset:3072
	global_load_dwordx4 v[20:23], v0, s[100:101]
	global_load_dwordx4 v[24:27], v0, s[100:101] offset:1024
	global_load_dwordx4 v[28:31], v0, s[100:101] offset:2048
	global_load_dwordx4 v[32:35], v0, s[100:101] offset:3072
	s_add_u32 s98, s98, 0x3000
	s_addc_u32 s99, s99, 0
	s_add_u32 s100, s100, 0x3000
	s_addc_u32 s101, s101, 0
	global_load_dwordx4 v[68:71], v0, s[56:57]
	global_load_dwordx4 v[72:75], v0, s[56:57] offset:1024
	global_load_dwordx4 v[76:79], v0, s[56:57] offset:2048
	global_load_dwordx4 v[80:83], v0, s[56:57] offset:3072
	s_add_u32 s56, s56, 0x800000
	s_addc_u32 s57, s57, 0
	global_load_dwordx4 v[84:87], v0, s[56:57]
	global_load_dwordx4 v[88:91], v0, s[56:57] offset:1024
	global_load_dwordx4 v[92:95], v0, s[56:57] offset:2048
	global_load_dwordx4 v[96:99], v0, s[56:57] offset:3072
	s_add_u32 s56, s56, 0x800000
	s_addc_u32 s57, s57, 0
	global_load_dwordx4 v[100:103], v0, s[56:57]
	global_load_dwordx4 v[104:107], v0, s[56:57] offset:1024
	global_load_dwordx4 v[108:111], v0, s[56:57] offset:2048
	global_load_dwordx4 v[112:115], v0, s[56:57] offset:3072
	s_add_u32 s56, s56, 0x800000
	s_addc_u32 s57, s57, 0
	global_load_dwordx4 v[116:119], v0, s[56:57]
	global_load_dwordx4 v[120:123], v0, s[56:57] offset:1024
	global_load_dwordx4 v[124:127], v0, s[56:57] offset:2048
	global_load_dwordx4 v[128:131], v0, s[56:57] offset:3072
	s_add_u32 s56, s56, 0x800000
	s_addc_u32 s57, s57, 0
	s_waitcnt vmcnt(12)
	v_add_f32_e32 v220, v68, v69
	v_add_f32_e32 v221, v70, v71
	v_add_f32_e32 v222, v72, v73
	v_add_f32_e32 v223, v74, v75
	v_add_f32_e32 v224, v76, v77
	v_add_f32_e32 v225, v78, v79
	v_add_f32_e32 v226, v80, v81
	v_add_f32_e32 v227, v82, v83
	v_add_f32_e32 v220, v220, v221
	v_add_f32_e32 v222, v222, v223
	v_add_f32_e32 v224, v224, v225
	v_add_f32_e32 v226, v226, v227
	v_add_f32_e32 v220, v220, v222
	v_add_f32_e32 v224, v224, v226
	v_add_f32_e32 v220, v220, v224
	s_nop 1
	v_add_f32_dpp v220, v220, v220 quad_perm:[1,0,3,2] row_mask:0xf bank_mask:0xf
	s_nop 1
	v_add_f32_dpp v220, v220, v220 quad_perm:[2,3,0,1] row_mask:0xf bank_mask:0xf
	s_nop 1
	v_add_f32_dpp v220, v220, v220 row_half_mirror row_mask:0xf bank_mask:0xf
	s_nop 1
	v_add_f32_dpp v220, v220, v220 row_mirror row_mask:0xf bank_mask:0xf
	s_nop 1
	v_add_f32_dpp v220, v220, v220 row_bcast:15 row_mask:0xa bank_mask:0xf
	s_nop 1
	v_add_f32_dpp v220, v220, v220 row_bcast:31 row_mask:0xc bank_mask:0xf
	s_nop 1
	v_readlane_b32 s6, v220, 63
	s_nop 1
	v_mov_b32_e32 v228, s6
	v_mul_f32_e32 v228, 0x3a800000, v228
	v_sub_f32_e32 v68, v68, v228
	v_sub_f32_e32 v69, v69, v228
	v_sub_f32_e32 v70, v70, v228
	v_sub_f32_e32 v71, v71, v228
	v_sub_f32_e32 v72, v72, v228
	v_sub_f32_e32 v73, v73, v228
	v_sub_f32_e32 v74, v74, v228
	v_sub_f32_e32 v75, v75, v228
	v_sub_f32_e32 v76, v76, v228
	v_sub_f32_e32 v77, v77, v228
	v_sub_f32_e32 v78, v78, v228
	v_sub_f32_e32 v79, v79, v228
	v_sub_f32_e32 v80, v80, v228
	v_sub_f32_e32 v81, v81, v228
	v_sub_f32_e32 v82, v82, v228
	v_sub_f32_e32 v83, v83, v228
	v_mul_f32_e32 v222, v68, v68
	v_mul_f32_e32 v223, v69, v69
	v_fmac_f32_e32 v222, v70, v70
	v_fmac_f32_e32 v223, v71, v71
	v_fmac_f32_e32 v222, v72, v72
	v_fmac_f32_e32 v223, v73, v73
	v_fmac_f32_e32 v222, v74, v74
	v_fmac_f32_e32 v223, v75, v75
	v_fmac_f32_e32 v222, v76, v76
	v_fmac_f32_e32 v223, v77, v77
	v_fmac_f32_e32 v222, v78, v78
	v_fmac_f32_e32 v223, v79, v79
	v_fmac_f32_e32 v222, v80, v80
	v_fmac_f32_e32 v223, v81, v81
	v_fmac_f32_e32 v222, v82, v82
	v_fmac_f32_e32 v223, v83, v83
	v_add_f32_e32 v222, v222, v223
	s_nop 1
	v_add_f32_dpp v222, v222, v222 quad_perm:[1,0,3,2] row_mask:0xf bank_mask:0xf
	s_nop 1
	v_add_f32_dpp v222, v222, v222 quad_perm:[2,3,0,1] row_mask:0xf bank_mask:0xf
	s_nop 1
	v_add_f32_dpp v222, v222, v222 row_half_mirror row_mask:0xf bank_mask:0xf
	s_nop 1
	v_add_f32_dpp v222, v222, v222 row_mirror row_mask:0xf bank_mask:0xf
	s_nop 1
	v_add_f32_dpp v222, v222, v222 row_bcast:15 row_mask:0xa bank_mask:0xf
	s_nop 1
	v_add_f32_dpp v222, v222, v222 row_bcast:31 row_mask:0xc bank_mask:0xf
	s_nop 1
	v_readlane_b32 s6, v222, 63
	s_nop 1
	v_mov_b32_e32 v224, s6
	v_mov_b32_e32 v225, 0x3727c5ac
	v_fmac_f32_e32 v225, 0x3a800000, v224
	v_rsq_f32_e32 v229, v225
	global_load_dwordx4 v[36:39], v0, s[98:99]
	global_load_dwordx4 v[40:43], v0, s[98:99] offset:1024
	global_load_dwordx4 v[44:47], v0, s[98:99] offset:2048
	global_load_dwordx4 v[48:51], v0, s[98:99] offset:3072
	global_load_dwordx4 v[52:55], v0, s[100:101]
	global_load_dwordx4 v[56:59], v0, s[100:101] offset:1024
	global_load_dwordx4 v[60:63], v0, s[100:101] offset:2048
	global_load_dwordx4 v[64:67], v0, s[100:101] offset:3072
	s_add_u32 s98, s98, 0x3000
	s_addc_u32 s99, s99, 0
	s_add_u32 s100, s100, 0x3000
	s_addc_u32 s101, s101, 0
	s_waitcnt vmcnt(24)
	v_add_f32_e32 v20, 1.0, v20
	v_add_f32_e32 v21, 1.0, v21
	v_add_f32_e32 v22, 1.0, v22
	v_add_f32_e32 v23, 1.0, v23
	v_add_f32_e32 v24, 1.0, v24
	v_add_f32_e32 v25, 1.0, v25
	v_add_f32_e32 v26, 1.0, v26
	v_add_f32_e32 v27, 1.0, v27
	v_add_f32_e32 v28, 1.0, v28
	v_add_f32_e32 v29, 1.0, v29
	v_add_f32_e32 v30, 1.0, v30
	v_add_f32_e32 v31, 1.0, v31
	v_add_f32_e32 v32, 1.0, v32
	v_add_f32_e32 v33, 1.0, v33
	v_add_f32_e32 v34, 1.0, v34
	v_add_f32_e32 v35, 1.0, v35
	s_mov_b64 exec, 1
	global_store_dwordx2 v3, v[228:229], s[62:63]
	s_mov_b64 exec, -1
	s_add_u32 s62, s62, 0x4000
	s_addc_u32 s63, s63, 0
	v_mul_f32_e32 v68, v68, v229
	v_mul_f32_e32 v69, v69, v229
	v_mul_f32_e32 v70, v70, v229
	v_mul_f32_e32 v71, v71, v229
	v_mul_f32_e32 v72, v72, v229
	v_mul_f32_e32 v73, v73, v229
	v_mul_f32_e32 v74, v74, v229
	v_mul_f32_e32 v75, v75, v229
	v_mul_f32_e32 v76, v76, v229
	v_mul_f32_e32 v77, v77, v229
	v_mul_f32_e32 v78, v78, v229
	v_mul_f32_e32 v79, v79, v229
	v_mul_f32_e32 v80, v80, v229
	v_mul_f32_e32 v81, v81, v229
	v_mul_f32_e32 v82, v82, v229
	v_mul_f32_e32 v83, v83, v229
	v_fma_f32 v68, v68, v188, v204
	v_fma_f32 v69, v69, v189, v205
	v_fma_f32 v70, v70, v190, v206
	v_fma_f32 v71, v71, v191, v207
	v_fma_f32 v72, v72, v192, v208
	v_fma_f32 v73, v73, v193, v209
	v_fma_f32 v74, v74, v194, v210
	v_fma_f32 v75, v75, v195, v211
	v_fma_f32 v76, v76, v196, v212
	v_fma_f32 v77, v77, v197, v213
	v_fma_f32 v78, v78, v198, v214
	v_fma_f32 v79, v79, v199, v215
	v_fma_f32 v80, v80, v200, v216
	v_fma_f32 v81, v81, v201, v217
	v_fma_f32 v82, v82, v202, v218
	v_fma_f32 v83, v83, v203, v219
	v_fma_f32 v68, v68, v20, v4
	v_fma_f32 v69, v69, v21, v5
	v_fma_f32 v70, v70, v22, v6
	v_fma_f32 v71, v71, v23, v7
	v_fma_f32 v72, v72, v24, v8
	v_fma_f32 v73, v73, v25, v9
	v_fma_f32 v74, v74, v26, v10
	v_fma_f32 v75, v75, v27, v11
	v_fma_f32 v76, v76, v28, v12
	v_fma_f32 v77, v77, v29, v13
	v_fma_f32 v78, v78, v30, v14
	v_fma_f32 v79, v79, v31, v15
	v_fma_f32 v80, v80, v32, v16
	v_fma_f32 v81, v81, v33, v17
	v_fma_f32 v82, v82, v34, v18
	v_fma_f32 v83, v83, v35, v19
	v_cvt_pk_bf16_f32 v68, v68, v69
	v_cvt_pk_bf16_f32 v69, v70, v71
	v_cvt_pk_bf16_f32 v72, v72, v73
	v_cvt_pk_bf16_f32 v73, v74, v75
	v_cvt_pk_bf16_f32 v76, v76, v77
	v_cvt_pk_bf16_f32 v77, v78, v79
	v_cvt_pk_bf16_f32 v80, v80, v81
	v_cvt_pk_bf16_f32 v81, v82, v83
	global_store_dwordx2 v2, v[68:69], s[60:61]
	global_store_dwordx2 v2, v[72:73], s[60:61] offset:512
	global_store_dwordx2 v2, v[76:77], s[60:61] offset:1024
	global_store_dwordx2 v2, v[80:81], s[60:61] offset:1536
	s_add_u32 s60, s60, 0x400000
	s_addc_u32 s61, s61, 0
	s_nop 0
	global_load_dwordx4 v[68:71], v0, s[56:57]
	global_load_dwordx4 v[72:75], v0, s[56:57] offset:1024
	global_load_dwordx4 v[76:79], v0, s[56:57] offset:2048
	global_load_dwordx4 v[80:83], v0, s[56:57] offset:3072
	s_add_u32 s56, s56, 0x800000
	s_addc_u32 s57, s57, 0
	s_waitcnt vmcnt(25)
	v_add_f32_e32 v220, v84, v85
	v_add_f32_e32 v221, v86, v87
	v_add_f32_e32 v222, v88, v89
	v_add_f32_e32 v223, v90, v91
	v_add_f32_e32 v224, v92, v93
	v_add_f32_e32 v225, v94, v95
	v_add_f32_e32 v226, v96, v97
	v_add_f32_e32 v227, v98, v99
	v_add_f32_e32 v220, v220, v221
	v_add_f32_e32 v222, v222, v223
	v_add_f32_e32 v224, v224, v225
	v_add_f32_e32 v226, v226, v227
	v_add_f32_e32 v220, v220, v222
	v_add_f32_e32 v224, v224, v226
	v_add_f32_e32 v220, v220, v224
	s_nop 1
	v_add_f32_dpp v220, v220, v220 quad_perm:[1,0,3,2] row_mask:0xf bank_mask:0xf
	s_nop 1
	v_add_f32_dpp v220, v220, v220 quad_perm:[2,3,0,1] row_mask:0xf bank_mask:0xf
	s_nop 1
	v_add_f32_dpp v220, v220, v220 row_half_mirror row_mask:0xf bank_mask:0xf
	s_nop 1
	v_add_f32_dpp v220, v220, v220 row_mirror row_mask:0xf bank_mask:0xf
	s_nop 1
	v_add_f32_dpp v220, v220, v220 row_bcast:15 row_mask:0xa bank_mask:0xf
	s_nop 1
	v_add_f32_dpp v220, v220, v220 row_bcast:31 row_mask:0xc bank_mask:0xf
	s_nop 1
	v_readlane_b32 s6, v220, 63
	s_nop 1
	v_mov_b32_e32 v228, s6
	v_mul_f32_e32 v228, 0x3a800000, v228
	v_sub_f32_e32 v84, v84, v228
	v_sub_f32_e32 v85, v85, v228
	v_sub_f32_e32 v86, v86, v228
	v_sub_f32_e32 v87, v87, v228
	v_sub_f32_e32 v88, v88, v228
	v_sub_f32_e32 v89, v89, v228
	v_sub_f32_e32 v90, v90, v228
	v_sub_f32_e32 v91, v91, v228
	v_sub_f32_e32 v92, v92, v228
	v_sub_f32_e32 v93, v93, v228
	v_sub_f32_e32 v94, v94, v228
	v_sub_f32_e32 v95, v95, v228
	v_sub_f32_e32 v96, v96, v228
	v_sub_f32_e32 v97, v97, v228
	v_sub_f32_e32 v98, v98, v228
	v_sub_f32_e32 v99, v99, v228
	v_mul_f32_e32 v222, v84, v84
	v_mul_f32_e32 v223, v85, v85
	v_fmac_f32_e32 v222, v86, v86
	v_fmac_f32_e32 v223, v87, v87
	v_fmac_f32_e32 v222, v88, v88
	v_fmac_f32_e32 v223, v89, v89
	v_fmac_f32_e32 v222, v90, v90
	v_fmac_f32_e32 v223, v91, v91
	v_fmac_f32_e32 v222, v92, v92
	v_fmac_f32_e32 v223, v93, v93
	v_fmac_f32_e32 v222, v94, v94
	v_fmac_f32_e32 v223, v95, v95
	v_fmac_f32_e32 v222, v96, v96
	v_fmac_f32_e32 v223, v97, v97
	v_fmac_f32_e32 v222, v98, v98
	v_fmac_f32_e32 v223, v99, v99
	v_add_f32_e32 v222, v222, v223
	s_nop 1
	v_add_f32_dpp v222, v222, v222 quad_perm:[1,0,3,2] row_mask:0xf bank_mask:0xf
	s_nop 1
	v_add_f32_dpp v222, v222, v222 quad_perm:[2,3,0,1] row_mask:0xf bank_mask:0xf
	s_nop 1
	v_add_f32_dpp v222, v222, v222 row_half_mirror row_mask:0xf bank_mask:0xf
	s_nop 1
	v_add_f32_dpp v222, v222, v222 row_mirror row_mask:0xf bank_mask:0xf
	s_nop 1
	v_add_f32_dpp v222, v222, v222 row_bcast:15 row_mask:0xa bank_mask:0xf
	s_nop 1
	v_add_f32_dpp v222, v222, v222 row_bcast:31 row_mask:0xc bank_mask:0xf
	s_nop 1
	v_readlane_b32 s6, v222, 63
	s_nop 1
	v_mov_b32_e32 v224, s6
	v_mov_b32_e32 v225, 0x3727c5ac
	v_fmac_f32_e32 v225, 0x3a800000, v224
	v_rsq_f32_e32 v229, v225
	s_nop 0
	s_mov_b64 exec, 1
	global_store_dwordx2 v3, v[228:229], s[62:63]
	s_mov_b64 exec, -1
	s_add_u32 s62, s62, 0x4000
	s_addc_u32 s63, s63, 0
	v_mul_f32_e32 v84, v84, v229
	v_mul_f32_e32 v85, v85, v229
	v_mul_f32_e32 v86, v86, v229
	v_mul_f32_e32 v87, v87, v229
	v_mul_f32_e32 v88, v88, v229
	v_mul_f32_e32 v89, v89, v229
	v_mul_f32_e32 v90, v90, v229
	v_mul_f32_e32 v91, v91, v229
	v_mul_f32_e32 v92, v92, v229
	v_mul_f32_e32 v93, v93, v229
	v_mul_f32_e32 v94, v94, v229
	v_mul_f32_e32 v95, v95, v229
	v_mul_f32_e32 v96, v96, v229
	v_mul_f32_e32 v97, v97, v229
	v_mul_f32_e32 v98, v98, v229
	v_mul_f32_e32 v99, v99, v229
	v_fma_f32 v84, v84, v188, v204
	v_fma_f32 v85, v85, v189, v205
	v_fma_f32 v86, v86, v190, v206
	v_fma_f32 v87, v87, v191, v207
	v_fma_f32 v88, v88, v192, v208
	v_fma_f32 v89, v89, v193, v209
	v_fma_f32 v90, v90, v194, v210
	v_fma_f32 v91, v91, v195, v211
	v_fma_f32 v92, v92, v196, v212
	v_fma_f32 v93, v93, v197, v213
	v_fma_f32 v94, v94, v198, v214
	v_fma_f32 v95, v95, v199, v215
	v_fma_f32 v96, v96, v200, v216
	v_fma_f32 v97, v97, v201, v217
	v_fma_f32 v98, v98, v202, v218
	v_fma_f32 v99, v99, v203, v219
	v_fma_f32 v84, v84, v20, v4
	v_fma_f32 v85, v85, v21, v5
	v_fma_f32 v86, v86, v22, v6
	v_fma_f32 v87, v87, v23, v7
	v_fma_f32 v88, v88, v24, v8
	v_fma_f32 v89, v89, v25, v9
	v_fma_f32 v90, v90, v26, v10
	v_fma_f32 v91, v91, v27, v11
	v_fma_f32 v92, v92, v28, v12
	v_fma_f32 v93, v93, v29, v13
	v_fma_f32 v94, v94, v30, v14
	v_fma_f32 v95, v95, v31, v15
	v_fma_f32 v96, v96, v32, v16
	v_fma_f32 v97, v97, v33, v17
	v_fma_f32 v98, v98, v34, v18
	v_fma_f32 v99, v99, v35, v19
	v_cvt_pk_bf16_f32 v84, v84, v85
	v_cvt_pk_bf16_f32 v85, v86, v87
	v_cvt_pk_bf16_f32 v88, v88, v89
	v_cvt_pk_bf16_f32 v89, v90, v91
	v_cvt_pk_bf16_f32 v92, v92, v93
	v_cvt_pk_bf16_f32 v93, v94, v95
	v_cvt_pk_bf16_f32 v96, v96, v97
	v_cvt_pk_bf16_f32 v97, v98, v99
	global_store_dwordx2 v2, v[84:85], s[60:61]
	global_store_dwordx2 v2, v[88:89], s[60:61] offset:512
	global_store_dwordx2 v2, v[92:93], s[60:61] offset:1024
	global_store_dwordx2 v2, v[96:97], s[60:61] offset:1536
	s_add_u32 s60, s60, 0x400000
	s_addc_u32 s61, s61, 0
	s_nop 0
	global_load_dwordx4 v[84:87], v0, s[56:57]
	global_load_dwordx4 v[88:91], v0, s[56:57] offset:1024
	global_load_dwordx4 v[92:95], v0, s[56:57] offset:2048
	global_load_dwordx4 v[96:99], v0, s[56:57] offset:3072
	s_add_u32 s56, s56, 0x800000
	s_addc_u32 s57, s57, 0
	s_waitcnt vmcnt(30)
	v_add_f32_e32 v220, v100, v101
	v_add_f32_e32 v221, v102, v103
	v_add_f32_e32 v222, v104, v105
	v_add_f32_e32 v223, v106, v107
	v_add_f32_e32 v224, v108, v109
	v_add_f32_e32 v225, v110, v111
	v_add_f32_e32 v226, v112, v113
	v_add_f32_e32 v227, v114, v115
	v_add_f32_e32 v220, v220, v221
	v_add_f32_e32 v222, v222, v223
	v_add_f32_e32 v224, v224, v225
	v_add_f32_e32 v226, v226, v227
	v_add_f32_e32 v220, v220, v222
	v_add_f32_e32 v224, v224, v226
	v_add_f32_e32 v220, v220, v224
	s_nop 1
	v_add_f32_dpp v220, v220, v220 quad_perm:[1,0,3,2] row_mask:0xf bank_mask:0xf
	s_nop 1
	v_add_f32_dpp v220, v220, v220 quad_perm:[2,3,0,1] row_mask:0xf bank_mask:0xf
	s_nop 1
	v_add_f32_dpp v220, v220, v220 row_half_mirror row_mask:0xf bank_mask:0xf
	s_nop 1
	v_add_f32_dpp v220, v220, v220 row_mirror row_mask:0xf bank_mask:0xf
	s_nop 1
	v_add_f32_dpp v220, v220, v220 row_bcast:15 row_mask:0xa bank_mask:0xf
	s_nop 1
	v_add_f32_dpp v220, v220, v220 row_bcast:31 row_mask:0xc bank_mask:0xf
	s_nop 1
	v_readlane_b32 s6, v220, 63
	s_nop 1
	v_mov_b32_e32 v228, s6
	v_mul_f32_e32 v228, 0x3a800000, v228
	v_sub_f32_e32 v100, v100, v228
	v_sub_f32_e32 v101, v101, v228
	v_sub_f32_e32 v102, v102, v228
	v_sub_f32_e32 v103, v103, v228
	v_sub_f32_e32 v104, v104, v228
	v_sub_f32_e32 v105, v105, v228
	v_sub_f32_e32 v106, v106, v228
	v_sub_f32_e32 v107, v107, v228
	v_sub_f32_e32 v108, v108, v228
	v_sub_f32_e32 v109, v109, v228
	v_sub_f32_e32 v110, v110, v228
	v_sub_f32_e32 v111, v111, v228
	v_sub_f32_e32 v112, v112, v228
	v_sub_f32_e32 v113, v113, v228
	v_sub_f32_e32 v114, v114, v228
	v_sub_f32_e32 v115, v115, v228
	v_mul_f32_e32 v222, v100, v100
	v_mul_f32_e32 v223, v101, v101
	v_fmac_f32_e32 v222, v102, v102
	v_fmac_f32_e32 v223, v103, v103
	v_fmac_f32_e32 v222, v104, v104
	v_fmac_f32_e32 v223, v105, v105
	v_fmac_f32_e32 v222, v106, v106
	v_fmac_f32_e32 v223, v107, v107
	v_fmac_f32_e32 v222, v108, v108
	v_fmac_f32_e32 v223, v109, v109
	v_fmac_f32_e32 v222, v110, v110
	v_fmac_f32_e32 v223, v111, v111
	v_fmac_f32_e32 v222, v112, v112
	v_fmac_f32_e32 v223, v113, v113
	v_fmac_f32_e32 v222, v114, v114
	v_fmac_f32_e32 v223, v115, v115
	v_add_f32_e32 v222, v222, v223
	s_nop 1
	v_add_f32_dpp v222, v222, v222 quad_perm:[1,0,3,2] row_mask:0xf bank_mask:0xf
	s_nop 1
	v_add_f32_dpp v222, v222, v222 quad_perm:[2,3,0,1] row_mask:0xf bank_mask:0xf
	s_nop 1
	v_add_f32_dpp v222, v222, v222 row_half_mirror row_mask:0xf bank_mask:0xf
	s_nop 1
	v_add_f32_dpp v222, v222, v222 row_mirror row_mask:0xf bank_mask:0xf
	s_nop 1
	v_add_f32_dpp v222, v222, v222 row_bcast:15 row_mask:0xa bank_mask:0xf
	s_nop 1
	v_add_f32_dpp v222, v222, v222 row_bcast:31 row_mask:0xc bank_mask:0xf
	s_nop 1
	v_readlane_b32 s6, v222, 63
	s_nop 1
	v_mov_b32_e32 v224, s6
	v_mov_b32_e32 v225, 0x3727c5ac
	v_fmac_f32_e32 v225, 0x3a800000, v224
	v_rsq_f32_e32 v229, v225
	global_load_dwordx4 v[4:7], v0, s[98:99]
	global_load_dwordx4 v[8:11], v0, s[98:99] offset:1024
	global_load_dwordx4 v[12:15], v0, s[98:99] offset:2048
	global_load_dwordx4 v[16:19], v0, s[98:99] offset:3072
	global_load_dwordx4 v[20:23], v0, s[100:101]
	global_load_dwordx4 v[24:27], v0, s[100:101] offset:1024
	global_load_dwordx4 v[28:31], v0, s[100:101] offset:2048
	global_load_dwordx4 v[32:35], v0, s[100:101] offset:3072
	s_add_u32 s98, s98, 0x3000
	s_addc_u32 s99, s99, 0
	s_add_u32 s100, s100, 0x3000
	s_addc_u32 s101, s101, 0
	s_waitcnt vmcnt(26)
	v_add_f32_e32 v52, 1.0, v52
	v_add_f32_e32 v53, 1.0, v53
	v_add_f32_e32 v54, 1.0, v54
	v_add_f32_e32 v55, 1.0, v55
	v_add_f32_e32 v56, 1.0, v56
	v_add_f32_e32 v57, 1.0, v57
	v_add_f32_e32 v58, 1.0, v58
	v_add_f32_e32 v59, 1.0, v59
	v_add_f32_e32 v60, 1.0, v60
	v_add_f32_e32 v61, 1.0, v61
	v_add_f32_e32 v62, 1.0, v62
	v_add_f32_e32 v63, 1.0, v63
	v_add_f32_e32 v64, 1.0, v64
	v_add_f32_e32 v65, 1.0, v65
	v_add_f32_e32 v66, 1.0, v66
	v_add_f32_e32 v67, 1.0, v67
	s_mov_b64 exec, 1
	global_store_dwordx2 v3, v[228:229], s[62:63]
	s_mov_b64 exec, -1
	s_add_u32 s62, s62, 0x4000
	s_addc_u32 s63, s63, 0
	v_mul_f32_e32 v100, v100, v229
	v_mul_f32_e32 v101, v101, v229
	v_mul_f32_e32 v102, v102, v229
	v_mul_f32_e32 v103, v103, v229
	v_mul_f32_e32 v104, v104, v229
	v_mul_f32_e32 v105, v105, v229
	v_mul_f32_e32 v106, v106, v229
	v_mul_f32_e32 v107, v107, v229
	v_mul_f32_e32 v108, v108, v229
	v_mul_f32_e32 v109, v109, v229
	v_mul_f32_e32 v110, v110, v229
	v_mul_f32_e32 v111, v111, v229
	v_mul_f32_e32 v112, v112, v229
	v_mul_f32_e32 v113, v113, v229
	v_mul_f32_e32 v114, v114, v229
	v_mul_f32_e32 v115, v115, v229
	v_fma_f32 v100, v100, v188, v204
	v_fma_f32 v101, v101, v189, v205
	v_fma_f32 v102, v102, v190, v206
	v_fma_f32 v103, v103, v191, v207
	v_fma_f32 v104, v104, v192, v208
	v_fma_f32 v105, v105, v193, v209
	v_fma_f32 v106, v106, v194, v210
	v_fma_f32 v107, v107, v195, v211
	v_fma_f32 v108, v108, v196, v212
	v_fma_f32 v109, v109, v197, v213
	v_fma_f32 v110, v110, v198, v214
	v_fma_f32 v111, v111, v199, v215
	v_fma_f32 v112, v112, v200, v216
	v_fma_f32 v113, v113, v201, v217
	v_fma_f32 v114, v114, v202, v218
	v_fma_f32 v115, v115, v203, v219
	v_fma_f32 v100, v100, v52, v36
	v_fma_f32 v101, v101, v53, v37
	v_fma_f32 v102, v102, v54, v38
	v_fma_f32 v103, v103, v55, v39
	v_fma_f32 v104, v104, v56, v40
	v_fma_f32 v105, v105, v57, v41
	v_fma_f32 v106, v106, v58, v42
	v_fma_f32 v107, v107, v59, v43
	v_fma_f32 v108, v108, v60, v44
	v_fma_f32 v109, v109, v61, v45
	v_fma_f32 v110, v110, v62, v46
	v_fma_f32 v111, v111, v63, v47
	v_fma_f32 v112, v112, v64, v48
	v_fma_f32 v113, v113, v65, v49
	v_fma_f32 v114, v114, v66, v50
	v_fma_f32 v115, v115, v67, v51
	v_cvt_pk_bf16_f32 v100, v100, v101
	v_cvt_pk_bf16_f32 v101, v102, v103
	v_cvt_pk_bf16_f32 v104, v104, v105
	v_cvt_pk_bf16_f32 v105, v106, v107
	v_cvt_pk_bf16_f32 v108, v108, v109
	v_cvt_pk_bf16_f32 v109, v110, v111
	v_cvt_pk_bf16_f32 v112, v112, v113
	v_cvt_pk_bf16_f32 v113, v114, v115
	global_store_dwordx2 v2, v[100:101], s[60:61]
	global_store_dwordx2 v2, v[104:105], s[60:61] offset:512
	global_store_dwordx2 v2, v[108:109], s[60:61] offset:1024
	global_store_dwordx2 v2, v[112:113], s[60:61] offset:1536
	s_add_u32 s60, s60, 0x400000
	s_addc_u32 s61, s61, 0
	s_nop 0
	global_load_dwordx4 v[100:103], v0, s[56:57]
	global_load_dwordx4 v[104:107], v0, s[56:57] offset:1024
	global_load_dwordx4 v[108:111], v0, s[56:57] offset:2048
	global_load_dwordx4 v[112:115], v0, s[56:57] offset:3072
	s_add_u32 s56, s56, 0x800000
	s_addc_u32 s57, s57, 0
	s_waitcnt vmcnt(43)
	v_add_f32_e32 v220, v116, v117
	v_add_f32_e32 v221, v118, v119
	v_add_f32_e32 v222, v120, v121
	v_add_f32_e32 v223, v122, v123
	v_add_f32_e32 v224, v124, v125
	v_add_f32_e32 v225, v126, v127
	v_add_f32_e32 v226, v128, v129
	v_add_f32_e32 v227, v130, v131
	v_add_f32_e32 v220, v220, v221
	v_add_f32_e32 v222, v222, v223
	v_add_f32_e32 v224, v224, v225
	v_add_f32_e32 v226, v226, v227
	v_add_f32_e32 v220, v220, v222
	v_add_f32_e32 v224, v224, v226
	v_add_f32_e32 v220, v220, v224
	s_nop 1
	v_add_f32_dpp v220, v220, v220 quad_perm:[1,0,3,2] row_mask:0xf bank_mask:0xf
	s_nop 1
	v_add_f32_dpp v220, v220, v220 quad_perm:[2,3,0,1] row_mask:0xf bank_mask:0xf
	s_nop 1
	v_add_f32_dpp v220, v220, v220 row_half_mirror row_mask:0xf bank_mask:0xf
	s_nop 1
	v_add_f32_dpp v220, v220, v220 row_mirror row_mask:0xf bank_mask:0xf
	s_nop 1
	v_add_f32_dpp v220, v220, v220 row_bcast:15 row_mask:0xa bank_mask:0xf
	s_nop 1
	v_add_f32_dpp v220, v220, v220 row_bcast:31 row_mask:0xc bank_mask:0xf
	s_nop 1
	v_readlane_b32 s6, v220, 63
	s_nop 1
	v_mov_b32_e32 v228, s6
	v_mul_f32_e32 v228, 0x3a800000, v228
	v_sub_f32_e32 v116, v116, v228
	v_sub_f32_e32 v117, v117, v228
	v_sub_f32_e32 v118, v118, v228
	v_sub_f32_e32 v119, v119, v228
	v_sub_f32_e32 v120, v120, v228
	v_sub_f32_e32 v121, v121, v228
	v_sub_f32_e32 v122, v122, v228
	v_sub_f32_e32 v123, v123, v228
	v_sub_f32_e32 v124, v124, v228
	v_sub_f32_e32 v125, v125, v228
	v_sub_f32_e32 v126, v126, v228
	v_sub_f32_e32 v127, v127, v228
	v_sub_f32_e32 v128, v128, v228
	v_sub_f32_e32 v129, v129, v228
	v_sub_f32_e32 v130, v130, v228
	v_sub_f32_e32 v131, v131, v228
	v_mul_f32_e32 v222, v116, v116
	v_mul_f32_e32 v223, v117, v117
	v_fmac_f32_e32 v222, v118, v118
	v_fmac_f32_e32 v223, v119, v119
	v_fmac_f32_e32 v222, v120, v120
	v_fmac_f32_e32 v223, v121, v121
	v_fmac_f32_e32 v222, v122, v122
	v_fmac_f32_e32 v223, v123, v123
	v_fmac_f32_e32 v222, v124, v124
	v_fmac_f32_e32 v223, v125, v125
	v_fmac_f32_e32 v222, v126, v126
	v_fmac_f32_e32 v223, v127, v127
	v_fmac_f32_e32 v222, v128, v128
	v_fmac_f32_e32 v223, v129, v129
	v_fmac_f32_e32 v222, v130, v130
	v_fmac_f32_e32 v223, v131, v131
	v_add_f32_e32 v222, v222, v223
	s_nop 1
	v_add_f32_dpp v222, v222, v222 quad_perm:[1,0,3,2] row_mask:0xf bank_mask:0xf
	s_nop 1
	v_add_f32_dpp v222, v222, v222 quad_perm:[2,3,0,1] row_mask:0xf bank_mask:0xf
	s_nop 1
	v_add_f32_dpp v222, v222, v222 row_half_mirror row_mask:0xf bank_mask:0xf
	s_nop 1
	v_add_f32_dpp v222, v222, v222 row_mirror row_mask:0xf bank_mask:0xf
	s_nop 1
	v_add_f32_dpp v222, v222, v222 row_bcast:15 row_mask:0xa bank_mask:0xf
	s_nop 1
	v_add_f32_dpp v222, v222, v222 row_bcast:31 row_mask:0xc bank_mask:0xf
	s_nop 1
	v_readlane_b32 s6, v222, 63
	s_nop 1
	v_mov_b32_e32 v224, s6
	v_mov_b32_e32 v225, 0x3727c5ac
	v_fmac_f32_e32 v225, 0x3a800000, v224
	v_rsq_f32_e32 v229, v225
	s_nop 0
	s_mov_b64 exec, 1
	global_store_dwordx2 v3, v[228:229], s[62:63]
	s_mov_b64 exec, -1
	s_add_u32 s62, s62, 0x4000
	s_addc_u32 s63, s63, 0
	v_mul_f32_e32 v116, v116, v229
	v_mul_f32_e32 v117, v117, v229
	v_mul_f32_e32 v118, v118, v229
	v_mul_f32_e32 v119, v119, v229
	v_mul_f32_e32 v120, v120, v229
	v_mul_f32_e32 v121, v121, v229
	v_mul_f32_e32 v122, v122, v229
	v_mul_f32_e32 v123, v123, v229
	v_mul_f32_e32 v124, v124, v229
	v_mul_f32_e32 v125, v125, v229
	v_mul_f32_e32 v126, v126, v229
	v_mul_f32_e32 v127, v127, v229
	v_mul_f32_e32 v128, v128, v229
	v_mul_f32_e32 v129, v129, v229
	v_mul_f32_e32 v130, v130, v229
	v_mul_f32_e32 v131, v131, v229
	v_fma_f32 v116, v116, v188, v204
	v_fma_f32 v117, v117, v189, v205
	v_fma_f32 v118, v118, v190, v206
	v_fma_f32 v119, v119, v191, v207
	v_fma_f32 v120, v120, v192, v208
	v_fma_f32 v121, v121, v193, v209
	v_fma_f32 v122, v122, v194, v210
	v_fma_f32 v123, v123, v195, v211
	v_fma_f32 v124, v124, v196, v212
	v_fma_f32 v125, v125, v197, v213
	v_fma_f32 v126, v126, v198, v214
	v_fma_f32 v127, v127, v199, v215
	v_fma_f32 v128, v128, v200, v216
	v_fma_f32 v129, v129, v201, v217
	v_fma_f32 v130, v130, v202, v218
	v_fma_f32 v131, v131, v203, v219
	v_fma_f32 v116, v116, v52, v36
	v_fma_f32 v117, v117, v53, v37
	v_fma_f32 v118, v118, v54, v38
	v_fma_f32 v119, v119, v55, v39
	v_fma_f32 v120, v120, v56, v40
	v_fma_f32 v121, v121, v57, v41
	v_fma_f32 v122, v122, v58, v42
	v_fma_f32 v123, v123, v59, v43
	v_fma_f32 v124, v124, v60, v44
	v_fma_f32 v125, v125, v61, v45
	v_fma_f32 v126, v126, v62, v46
	v_fma_f32 v127, v127, v63, v47
	v_fma_f32 v128, v128, v64, v48
	v_fma_f32 v129, v129, v65, v49
	v_fma_f32 v130, v130, v66, v50
	v_fma_f32 v131, v131, v67, v51
	v_cvt_pk_bf16_f32 v116, v116, v117
	v_cvt_pk_bf16_f32 v117, v118, v119
	v_cvt_pk_bf16_f32 v120, v120, v121
	v_cvt_pk_bf16_f32 v121, v122, v123
	v_cvt_pk_bf16_f32 v124, v124, v125
	v_cvt_pk_bf16_f32 v125, v126, v127
	v_cvt_pk_bf16_f32 v128, v128, v129
	v_cvt_pk_bf16_f32 v129, v130, v131
	global_store_dwordx2 v2, v[116:117], s[60:61]
	global_store_dwordx2 v2, v[120:121], s[60:61] offset:512
	global_store_dwordx2 v2, v[124:125], s[60:61] offset:1024
	global_store_dwordx2 v2, v[128:129], s[60:61] offset:1536
	s_add_u32 s60, s60, 0x400000
	s_addc_u32 s61, s61, 0
	s_nop 0
	global_load_dwordx4 v[116:119], v0, s[56:57]
	global_load_dwordx4 v[120:123], v0, s[56:57] offset:1024
	global_load_dwordx4 v[124:127], v0, s[56:57] offset:2048
	global_load_dwordx4 v[128:131], v0, s[56:57] offset:3072
	s_add_u32 s56, s56, 0x800000
	s_addc_u32 s57, s57, 0
	s_waitcnt vmcnt(35)
	v_add_f32_e32 v220, v68, v69
	v_add_f32_e32 v221, v70, v71
	v_add_f32_e32 v222, v72, v73
	v_add_f32_e32 v223, v74, v75
	v_add_f32_e32 v224, v76, v77
	v_add_f32_e32 v225, v78, v79
	v_add_f32_e32 v226, v80, v81
	v_add_f32_e32 v227, v82, v83
	v_add_f32_e32 v220, v220, v221
	v_add_f32_e32 v222, v222, v223
	v_add_f32_e32 v224, v224, v225
	v_add_f32_e32 v226, v226, v227
	v_add_f32_e32 v220, v220, v222
	v_add_f32_e32 v224, v224, v226
	v_add_f32_e32 v220, v220, v224
	s_nop 1
	v_add_f32_dpp v220, v220, v220 quad_perm:[1,0,3,2] row_mask:0xf bank_mask:0xf
	s_nop 1
	v_add_f32_dpp v220, v220, v220 quad_perm:[2,3,0,1] row_mask:0xf bank_mask:0xf
	s_nop 1
	v_add_f32_dpp v220, v220, v220 row_half_mirror row_mask:0xf bank_mask:0xf
	s_nop 1
	v_add_f32_dpp v220, v220, v220 row_mirror row_mask:0xf bank_mask:0xf
	s_nop 1
	v_add_f32_dpp v220, v220, v220 row_bcast:15 row_mask:0xa bank_mask:0xf
	s_nop 1
	v_add_f32_dpp v220, v220, v220 row_bcast:31 row_mask:0xc bank_mask:0xf
	s_nop 1
	v_readlane_b32 s6, v220, 63
	s_nop 1
	v_mov_b32_e32 v228, s6
	v_mul_f32_e32 v228, 0x3a800000, v228
	v_sub_f32_e32 v68, v68, v228
	v_sub_f32_e32 v69, v69, v228
	v_sub_f32_e32 v70, v70, v228
	v_sub_f32_e32 v71, v71, v228
	v_sub_f32_e32 v72, v72, v228
	v_sub_f32_e32 v73, v73, v228
	v_sub_f32_e32 v74, v74, v228
	v_sub_f32_e32 v75, v75, v228
	v_sub_f32_e32 v76, v76, v228
	v_sub_f32_e32 v77, v77, v228
	v_sub_f32_e32 v78, v78, v228
	v_sub_f32_e32 v79, v79, v228
	v_sub_f32_e32 v80, v80, v228
	v_sub_f32_e32 v81, v81, v228
	v_sub_f32_e32 v82, v82, v228
	v_sub_f32_e32 v83, v83, v228
	v_mul_f32_e32 v222, v68, v68
	v_mul_f32_e32 v223, v69, v69
	v_fmac_f32_e32 v222, v70, v70
	v_fmac_f32_e32 v223, v71, v71
	v_fmac_f32_e32 v222, v72, v72
	v_fmac_f32_e32 v223, v73, v73
	v_fmac_f32_e32 v222, v74, v74
	v_fmac_f32_e32 v223, v75, v75
	v_fmac_f32_e32 v222, v76, v76
	v_fmac_f32_e32 v223, v77, v77
	v_fmac_f32_e32 v222, v78, v78
	v_fmac_f32_e32 v223, v79, v79
	v_fmac_f32_e32 v222, v80, v80
	v_fmac_f32_e32 v223, v81, v81
	v_fmac_f32_e32 v222, v82, v82
	v_fmac_f32_e32 v223, v83, v83
	v_add_f32_e32 v222, v222, v223
	s_nop 1
	v_add_f32_dpp v222, v222, v222 quad_perm:[1,0,3,2] row_mask:0xf bank_mask:0xf
	s_nop 1
	v_add_f32_dpp v222, v222, v222 quad_perm:[2,3,0,1] row_mask:0xf bank_mask:0xf
	s_nop 1
	v_add_f32_dpp v222, v222, v222 row_half_mirror row_mask:0xf bank_mask:0xf
	s_nop 1
	v_add_f32_dpp v222, v222, v222 row_mirror row_mask:0xf bank_mask:0xf
	s_nop 1
	v_add_f32_dpp v222, v222, v222 row_bcast:15 row_mask:0xa bank_mask:0xf
	s_nop 1
	v_add_f32_dpp v222, v222, v222 row_bcast:31 row_mask:0xc bank_mask:0xf
	s_nop 1
	v_readlane_b32 s6, v222, 63
	s_nop 1
	v_mov_b32_e32 v224, s6
	v_mov_b32_e32 v225, 0x3727c5ac
	v_fmac_f32_e32 v225, 0x3a800000, v224
	v_rsq_f32_e32 v229, v225
	global_load_dwordx4 v[36:39], v0, s[98:99]
	global_load_dwordx4 v[40:43], v0, s[98:99] offset:1024
	global_load_dwordx4 v[44:47], v0, s[98:99] offset:2048
	global_load_dwordx4 v[48:51], v0, s[98:99] offset:3072
	global_load_dwordx4 v[52:55], v0, s[100:101]
	global_load_dwordx4 v[56:59], v0, s[100:101] offset:1024
	global_load_dwordx4 v[60:63], v0, s[100:101] offset:2048
	global_load_dwordx4 v[64:67], v0, s[100:101] offset:3072
	s_add_u32 s98, s98, 0x3000
	s_addc_u32 s99, s99, 0
	s_add_u32 s100, s100, 0x3000
	s_addc_u32 s101, s101, 0
	s_waitcnt vmcnt(26)
	v_add_f32_e32 v20, 1.0, v20
	v_add_f32_e32 v21, 1.0, v21
	v_add_f32_e32 v22, 1.0, v22
	v_add_f32_e32 v23, 1.0, v23
	v_add_f32_e32 v24, 1.0, v24
	v_add_f32_e32 v25, 1.0, v25
	v_add_f32_e32 v26, 1.0, v26
	v_add_f32_e32 v27, 1.0, v27
	v_add_f32_e32 v28, 1.0, v28
	v_add_f32_e32 v29, 1.0, v29
	v_add_f32_e32 v30, 1.0, v30
	v_add_f32_e32 v31, 1.0, v31
	v_add_f32_e32 v32, 1.0, v32
	v_add_f32_e32 v33, 1.0, v33
	v_add_f32_e32 v34, 1.0, v34
	v_add_f32_e32 v35, 1.0, v35
	s_mov_b64 exec, 1
	global_store_dwordx2 v3, v[228:229], s[62:63]
	s_mov_b64 exec, -1
	s_add_u32 s62, s62, 0x4000
	s_addc_u32 s63, s63, 0
	v_mul_f32_e32 v68, v68, v229
	v_mul_f32_e32 v69, v69, v229
	v_mul_f32_e32 v70, v70, v229
	v_mul_f32_e32 v71, v71, v229
	v_mul_f32_e32 v72, v72, v229
	v_mul_f32_e32 v73, v73, v229
	v_mul_f32_e32 v74, v74, v229
	v_mul_f32_e32 v75, v75, v229
	v_mul_f32_e32 v76, v76, v229
	v_mul_f32_e32 v77, v77, v229
	v_mul_f32_e32 v78, v78, v229
	v_mul_f32_e32 v79, v79, v229
	v_mul_f32_e32 v80, v80, v229
	v_mul_f32_e32 v81, v81, v229
	v_mul_f32_e32 v82, v82, v229
	v_mul_f32_e32 v83, v83, v229
	v_fma_f32 v68, v68, v188, v204
	v_fma_f32 v69, v69, v189, v205
	v_fma_f32 v70, v70, v190, v206
	v_fma_f32 v71, v71, v191, v207
	v_fma_f32 v72, v72, v192, v208
	v_fma_f32 v73, v73, v193, v209
	v_fma_f32 v74, v74, v194, v210
	v_fma_f32 v75, v75, v195, v211
	v_fma_f32 v76, v76, v196, v212
	v_fma_f32 v77, v77, v197, v213
	v_fma_f32 v78, v78, v198, v214
	v_fma_f32 v79, v79, v199, v215
	v_fma_f32 v80, v80, v200, v216
	v_fma_f32 v81, v81, v201, v217
	v_fma_f32 v82, v82, v202, v218
	v_fma_f32 v83, v83, v203, v219
	v_fma_f32 v68, v68, v20, v4
	v_fma_f32 v69, v69, v21, v5
	v_fma_f32 v70, v70, v22, v6
	v_fma_f32 v71, v71, v23, v7
	v_fma_f32 v72, v72, v24, v8
	v_fma_f32 v73, v73, v25, v9
	v_fma_f32 v74, v74, v26, v10
	v_fma_f32 v75, v75, v27, v11
	v_fma_f32 v76, v76, v28, v12
	v_fma_f32 v77, v77, v29, v13
	v_fma_f32 v78, v78, v30, v14
	v_fma_f32 v79, v79, v31, v15
	v_fma_f32 v80, v80, v32, v16
	v_fma_f32 v81, v81, v33, v17
	v_fma_f32 v82, v82, v34, v18
	v_fma_f32 v83, v83, v35, v19
	v_cvt_pk_bf16_f32 v68, v68, v69
	v_cvt_pk_bf16_f32 v69, v70, v71
	v_cvt_pk_bf16_f32 v72, v72, v73
	v_cvt_pk_bf16_f32 v73, v74, v75
	v_cvt_pk_bf16_f32 v76, v76, v77
	v_cvt_pk_bf16_f32 v77, v78, v79
	v_cvt_pk_bf16_f32 v80, v80, v81
	v_cvt_pk_bf16_f32 v81, v82, v83
	global_store_dwordx2 v2, v[68:69], s[60:61]
	global_store_dwordx2 v2, v[72:73], s[60:61] offset:512
	global_store_dwordx2 v2, v[76:77], s[60:61] offset:1024
	global_store_dwordx2 v2, v[80:81], s[60:61] offset:1536
	s_add_u32 s60, s60, 0x400000
	s_addc_u32 s61, s61, 0
	s_nop 0
	global_load_dwordx4 v[68:71], v0, s[56:57]
	global_load_dwordx4 v[72:75], v0, s[56:57] offset:1024
	global_load_dwordx4 v[76:79], v0, s[56:57] offset:2048
	global_load_dwordx4 v[80:83], v0, s[56:57] offset:3072
	s_add_u32 s56, s56, 0x800000
	s_addc_u32 s57, s57, 0
	s_waitcnt vmcnt(43)
	v_add_f32_e32 v220, v84, v85
	v_add_f32_e32 v221, v86, v87
	v_add_f32_e32 v222, v88, v89
	v_add_f32_e32 v223, v90, v91
	v_add_f32_e32 v224, v92, v93
	v_add_f32_e32 v225, v94, v95
	v_add_f32_e32 v226, v96, v97
	v_add_f32_e32 v227, v98, v99
	v_add_f32_e32 v220, v220, v221
	v_add_f32_e32 v222, v222, v223
	v_add_f32_e32 v224, v224, v225
	v_add_f32_e32 v226, v226, v227
	v_add_f32_e32 v220, v220, v222
	v_add_f32_e32 v224, v224, v226
	v_add_f32_e32 v220, v220, v224
	s_nop 1
	v_add_f32_dpp v220, v220, v220 quad_perm:[1,0,3,2] row_mask:0xf bank_mask:0xf
	s_nop 1
	v_add_f32_dpp v220, v220, v220 quad_perm:[2,3,0,1] row_mask:0xf bank_mask:0xf
	s_nop 1
	v_add_f32_dpp v220, v220, v220 row_half_mirror row_mask:0xf bank_mask:0xf
	s_nop 1
	v_add_f32_dpp v220, v220, v220 row_mirror row_mask:0xf bank_mask:0xf
	s_nop 1
	v_add_f32_dpp v220, v220, v220 row_bcast:15 row_mask:0xa bank_mask:0xf
	s_nop 1
	v_add_f32_dpp v220, v220, v220 row_bcast:31 row_mask:0xc bank_mask:0xf
	s_nop 1
	v_readlane_b32 s6, v220, 63
	s_nop 1
	v_mov_b32_e32 v228, s6
	v_mul_f32_e32 v228, 0x3a800000, v228
	v_sub_f32_e32 v84, v84, v228
	v_sub_f32_e32 v85, v85, v228
	v_sub_f32_e32 v86, v86, v228
	v_sub_f32_e32 v87, v87, v228
	v_sub_f32_e32 v88, v88, v228
	v_sub_f32_e32 v89, v89, v228
	v_sub_f32_e32 v90, v90, v228
	v_sub_f32_e32 v91, v91, v228
	v_sub_f32_e32 v92, v92, v228
	v_sub_f32_e32 v93, v93, v228
	v_sub_f32_e32 v94, v94, v228
	v_sub_f32_e32 v95, v95, v228
	v_sub_f32_e32 v96, v96, v228
	v_sub_f32_e32 v97, v97, v228
	v_sub_f32_e32 v98, v98, v228
	v_sub_f32_e32 v99, v99, v228
	v_mul_f32_e32 v222, v84, v84
	v_mul_f32_e32 v223, v85, v85
	v_fmac_f32_e32 v222, v86, v86
	v_fmac_f32_e32 v223, v87, v87
	v_fmac_f32_e32 v222, v88, v88
	v_fmac_f32_e32 v223, v89, v89
	v_fmac_f32_e32 v222, v90, v90
	v_fmac_f32_e32 v223, v91, v91
	v_fmac_f32_e32 v222, v92, v92
	v_fmac_f32_e32 v223, v93, v93
	v_fmac_f32_e32 v222, v94, v94
	v_fmac_f32_e32 v223, v95, v95
	v_fmac_f32_e32 v222, v96, v96
	v_fmac_f32_e32 v223, v97, v97
	v_fmac_f32_e32 v222, v98, v98
	v_fmac_f32_e32 v223, v99, v99
	v_add_f32_e32 v222, v222, v223
	s_nop 1
	v_add_f32_dpp v222, v222, v222 quad_perm:[1,0,3,2] row_mask:0xf bank_mask:0xf
	s_nop 1
	v_add_f32_dpp v222, v222, v222 quad_perm:[2,3,0,1] row_mask:0xf bank_mask:0xf
	s_nop 1
	v_add_f32_dpp v222, v222, v222 row_half_mirror row_mask:0xf bank_mask:0xf
	s_nop 1
	v_add_f32_dpp v222, v222, v222 row_mirror row_mask:0xf bank_mask:0xf
	s_nop 1
	v_add_f32_dpp v222, v222, v222 row_bcast:15 row_mask:0xa bank_mask:0xf
	s_nop 1
	v_add_f32_dpp v222, v222, v222 row_bcast:31 row_mask:0xc bank_mask:0xf
	s_nop 1
	v_readlane_b32 s6, v222, 63
	s_nop 1
	v_mov_b32_e32 v224, s6
	v_mov_b32_e32 v225, 0x3727c5ac
	v_fmac_f32_e32 v225, 0x3a800000, v224
	v_rsq_f32_e32 v229, v225
	s_nop 0
	s_mov_b64 exec, 1
	global_store_dwordx2 v3, v[228:229], s[62:63]
	s_mov_b64 exec, -1
	s_add_u32 s62, s62, 0x4000
	s_addc_u32 s63, s63, 0
	v_mul_f32_e32 v84, v84, v229
	v_mul_f32_e32 v85, v85, v229
	v_mul_f32_e32 v86, v86, v229
	v_mul_f32_e32 v87, v87, v229
	v_mul_f32_e32 v88, v88, v229
	v_mul_f32_e32 v89, v89, v229
	v_mul_f32_e32 v90, v90, v229
	v_mul_f32_e32 v91, v91, v229
	v_mul_f32_e32 v92, v92, v229
	v_mul_f32_e32 v93, v93, v229
	v_mul_f32_e32 v94, v94, v229
	v_mul_f32_e32 v95, v95, v229
	v_mul_f32_e32 v96, v96, v229
	v_mul_f32_e32 v97, v97, v229
	v_mul_f32_e32 v98, v98, v229
	v_mul_f32_e32 v99, v99, v229
	v_fma_f32 v84, v84, v188, v204
	v_fma_f32 v85, v85, v189, v205
	v_fma_f32 v86, v86, v190, v206
	v_fma_f32 v87, v87, v191, v207
	v_fma_f32 v88, v88, v192, v208
	v_fma_f32 v89, v89, v193, v209
	v_fma_f32 v90, v90, v194, v210
	v_fma_f32 v91, v91, v195, v211
	v_fma_f32 v92, v92, v196, v212
	v_fma_f32 v93, v93, v197, v213
	v_fma_f32 v94, v94, v198, v214
	v_fma_f32 v95, v95, v199, v215
	v_fma_f32 v96, v96, v200, v216
	v_fma_f32 v97, v97, v201, v217
	v_fma_f32 v98, v98, v202, v218
	v_fma_f32 v99, v99, v203, v219
	v_fma_f32 v84, v84, v20, v4
	v_fma_f32 v85, v85, v21, v5
	v_fma_f32 v86, v86, v22, v6
	v_fma_f32 v87, v87, v23, v7
	v_fma_f32 v88, v88, v24, v8
	v_fma_f32 v89, v89, v25, v9
	v_fma_f32 v90, v90, v26, v10
	v_fma_f32 v91, v91, v27, v11
	v_fma_f32 v92, v92, v28, v12
	v_fma_f32 v93, v93, v29, v13
	v_fma_f32 v94, v94, v30, v14
	v_fma_f32 v95, v95, v31, v15
	v_fma_f32 v96, v96, v32, v16
	v_fma_f32 v97, v97, v33, v17
	v_fma_f32 v98, v98, v34, v18
	v_fma_f32 v99, v99, v35, v19
	v_cvt_pk_bf16_f32 v84, v84, v85
	v_cvt_pk_bf16_f32 v85, v86, v87
	v_cvt_pk_bf16_f32 v88, v88, v89
	v_cvt_pk_bf16_f32 v89, v90, v91
	v_cvt_pk_bf16_f32 v92, v92, v93
	v_cvt_pk_bf16_f32 v93, v94, v95
	v_cvt_pk_bf16_f32 v96, v96, v97
	v_cvt_pk_bf16_f32 v97, v98, v99
	global_store_dwordx2 v2, v[84:85], s[60:61]
	global_store_dwordx2 v2, v[88:89], s[60:61] offset:512
	global_store_dwordx2 v2, v[92:93], s[60:61] offset:1024
	global_store_dwordx2 v2, v[96:97], s[60:61] offset:1536
	s_add_u32 s60, s60, 0x400000
	s_addc_u32 s61, s61, 0
	s_nop 0
	global_load_dwordx4 v[84:87], v0, s[56:57]
	global_load_dwordx4 v[88:91], v0, s[56:57] offset:1024
	global_load_dwordx4 v[92:95], v0, s[56:57] offset:2048
	global_load_dwordx4 v[96:99], v0, s[56:57] offset:3072
	s_add_u32 s56, s56, 0x800000
	s_addc_u32 s57, s57, 0
	s_waitcnt vmcnt(35)
	v_add_f32_e32 v220, v100, v101
	v_add_f32_e32 v221, v102, v103
	v_add_f32_e32 v222, v104, v105
	v_add_f32_e32 v223, v106, v107
	v_add_f32_e32 v224, v108, v109
	v_add_f32_e32 v225, v110, v111
	v_add_f32_e32 v226, v112, v113
	v_add_f32_e32 v227, v114, v115
	v_add_f32_e32 v220, v220, v221
	v_add_f32_e32 v222, v222, v223
	v_add_f32_e32 v224, v224, v225
	v_add_f32_e32 v226, v226, v227
	v_add_f32_e32 v220, v220, v222
	v_add_f32_e32 v224, v224, v226
	v_add_f32_e32 v220, v220, v224
	s_nop 1
	v_add_f32_dpp v220, v220, v220 quad_perm:[1,0,3,2] row_mask:0xf bank_mask:0xf
	s_nop 1
	v_add_f32_dpp v220, v220, v220 quad_perm:[2,3,0,1] row_mask:0xf bank_mask:0xf
	s_nop 1
	v_add_f32_dpp v220, v220, v220 row_half_mirror row_mask:0xf bank_mask:0xf
	s_nop 1
	v_add_f32_dpp v220, v220, v220 row_mirror row_mask:0xf bank_mask:0xf
	s_nop 1
	v_add_f32_dpp v220, v220, v220 row_bcast:15 row_mask:0xa bank_mask:0xf
	s_nop 1
	v_add_f32_dpp v220, v220, v220 row_bcast:31 row_mask:0xc bank_mask:0xf
	s_nop 1
	v_readlane_b32 s6, v220, 63
	s_nop 1
	v_mov_b32_e32 v228, s6
	v_mul_f32_e32 v228, 0x3a800000, v228
	v_sub_f32_e32 v100, v100, v228
	v_sub_f32_e32 v101, v101, v228
	v_sub_f32_e32 v102, v102, v228
	v_sub_f32_e32 v103, v103, v228
	v_sub_f32_e32 v104, v104, v228
	v_sub_f32_e32 v105, v105, v228
	v_sub_f32_e32 v106, v106, v228
	v_sub_f32_e32 v107, v107, v228
	v_sub_f32_e32 v108, v108, v228
	v_sub_f32_e32 v109, v109, v228
	v_sub_f32_e32 v110, v110, v228
	v_sub_f32_e32 v111, v111, v228
	v_sub_f32_e32 v112, v112, v228
	v_sub_f32_e32 v113, v113, v228
	v_sub_f32_e32 v114, v114, v228
	v_sub_f32_e32 v115, v115, v228
	v_mul_f32_e32 v222, v100, v100
	v_mul_f32_e32 v223, v101, v101
	v_fmac_f32_e32 v222, v102, v102
	v_fmac_f32_e32 v223, v103, v103
	v_fmac_f32_e32 v222, v104, v104
	v_fmac_f32_e32 v223, v105, v105
	v_fmac_f32_e32 v222, v106, v106
	v_fmac_f32_e32 v223, v107, v107
	v_fmac_f32_e32 v222, v108, v108
	v_fmac_f32_e32 v223, v109, v109
	v_fmac_f32_e32 v222, v110, v110
	v_fmac_f32_e32 v223, v111, v111
	v_fmac_f32_e32 v222, v112, v112
	v_fmac_f32_e32 v223, v113, v113
	v_fmac_f32_e32 v222, v114, v114
	v_fmac_f32_e32 v223, v115, v115
	v_add_f32_e32 v222, v222, v223
	s_nop 1
	v_add_f32_dpp v222, v222, v222 quad_perm:[1,0,3,2] row_mask:0xf bank_mask:0xf
	s_nop 1
	v_add_f32_dpp v222, v222, v222 quad_perm:[2,3,0,1] row_mask:0xf bank_mask:0xf
	s_nop 1
	v_add_f32_dpp v222, v222, v222 row_half_mirror row_mask:0xf bank_mask:0xf
	s_nop 1
	v_add_f32_dpp v222, v222, v222 row_mirror row_mask:0xf bank_mask:0xf
	s_nop 1
	v_add_f32_dpp v222, v222, v222 row_bcast:15 row_mask:0xa bank_mask:0xf
	s_nop 1
	v_add_f32_dpp v222, v222, v222 row_bcast:31 row_mask:0xc bank_mask:0xf
	s_nop 1
	v_readlane_b32 s6, v222, 63
	s_nop 1
	v_mov_b32_e32 v224, s6
	v_mov_b32_e32 v225, 0x3727c5ac
	v_fmac_f32_e32 v225, 0x3a800000, v224
	v_rsq_f32_e32 v229, v225
	global_load_dwordx4 v[4:7], v0, s[98:99]
	global_load_dwordx4 v[8:11], v0, s[98:99] offset:1024
	global_load_dwordx4 v[12:15], v0, s[98:99] offset:2048
	global_load_dwordx4 v[16:19], v0, s[98:99] offset:3072
	global_load_dwordx4 v[20:23], v0, s[100:101]
	global_load_dwordx4 v[24:27], v0, s[100:101] offset:1024
	global_load_dwordx4 v[28:31], v0, s[100:101] offset:2048
	global_load_dwordx4 v[32:35], v0, s[100:101] offset:3072
	s_add_u32 s98, s98, 0x3000
	s_addc_u32 s99, s99, 0
	s_add_u32 s100, s100, 0x3000
	s_addc_u32 s101, s101, 0
	s_waitcnt vmcnt(26)
	v_add_f32_e32 v52, 1.0, v52
	v_add_f32_e32 v53, 1.0, v53
	v_add_f32_e32 v54, 1.0, v54
	v_add_f32_e32 v55, 1.0, v55
	v_add_f32_e32 v56, 1.0, v56
	v_add_f32_e32 v57, 1.0, v57
	v_add_f32_e32 v58, 1.0, v58
	v_add_f32_e32 v59, 1.0, v59
	v_add_f32_e32 v60, 1.0, v60
	v_add_f32_e32 v61, 1.0, v61
	v_add_f32_e32 v62, 1.0, v62
	v_add_f32_e32 v63, 1.0, v63
	v_add_f32_e32 v64, 1.0, v64
	v_add_f32_e32 v65, 1.0, v65
	v_add_f32_e32 v66, 1.0, v66
	v_add_f32_e32 v67, 1.0, v67
	s_mov_b64 exec, 1
	global_store_dwordx2 v3, v[228:229], s[62:63]
	s_mov_b64 exec, -1
	s_add_u32 s62, s62, 0x4000
	s_addc_u32 s63, s63, 0
	v_mul_f32_e32 v100, v100, v229
	v_mul_f32_e32 v101, v101, v229
	v_mul_f32_e32 v102, v102, v229
	v_mul_f32_e32 v103, v103, v229
	v_mul_f32_e32 v104, v104, v229
	v_mul_f32_e32 v105, v105, v229
	v_mul_f32_e32 v106, v106, v229
	v_mul_f32_e32 v107, v107, v229
	v_mul_f32_e32 v108, v108, v229
	v_mul_f32_e32 v109, v109, v229
	v_mul_f32_e32 v110, v110, v229
	v_mul_f32_e32 v111, v111, v229
	v_mul_f32_e32 v112, v112, v229
	v_mul_f32_e32 v113, v113, v229
	v_mul_f32_e32 v114, v114, v229
	v_mul_f32_e32 v115, v115, v229
	v_fma_f32 v100, v100, v188, v204
	v_fma_f32 v101, v101, v189, v205
	v_fma_f32 v102, v102, v190, v206
	v_fma_f32 v103, v103, v191, v207
	v_fma_f32 v104, v104, v192, v208
	v_fma_f32 v105, v105, v193, v209
	v_fma_f32 v106, v106, v194, v210
	v_fma_f32 v107, v107, v195, v211
	v_fma_f32 v108, v108, v196, v212
	v_fma_f32 v109, v109, v197, v213
	v_fma_f32 v110, v110, v198, v214
	v_fma_f32 v111, v111, v199, v215
	v_fma_f32 v112, v112, v200, v216
	v_fma_f32 v113, v113, v201, v217
	v_fma_f32 v114, v114, v202, v218
	v_fma_f32 v115, v115, v203, v219
	v_fma_f32 v100, v100, v52, v36
	v_fma_f32 v101, v101, v53, v37
	v_fma_f32 v102, v102, v54, v38
	v_fma_f32 v103, v103, v55, v39
	v_fma_f32 v104, v104, v56, v40
	v_fma_f32 v105, v105, v57, v41
	v_fma_f32 v106, v106, v58, v42
	v_fma_f32 v107, v107, v59, v43
	v_fma_f32 v108, v108, v60, v44
	v_fma_f32 v109, v109, v61, v45
	v_fma_f32 v110, v110, v62, v46
	v_fma_f32 v111, v111, v63, v47
	v_fma_f32 v112, v112, v64, v48
	v_fma_f32 v113, v113, v65, v49
	v_fma_f32 v114, v114, v66, v50
	v_fma_f32 v115, v115, v67, v51
	v_cvt_pk_bf16_f32 v100, v100, v101
	v_cvt_pk_bf16_f32 v101, v102, v103
	v_cvt_pk_bf16_f32 v104, v104, v105
	v_cvt_pk_bf16_f32 v105, v106, v107
	v_cvt_pk_bf16_f32 v108, v108, v109
	v_cvt_pk_bf16_f32 v109, v110, v111
	v_cvt_pk_bf16_f32 v112, v112, v113
	v_cvt_pk_bf16_f32 v113, v114, v115
	global_store_dwordx2 v2, v[100:101], s[60:61]
	global_store_dwordx2 v2, v[104:105], s[60:61] offset:512
	global_store_dwordx2 v2, v[108:109], s[60:61] offset:1024
	global_store_dwordx2 v2, v[112:113], s[60:61] offset:1536
	s_add_u32 s60, s60, 0x400000
	s_addc_u32 s61, s61, 0
	s_nop 0
	global_load_dwordx4 v[100:103], v0, s[56:57]
	global_load_dwordx4 v[104:107], v0, s[56:57] offset:1024
	global_load_dwordx4 v[108:111], v0, s[56:57] offset:2048
	global_load_dwordx4 v[112:115], v0, s[56:57] offset:3072
	s_add_u32 s56, s56, 0x800000
	s_addc_u32 s57, s57, 0
	s_waitcnt vmcnt(43)
	v_add_f32_e32 v220, v116, v117
	v_add_f32_e32 v221, v118, v119
	v_add_f32_e32 v222, v120, v121
	v_add_f32_e32 v223, v122, v123
	v_add_f32_e32 v224, v124, v125
	v_add_f32_e32 v225, v126, v127
	v_add_f32_e32 v226, v128, v129
	v_add_f32_e32 v227, v130, v131
	v_add_f32_e32 v220, v220, v221
	v_add_f32_e32 v222, v222, v223
	v_add_f32_e32 v224, v224, v225
	v_add_f32_e32 v226, v226, v227
	v_add_f32_e32 v220, v220, v222
	v_add_f32_e32 v224, v224, v226
	v_add_f32_e32 v220, v220, v224
	s_nop 1
	v_add_f32_dpp v220, v220, v220 quad_perm:[1,0,3,2] row_mask:0xf bank_mask:0xf
	s_nop 1
	v_add_f32_dpp v220, v220, v220 quad_perm:[2,3,0,1] row_mask:0xf bank_mask:0xf
	s_nop 1
	v_add_f32_dpp v220, v220, v220 row_half_mirror row_mask:0xf bank_mask:0xf
	s_nop 1
	v_add_f32_dpp v220, v220, v220 row_mirror row_mask:0xf bank_mask:0xf
	s_nop 1
	v_add_f32_dpp v220, v220, v220 row_bcast:15 row_mask:0xa bank_mask:0xf
	s_nop 1
	v_add_f32_dpp v220, v220, v220 row_bcast:31 row_mask:0xc bank_mask:0xf
	s_nop 1
	v_readlane_b32 s6, v220, 63
	s_nop 1
	v_mov_b32_e32 v228, s6
	v_mul_f32_e32 v228, 0x3a800000, v228
	v_sub_f32_e32 v116, v116, v228
	v_sub_f32_e32 v117, v117, v228
	v_sub_f32_e32 v118, v118, v228
	v_sub_f32_e32 v119, v119, v228
	v_sub_f32_e32 v120, v120, v228
	v_sub_f32_e32 v121, v121, v228
	v_sub_f32_e32 v122, v122, v228
	v_sub_f32_e32 v123, v123, v228
	v_sub_f32_e32 v124, v124, v228
	v_sub_f32_e32 v125, v125, v228
	v_sub_f32_e32 v126, v126, v228
	v_sub_f32_e32 v127, v127, v228
	v_sub_f32_e32 v128, v128, v228
	v_sub_f32_e32 v129, v129, v228
	v_sub_f32_e32 v130, v130, v228
	v_sub_f32_e32 v131, v131, v228
	v_mul_f32_e32 v222, v116, v116
	v_mul_f32_e32 v223, v117, v117
	v_fmac_f32_e32 v222, v118, v118
	v_fmac_f32_e32 v223, v119, v119
	v_fmac_f32_e32 v222, v120, v120
	v_fmac_f32_e32 v223, v121, v121
	v_fmac_f32_e32 v222, v122, v122
	v_fmac_f32_e32 v223, v123, v123
	v_fmac_f32_e32 v222, v124, v124
	v_fmac_f32_e32 v223, v125, v125
	v_fmac_f32_e32 v222, v126, v126
	v_fmac_f32_e32 v223, v127, v127
	v_fmac_f32_e32 v222, v128, v128
	v_fmac_f32_e32 v223, v129, v129
	v_fmac_f32_e32 v222, v130, v130
	v_fmac_f32_e32 v223, v131, v131
	v_add_f32_e32 v222, v222, v223
	s_nop 1
	v_add_f32_dpp v222, v222, v222 quad_perm:[1,0,3,2] row_mask:0xf bank_mask:0xf
	s_nop 1
	v_add_f32_dpp v222, v222, v222 quad_perm:[2,3,0,1] row_mask:0xf bank_mask:0xf
	s_nop 1
	v_add_f32_dpp v222, v222, v222 row_half_mirror row_mask:0xf bank_mask:0xf
	s_nop 1
	v_add_f32_dpp v222, v222, v222 row_mirror row_mask:0xf bank_mask:0xf
	s_nop 1
	v_add_f32_dpp v222, v222, v222 row_bcast:15 row_mask:0xa bank_mask:0xf
	s_nop 1
	v_add_f32_dpp v222, v222, v222 row_bcast:31 row_mask:0xc bank_mask:0xf
	s_nop 1
	v_readlane_b32 s6, v222, 63
	s_nop 1
	v_mov_b32_e32 v224, s6
	v_mov_b32_e32 v225, 0x3727c5ac
	v_fmac_f32_e32 v225, 0x3a800000, v224
	v_rsq_f32_e32 v229, v225
	s_nop 0
	s_mov_b64 exec, 1
	global_store_dwordx2 v3, v[228:229], s[62:63]
	s_mov_b64 exec, -1
	s_add_u32 s62, s62, 0x4000
	s_addc_u32 s63, s63, 0
	v_mul_f32_e32 v116, v116, v229
	v_mul_f32_e32 v117, v117, v229
	v_mul_f32_e32 v118, v118, v229
	v_mul_f32_e32 v119, v119, v229
	v_mul_f32_e32 v120, v120, v229
	v_mul_f32_e32 v121, v121, v229
	v_mul_f32_e32 v122, v122, v229
	v_mul_f32_e32 v123, v123, v229
	v_mul_f32_e32 v124, v124, v229
	v_mul_f32_e32 v125, v125, v229
	v_mul_f32_e32 v126, v126, v229
	v_mul_f32_e32 v127, v127, v229
	v_mul_f32_e32 v128, v128, v229
	v_mul_f32_e32 v129, v129, v229
	v_mul_f32_e32 v130, v130, v229
	v_mul_f32_e32 v131, v131, v229
	v_fma_f32 v116, v116, v188, v204
	v_fma_f32 v117, v117, v189, v205
	v_fma_f32 v118, v118, v190, v206
	v_fma_f32 v119, v119, v191, v207
	v_fma_f32 v120, v120, v192, v208
	v_fma_f32 v121, v121, v193, v209
	v_fma_f32 v122, v122, v194, v210
	v_fma_f32 v123, v123, v195, v211
	v_fma_f32 v124, v124, v196, v212
	v_fma_f32 v125, v125, v197, v213
	v_fma_f32 v126, v126, v198, v214
	v_fma_f32 v127, v127, v199, v215
	v_fma_f32 v128, v128, v200, v216
	v_fma_f32 v129, v129, v201, v217
	v_fma_f32 v130, v130, v202, v218
	v_fma_f32 v131, v131, v203, v219
	v_fma_f32 v116, v116, v52, v36
	v_fma_f32 v117, v117, v53, v37
	v_fma_f32 v118, v118, v54, v38
	v_fma_f32 v119, v119, v55, v39
	v_fma_f32 v120, v120, v56, v40
	v_fma_f32 v121, v121, v57, v41
	v_fma_f32 v122, v122, v58, v42
	v_fma_f32 v123, v123, v59, v43
	v_fma_f32 v124, v124, v60, v44
	v_fma_f32 v125, v125, v61, v45
	v_fma_f32 v126, v126, v62, v46
	v_fma_f32 v127, v127, v63, v47
	v_fma_f32 v128, v128, v64, v48
	v_fma_f32 v129, v129, v65, v49
	v_fma_f32 v130, v130, v66, v50
	v_fma_f32 v131, v131, v67, v51
	v_cvt_pk_bf16_f32 v116, v116, v117
	v_cvt_pk_bf16_f32 v117, v118, v119
	v_cvt_pk_bf16_f32 v120, v120, v121
	v_cvt_pk_bf16_f32 v121, v122, v123
	v_cvt_pk_bf16_f32 v124, v124, v125
	v_cvt_pk_bf16_f32 v125, v126, v127
	v_cvt_pk_bf16_f32 v128, v128, v129
	v_cvt_pk_bf16_f32 v129, v130, v131
	global_store_dwordx2 v2, v[116:117], s[60:61]
	global_store_dwordx2 v2, v[120:121], s[60:61] offset:512
	global_store_dwordx2 v2, v[124:125], s[60:61] offset:1024
	global_store_dwordx2 v2, v[128:129], s[60:61] offset:1536
	s_add_u32 s60, s60, 0x400000
	s_addc_u32 s61, s61, 0
	s_nop 0
	global_load_dwordx4 v[116:119], v0, s[56:57]
	global_load_dwordx4 v[120:123], v0, s[56:57] offset:1024
	global_load_dwordx4 v[124:127], v0, s[56:57] offset:2048
	global_load_dwordx4 v[128:131], v0, s[56:57] offset:3072
	s_add_u32 s56, s56, 0x800000
	s_addc_u32 s57, s57, 0
	s_waitcnt vmcnt(35)
	v_add_f32_e32 v220, v68, v69
	v_add_f32_e32 v221, v70, v71
	v_add_f32_e32 v222, v72, v73
	v_add_f32_e32 v223, v74, v75
	v_add_f32_e32 v224, v76, v77
	v_add_f32_e32 v225, v78, v79
	v_add_f32_e32 v226, v80, v81
	v_add_f32_e32 v227, v82, v83
	v_add_f32_e32 v220, v220, v221
	v_add_f32_e32 v222, v222, v223
	v_add_f32_e32 v224, v224, v225
	v_add_f32_e32 v226, v226, v227
	v_add_f32_e32 v220, v220, v222
	v_add_f32_e32 v224, v224, v226
	v_add_f32_e32 v220, v220, v224
	s_nop 1
	v_add_f32_dpp v220, v220, v220 quad_perm:[1,0,3,2] row_mask:0xf bank_mask:0xf
	s_nop 1
	v_add_f32_dpp v220, v220, v220 quad_perm:[2,3,0,1] row_mask:0xf bank_mask:0xf
	s_nop 1
	v_add_f32_dpp v220, v220, v220 row_half_mirror row_mask:0xf bank_mask:0xf
	s_nop 1
	v_add_f32_dpp v220, v220, v220 row_mirror row_mask:0xf bank_mask:0xf
	s_nop 1
	v_add_f32_dpp v220, v220, v220 row_bcast:15 row_mask:0xa bank_mask:0xf
	s_nop 1
	v_add_f32_dpp v220, v220, v220 row_bcast:31 row_mask:0xc bank_mask:0xf
	s_nop 1
	v_readlane_b32 s6, v220, 63
	s_nop 1
	v_mov_b32_e32 v228, s6
	v_mul_f32_e32 v228, 0x3a800000, v228
	v_sub_f32_e32 v68, v68, v228
	v_sub_f32_e32 v69, v69, v228
	v_sub_f32_e32 v70, v70, v228
	v_sub_f32_e32 v71, v71, v228
	v_sub_f32_e32 v72, v72, v228
	v_sub_f32_e32 v73, v73, v228
	v_sub_f32_e32 v74, v74, v228
	v_sub_f32_e32 v75, v75, v228
	v_sub_f32_e32 v76, v76, v228
	v_sub_f32_e32 v77, v77, v228
	v_sub_f32_e32 v78, v78, v228
	v_sub_f32_e32 v79, v79, v228
	v_sub_f32_e32 v80, v80, v228
	v_sub_f32_e32 v81, v81, v228
	v_sub_f32_e32 v82, v82, v228
	v_sub_f32_e32 v83, v83, v228
	v_mul_f32_e32 v222, v68, v68
	v_mul_f32_e32 v223, v69, v69
	v_fmac_f32_e32 v222, v70, v70
	v_fmac_f32_e32 v223, v71, v71
	v_fmac_f32_e32 v222, v72, v72
	v_fmac_f32_e32 v223, v73, v73
	v_fmac_f32_e32 v222, v74, v74
	v_fmac_f32_e32 v223, v75, v75
	v_fmac_f32_e32 v222, v76, v76
	v_fmac_f32_e32 v223, v77, v77
	v_fmac_f32_e32 v222, v78, v78
	v_fmac_f32_e32 v223, v79, v79
	v_fmac_f32_e32 v222, v80, v80
	v_fmac_f32_e32 v223, v81, v81
	v_fmac_f32_e32 v222, v82, v82
	v_fmac_f32_e32 v223, v83, v83
	v_add_f32_e32 v222, v222, v223
	s_nop 1
	v_add_f32_dpp v222, v222, v222 quad_perm:[1,0,3,2] row_mask:0xf bank_mask:0xf
	s_nop 1
	v_add_f32_dpp v222, v222, v222 quad_perm:[2,3,0,1] row_mask:0xf bank_mask:0xf
	s_nop 1
	v_add_f32_dpp v222, v222, v222 row_half_mirror row_mask:0xf bank_mask:0xf
	s_nop 1
	v_add_f32_dpp v222, v222, v222 row_mirror row_mask:0xf bank_mask:0xf
	s_nop 1
	v_add_f32_dpp v222, v222, v222 row_bcast:15 row_mask:0xa bank_mask:0xf
	s_nop 1
	v_add_f32_dpp v222, v222, v222 row_bcast:31 row_mask:0xc bank_mask:0xf
	s_nop 1
	v_readlane_b32 s6, v222, 63
	s_nop 1
	v_mov_b32_e32 v224, s6
	v_mov_b32_e32 v225, 0x3727c5ac
	v_fmac_f32_e32 v225, 0x3a800000, v224
	v_rsq_f32_e32 v229, v225
	global_load_dwordx4 v[36:39], v0, s[98:99]
	global_load_dwordx4 v[40:43], v0, s[98:99] offset:1024
	global_load_dwordx4 v[44:47], v0, s[98:99] offset:2048
	global_load_dwordx4 v[48:51], v0, s[98:99] offset:3072
	global_load_dwordx4 v[52:55], v0, s[100:101]
	global_load_dwordx4 v[56:59], v0, s[100:101] offset:1024
	global_load_dwordx4 v[60:63], v0, s[100:101] offset:2048
	global_load_dwordx4 v[64:67], v0, s[100:101] offset:3072
	s_add_u32 s98, s98, 0x3000
	s_addc_u32 s99, s99, 0
	s_add_u32 s100, s100, 0x3000
	s_addc_u32 s101, s101, 0
	s_waitcnt vmcnt(26)
	v_add_f32_e32 v20, 1.0, v20
	v_add_f32_e32 v21, 1.0, v21
	v_add_f32_e32 v22, 1.0, v22
	v_add_f32_e32 v23, 1.0, v23
	v_add_f32_e32 v24, 1.0, v24
	v_add_f32_e32 v25, 1.0, v25
	v_add_f32_e32 v26, 1.0, v26
	v_add_f32_e32 v27, 1.0, v27
	v_add_f32_e32 v28, 1.0, v28
	v_add_f32_e32 v29, 1.0, v29
	v_add_f32_e32 v30, 1.0, v30
	v_add_f32_e32 v31, 1.0, v31
	v_add_f32_e32 v32, 1.0, v32
	v_add_f32_e32 v33, 1.0, v33
	v_add_f32_e32 v34, 1.0, v34
	v_add_f32_e32 v35, 1.0, v35
	s_mov_b64 exec, 1
	global_store_dwordx2 v3, v[228:229], s[62:63]
	s_mov_b64 exec, -1
	s_add_u32 s62, s62, 0x4000
	s_addc_u32 s63, s63, 0
	v_mul_f32_e32 v68, v68, v229
	v_mul_f32_e32 v69, v69, v229
	v_mul_f32_e32 v70, v70, v229
	v_mul_f32_e32 v71, v71, v229
	v_mul_f32_e32 v72, v72, v229
	v_mul_f32_e32 v73, v73, v229
	v_mul_f32_e32 v74, v74, v229
	v_mul_f32_e32 v75, v75, v229
	v_mul_f32_e32 v76, v76, v229
	v_mul_f32_e32 v77, v77, v229
	v_mul_f32_e32 v78, v78, v229
	v_mul_f32_e32 v79, v79, v229
	v_mul_f32_e32 v80, v80, v229
	v_mul_f32_e32 v81, v81, v229
	v_mul_f32_e32 v82, v82, v229
	v_mul_f32_e32 v83, v83, v229
	v_fma_f32 v68, v68, v188, v204
	v_fma_f32 v69, v69, v189, v205
	v_fma_f32 v70, v70, v190, v206
	v_fma_f32 v71, v71, v191, v207
	v_fma_f32 v72, v72, v192, v208
	v_fma_f32 v73, v73, v193, v209
	v_fma_f32 v74, v74, v194, v210
	v_fma_f32 v75, v75, v195, v211
	v_fma_f32 v76, v76, v196, v212
	v_fma_f32 v77, v77, v197, v213
	v_fma_f32 v78, v78, v198, v214
	v_fma_f32 v79, v79, v199, v215
	v_fma_f32 v80, v80, v200, v216
	v_fma_f32 v81, v81, v201, v217
	v_fma_f32 v82, v82, v202, v218
	v_fma_f32 v83, v83, v203, v219
	v_fma_f32 v68, v68, v20, v4
	v_fma_f32 v69, v69, v21, v5
	v_fma_f32 v70, v70, v22, v6
	v_fma_f32 v71, v71, v23, v7
	v_fma_f32 v72, v72, v24, v8
	v_fma_f32 v73, v73, v25, v9
	v_fma_f32 v74, v74, v26, v10
	v_fma_f32 v75, v75, v27, v11
	v_fma_f32 v76, v76, v28, v12
	v_fma_f32 v77, v77, v29, v13
	v_fma_f32 v78, v78, v30, v14
	v_fma_f32 v79, v79, v31, v15
	v_fma_f32 v80, v80, v32, v16
	v_fma_f32 v81, v81, v33, v17
	v_fma_f32 v82, v82, v34, v18
	v_fma_f32 v83, v83, v35, v19
	v_cvt_pk_bf16_f32 v68, v68, v69
	v_cvt_pk_bf16_f32 v69, v70, v71
	v_cvt_pk_bf16_f32 v72, v72, v73
	v_cvt_pk_bf16_f32 v73, v74, v75
	v_cvt_pk_bf16_f32 v76, v76, v77
	v_cvt_pk_bf16_f32 v77, v78, v79
	v_cvt_pk_bf16_f32 v80, v80, v81
	v_cvt_pk_bf16_f32 v81, v82, v83
	global_store_dwordx2 v2, v[68:69], s[60:61]
	global_store_dwordx2 v2, v[72:73], s[60:61] offset:512
	global_store_dwordx2 v2, v[76:77], s[60:61] offset:1024
	global_store_dwordx2 v2, v[80:81], s[60:61] offset:1536
	s_add_u32 s60, s60, 0x400000
	s_addc_u32 s61, s61, 0
	s_nop 0
	global_load_dwordx4 v[68:71], v0, s[56:57]
	global_load_dwordx4 v[72:75], v0, s[56:57] offset:1024
	global_load_dwordx4 v[76:79], v0, s[56:57] offset:2048
	global_load_dwordx4 v[80:83], v0, s[56:57] offset:3072
	s_add_u32 s56, s56, 0x800000
	s_addc_u32 s57, s57, 0
	s_waitcnt vmcnt(43)
	v_add_f32_e32 v220, v84, v85
	v_add_f32_e32 v221, v86, v87
	v_add_f32_e32 v222, v88, v89
	v_add_f32_e32 v223, v90, v91
	v_add_f32_e32 v224, v92, v93
	v_add_f32_e32 v225, v94, v95
	v_add_f32_e32 v226, v96, v97
	v_add_f32_e32 v227, v98, v99
	v_add_f32_e32 v220, v220, v221
	v_add_f32_e32 v222, v222, v223
	v_add_f32_e32 v224, v224, v225
	v_add_f32_e32 v226, v226, v227
	v_add_f32_e32 v220, v220, v222
	v_add_f32_e32 v224, v224, v226
	v_add_f32_e32 v220, v220, v224
	s_nop 1
	v_add_f32_dpp v220, v220, v220 quad_perm:[1,0,3,2] row_mask:0xf bank_mask:0xf
	s_nop 1
	v_add_f32_dpp v220, v220, v220 quad_perm:[2,3,0,1] row_mask:0xf bank_mask:0xf
	s_nop 1
	v_add_f32_dpp v220, v220, v220 row_half_mirror row_mask:0xf bank_mask:0xf
	s_nop 1
	v_add_f32_dpp v220, v220, v220 row_mirror row_mask:0xf bank_mask:0xf
	s_nop 1
	v_add_f32_dpp v220, v220, v220 row_bcast:15 row_mask:0xa bank_mask:0xf
	s_nop 1
	v_add_f32_dpp v220, v220, v220 row_bcast:31 row_mask:0xc bank_mask:0xf
	s_nop 1
	v_readlane_b32 s6, v220, 63
	s_nop 1
	v_mov_b32_e32 v228, s6
	v_mul_f32_e32 v228, 0x3a800000, v228
	v_sub_f32_e32 v84, v84, v228
	v_sub_f32_e32 v85, v85, v228
	v_sub_f32_e32 v86, v86, v228
	v_sub_f32_e32 v87, v87, v228
	v_sub_f32_e32 v88, v88, v228
	v_sub_f32_e32 v89, v89, v228
	v_sub_f32_e32 v90, v90, v228
	v_sub_f32_e32 v91, v91, v228
	v_sub_f32_e32 v92, v92, v228
	v_sub_f32_e32 v93, v93, v228
	v_sub_f32_e32 v94, v94, v228
	v_sub_f32_e32 v95, v95, v228
	v_sub_f32_e32 v96, v96, v228
	v_sub_f32_e32 v97, v97, v228
	v_sub_f32_e32 v98, v98, v228
	v_sub_f32_e32 v99, v99, v228
	v_mul_f32_e32 v222, v84, v84
	v_mul_f32_e32 v223, v85, v85
	v_fmac_f32_e32 v222, v86, v86
	v_fmac_f32_e32 v223, v87, v87
	v_fmac_f32_e32 v222, v88, v88
	v_fmac_f32_e32 v223, v89, v89
	v_fmac_f32_e32 v222, v90, v90
	v_fmac_f32_e32 v223, v91, v91
	v_fmac_f32_e32 v222, v92, v92
	v_fmac_f32_e32 v223, v93, v93
	v_fmac_f32_e32 v222, v94, v94
	v_fmac_f32_e32 v223, v95, v95
	v_fmac_f32_e32 v222, v96, v96
	v_fmac_f32_e32 v223, v97, v97
	v_fmac_f32_e32 v222, v98, v98
	v_fmac_f32_e32 v223, v99, v99
	v_add_f32_e32 v222, v222, v223
	s_nop 1
	v_add_f32_dpp v222, v222, v222 quad_perm:[1,0,3,2] row_mask:0xf bank_mask:0xf
	s_nop 1
	v_add_f32_dpp v222, v222, v222 quad_perm:[2,3,0,1] row_mask:0xf bank_mask:0xf
	s_nop 1
	v_add_f32_dpp v222, v222, v222 row_half_mirror row_mask:0xf bank_mask:0xf
	s_nop 1
	v_add_f32_dpp v222, v222, v222 row_mirror row_mask:0xf bank_mask:0xf
	s_nop 1
	v_add_f32_dpp v222, v222, v222 row_bcast:15 row_mask:0xa bank_mask:0xf
	s_nop 1
	v_add_f32_dpp v222, v222, v222 row_bcast:31 row_mask:0xc bank_mask:0xf
	s_nop 1
	v_readlane_b32 s6, v222, 63
	s_nop 1
	v_mov_b32_e32 v224, s6
	v_mov_b32_e32 v225, 0x3727c5ac
	v_fmac_f32_e32 v225, 0x3a800000, v224
	v_rsq_f32_e32 v229, v225
	s_nop 0
	s_mov_b64 exec, 1
	global_store_dwordx2 v3, v[228:229], s[62:63]
	s_mov_b64 exec, -1
	s_add_u32 s62, s62, 0x4000
	s_addc_u32 s63, s63, 0
	v_mul_f32_e32 v84, v84, v229
	v_mul_f32_e32 v85, v85, v229
	v_mul_f32_e32 v86, v86, v229
	v_mul_f32_e32 v87, v87, v229
	v_mul_f32_e32 v88, v88, v229
	v_mul_f32_e32 v89, v89, v229
	v_mul_f32_e32 v90, v90, v229
	v_mul_f32_e32 v91, v91, v229
	v_mul_f32_e32 v92, v92, v229
	v_mul_f32_e32 v93, v93, v229
	v_mul_f32_e32 v94, v94, v229
	v_mul_f32_e32 v95, v95, v229
	v_mul_f32_e32 v96, v96, v229
	v_mul_f32_e32 v97, v97, v229
	v_mul_f32_e32 v98, v98, v229
	v_mul_f32_e32 v99, v99, v229
	v_fma_f32 v84, v84, v188, v204
	v_fma_f32 v85, v85, v189, v205
	v_fma_f32 v86, v86, v190, v206
	v_fma_f32 v87, v87, v191, v207
	v_fma_f32 v88, v88, v192, v208
	v_fma_f32 v89, v89, v193, v209
	v_fma_f32 v90, v90, v194, v210
	v_fma_f32 v91, v91, v195, v211
	v_fma_f32 v92, v92, v196, v212
	v_fma_f32 v93, v93, v197, v213
	v_fma_f32 v94, v94, v198, v214
	v_fma_f32 v95, v95, v199, v215
	v_fma_f32 v96, v96, v200, v216
	v_fma_f32 v97, v97, v201, v217
	v_fma_f32 v98, v98, v202, v218
	v_fma_f32 v99, v99, v203, v219
	v_fma_f32 v84, v84, v20, v4
	v_fma_f32 v85, v85, v21, v5
	v_fma_f32 v86, v86, v22, v6
	v_fma_f32 v87, v87, v23, v7
	v_fma_f32 v88, v88, v24, v8
	v_fma_f32 v89, v89, v25, v9
	v_fma_f32 v90, v90, v26, v10
	v_fma_f32 v91, v91, v27, v11
	v_fma_f32 v92, v92, v28, v12
	v_fma_f32 v93, v93, v29, v13
	v_fma_f32 v94, v94, v30, v14
	v_fma_f32 v95, v95, v31, v15
	v_fma_f32 v96, v96, v32, v16
	v_fma_f32 v97, v97, v33, v17
	v_fma_f32 v98, v98, v34, v18
	v_fma_f32 v99, v99, v35, v19
	v_cvt_pk_bf16_f32 v84, v84, v85
	v_cvt_pk_bf16_f32 v85, v86, v87
	v_cvt_pk_bf16_f32 v88, v88, v89
	v_cvt_pk_bf16_f32 v89, v90, v91
	v_cvt_pk_bf16_f32 v92, v92, v93
	v_cvt_pk_bf16_f32 v93, v94, v95
	v_cvt_pk_bf16_f32 v96, v96, v97
	v_cvt_pk_bf16_f32 v97, v98, v99
	global_store_dwordx2 v2, v[84:85], s[60:61]
	global_store_dwordx2 v2, v[88:89], s[60:61] offset:512
	global_store_dwordx2 v2, v[92:93], s[60:61] offset:1024
	global_store_dwordx2 v2, v[96:97], s[60:61] offset:1536
	s_add_u32 s60, s60, 0x400000
	s_addc_u32 s61, s61, 0
	s_nop 0
	global_load_dwordx4 v[84:87], v0, s[56:57]
	global_load_dwordx4 v[88:91], v0, s[56:57] offset:1024
	global_load_dwordx4 v[92:95], v0, s[56:57] offset:2048
	global_load_dwordx4 v[96:99], v0, s[56:57] offset:3072
	s_add_u32 s56, s56, 0x800000
	s_addc_u32 s57, s57, 0
	s_waitcnt vmcnt(35)
	v_add_f32_e32 v220, v100, v101
	v_add_f32_e32 v221, v102, v103
	v_add_f32_e32 v222, v104, v105
	v_add_f32_e32 v223, v106, v107
	v_add_f32_e32 v224, v108, v109
	v_add_f32_e32 v225, v110, v111
	v_add_f32_e32 v226, v112, v113
	v_add_f32_e32 v227, v114, v115
	v_add_f32_e32 v220, v220, v221
	v_add_f32_e32 v222, v222, v223
	v_add_f32_e32 v224, v224, v225
	v_add_f32_e32 v226, v226, v227
	v_add_f32_e32 v220, v220, v222
	v_add_f32_e32 v224, v224, v226
	v_add_f32_e32 v220, v220, v224
	s_nop 1
	v_add_f32_dpp v220, v220, v220 quad_perm:[1,0,3,2] row_mask:0xf bank_mask:0xf
	s_nop 1
	v_add_f32_dpp v220, v220, v220 quad_perm:[2,3,0,1] row_mask:0xf bank_mask:0xf
	s_nop 1
	v_add_f32_dpp v220, v220, v220 row_half_mirror row_mask:0xf bank_mask:0xf
	s_nop 1
	v_add_f32_dpp v220, v220, v220 row_mirror row_mask:0xf bank_mask:0xf
	s_nop 1
	v_add_f32_dpp v220, v220, v220 row_bcast:15 row_mask:0xa bank_mask:0xf
	s_nop 1
	v_add_f32_dpp v220, v220, v220 row_bcast:31 row_mask:0xc bank_mask:0xf
	s_nop 1
	v_readlane_b32 s6, v220, 63
	s_nop 1
	v_mov_b32_e32 v228, s6
	v_mul_f32_e32 v228, 0x3a800000, v228
	v_sub_f32_e32 v100, v100, v228
	v_sub_f32_e32 v101, v101, v228
	v_sub_f32_e32 v102, v102, v228
	v_sub_f32_e32 v103, v103, v228
	v_sub_f32_e32 v104, v104, v228
	v_sub_f32_e32 v105, v105, v228
	v_sub_f32_e32 v106, v106, v228
	v_sub_f32_e32 v107, v107, v228
	v_sub_f32_e32 v108, v108, v228
	v_sub_f32_e32 v109, v109, v228
	v_sub_f32_e32 v110, v110, v228
	v_sub_f32_e32 v111, v111, v228
	v_sub_f32_e32 v112, v112, v228
	v_sub_f32_e32 v113, v113, v228
	v_sub_f32_e32 v114, v114, v228
	v_sub_f32_e32 v115, v115, v228
	v_mul_f32_e32 v222, v100, v100
	v_mul_f32_e32 v223, v101, v101
	v_fmac_f32_e32 v222, v102, v102
	v_fmac_f32_e32 v223, v103, v103
	v_fmac_f32_e32 v222, v104, v104
	v_fmac_f32_e32 v223, v105, v105
	v_fmac_f32_e32 v222, v106, v106
	v_fmac_f32_e32 v223, v107, v107
	v_fmac_f32_e32 v222, v108, v108
	v_fmac_f32_e32 v223, v109, v109
	v_fmac_f32_e32 v222, v110, v110
	v_fmac_f32_e32 v223, v111, v111
	v_fmac_f32_e32 v222, v112, v112
	v_fmac_f32_e32 v223, v113, v113
	v_fmac_f32_e32 v222, v114, v114
	v_fmac_f32_e32 v223, v115, v115
	v_add_f32_e32 v222, v222, v223
	s_nop 1
	v_add_f32_dpp v222, v222, v222 quad_perm:[1,0,3,2] row_mask:0xf bank_mask:0xf
	s_nop 1
	v_add_f32_dpp v222, v222, v222 quad_perm:[2,3,0,1] row_mask:0xf bank_mask:0xf
	s_nop 1
	v_add_f32_dpp v222, v222, v222 row_half_mirror row_mask:0xf bank_mask:0xf
	s_nop 1
	v_add_f32_dpp v222, v222, v222 row_mirror row_mask:0xf bank_mask:0xf
	s_nop 1
	v_add_f32_dpp v222, v222, v222 row_bcast:15 row_mask:0xa bank_mask:0xf
	s_nop 1
	v_add_f32_dpp v222, v222, v222 row_bcast:31 row_mask:0xc bank_mask:0xf
	s_nop 1
	v_readlane_b32 s6, v222, 63
	s_nop 1
	v_mov_b32_e32 v224, s6
	v_mov_b32_e32 v225, 0x3727c5ac
	v_fmac_f32_e32 v225, 0x3a800000, v224
	v_rsq_f32_e32 v229, v225
	global_load_dwordx4 v[4:7], v0, s[98:99]
	global_load_dwordx4 v[8:11], v0, s[98:99] offset:1024
	global_load_dwordx4 v[12:15], v0, s[98:99] offset:2048
	global_load_dwordx4 v[16:19], v0, s[98:99] offset:3072
	global_load_dwordx4 v[20:23], v0, s[100:101]
	global_load_dwordx4 v[24:27], v0, s[100:101] offset:1024
	global_load_dwordx4 v[28:31], v0, s[100:101] offset:2048
	global_load_dwordx4 v[32:35], v0, s[100:101] offset:3072
	s_add_u32 s98, s98, 0x3000
	s_addc_u32 s99, s99, 0
	s_add_u32 s100, s100, 0x3000
	s_addc_u32 s101, s101, 0
	s_waitcnt vmcnt(26)
	v_add_f32_e32 v52, 1.0, v52
	v_add_f32_e32 v53, 1.0, v53
	v_add_f32_e32 v54, 1.0, v54
	v_add_f32_e32 v55, 1.0, v55
	v_add_f32_e32 v56, 1.0, v56
	v_add_f32_e32 v57, 1.0, v57
	v_add_f32_e32 v58, 1.0, v58
	v_add_f32_e32 v59, 1.0, v59
	v_add_f32_e32 v60, 1.0, v60
	v_add_f32_e32 v61, 1.0, v61
	v_add_f32_e32 v62, 1.0, v62
	v_add_f32_e32 v63, 1.0, v63
	v_add_f32_e32 v64, 1.0, v64
	v_add_f32_e32 v65, 1.0, v65
	v_add_f32_e32 v66, 1.0, v66
	v_add_f32_e32 v67, 1.0, v67
	s_mov_b64 exec, 1
	global_store_dwordx2 v3, v[228:229], s[62:63]
	s_mov_b64 exec, -1
	s_add_u32 s62, s62, 0x4000
	s_addc_u32 s63, s63, 0
	v_mul_f32_e32 v100, v100, v229
	v_mul_f32_e32 v101, v101, v229
	v_mul_f32_e32 v102, v102, v229
	v_mul_f32_e32 v103, v103, v229
	v_mul_f32_e32 v104, v104, v229
	v_mul_f32_e32 v105, v105, v229
	v_mul_f32_e32 v106, v106, v229
	v_mul_f32_e32 v107, v107, v229
	v_mul_f32_e32 v108, v108, v229
	v_mul_f32_e32 v109, v109, v229
	v_mul_f32_e32 v110, v110, v229
	v_mul_f32_e32 v111, v111, v229
	v_mul_f32_e32 v112, v112, v229
	v_mul_f32_e32 v113, v113, v229
	v_mul_f32_e32 v114, v114, v229
	v_mul_f32_e32 v115, v115, v229
	v_fma_f32 v100, v100, v188, v204
	v_fma_f32 v101, v101, v189, v205
	v_fma_f32 v102, v102, v190, v206
	v_fma_f32 v103, v103, v191, v207
	v_fma_f32 v104, v104, v192, v208
	v_fma_f32 v105, v105, v193, v209
	v_fma_f32 v106, v106, v194, v210
	v_fma_f32 v107, v107, v195, v211
	v_fma_f32 v108, v108, v196, v212
	v_fma_f32 v109, v109, v197, v213
	v_fma_f32 v110, v110, v198, v214
	v_fma_f32 v111, v111, v199, v215
	v_fma_f32 v112, v112, v200, v216
	v_fma_f32 v113, v113, v201, v217
	v_fma_f32 v114, v114, v202, v218
	v_fma_f32 v115, v115, v203, v219
	v_fma_f32 v100, v100, v52, v36
	v_fma_f32 v101, v101, v53, v37
	v_fma_f32 v102, v102, v54, v38
	v_fma_f32 v103, v103, v55, v39
	v_fma_f32 v104, v104, v56, v40
	v_fma_f32 v105, v105, v57, v41
	v_fma_f32 v106, v106, v58, v42
	v_fma_f32 v107, v107, v59, v43
	v_fma_f32 v108, v108, v60, v44
	v_fma_f32 v109, v109, v61, v45
	v_fma_f32 v110, v110, v62, v46
	v_fma_f32 v111, v111, v63, v47
	v_fma_f32 v112, v112, v64, v48
	v_fma_f32 v113, v113, v65, v49
	v_fma_f32 v114, v114, v66, v50
	v_fma_f32 v115, v115, v67, v51
	v_cvt_pk_bf16_f32 v100, v100, v101
	v_cvt_pk_bf16_f32 v101, v102, v103
	v_cvt_pk_bf16_f32 v104, v104, v105
	v_cvt_pk_bf16_f32 v105, v106, v107
	v_cvt_pk_bf16_f32 v108, v108, v109
	v_cvt_pk_bf16_f32 v109, v110, v111
	v_cvt_pk_bf16_f32 v112, v112, v113
	v_cvt_pk_bf16_f32 v113, v114, v115
	global_store_dwordx2 v2, v[100:101], s[60:61]
	global_store_dwordx2 v2, v[104:105], s[60:61] offset:512
	global_store_dwordx2 v2, v[108:109], s[60:61] offset:1024
	global_store_dwordx2 v2, v[112:113], s[60:61] offset:1536
	s_add_u32 s60, s60, 0x400000
	s_addc_u32 s61, s61, 0
	s_nop 0
	global_load_dwordx4 v[100:103], v0, s[56:57]
	global_load_dwordx4 v[104:107], v0, s[56:57] offset:1024
	global_load_dwordx4 v[108:111], v0, s[56:57] offset:2048
	global_load_dwordx4 v[112:115], v0, s[56:57] offset:3072
	s_add_u32 s56, s56, 0x800000
	s_addc_u32 s57, s57, 0
	s_waitcnt vmcnt(43)
	v_add_f32_e32 v220, v116, v117
	v_add_f32_e32 v221, v118, v119
	v_add_f32_e32 v222, v120, v121
	v_add_f32_e32 v223, v122, v123
	v_add_f32_e32 v224, v124, v125
	v_add_f32_e32 v225, v126, v127
	v_add_f32_e32 v226, v128, v129
	v_add_f32_e32 v227, v130, v131
	v_add_f32_e32 v220, v220, v221
	v_add_f32_e32 v222, v222, v223
	v_add_f32_e32 v224, v224, v225
	v_add_f32_e32 v226, v226, v227
	v_add_f32_e32 v220, v220, v222
	v_add_f32_e32 v224, v224, v226
	v_add_f32_e32 v220, v220, v224
	s_nop 1
	v_add_f32_dpp v220, v220, v220 quad_perm:[1,0,3,2] row_mask:0xf bank_mask:0xf
	s_nop 1
	v_add_f32_dpp v220, v220, v220 quad_perm:[2,3,0,1] row_mask:0xf bank_mask:0xf
	s_nop 1
	v_add_f32_dpp v220, v220, v220 row_half_mirror row_mask:0xf bank_mask:0xf
	s_nop 1
	v_add_f32_dpp v220, v220, v220 row_mirror row_mask:0xf bank_mask:0xf
	s_nop 1
	v_add_f32_dpp v220, v220, v220 row_bcast:15 row_mask:0xa bank_mask:0xf
	s_nop 1
	v_add_f32_dpp v220, v220, v220 row_bcast:31 row_mask:0xc bank_mask:0xf
	s_nop 1
	v_readlane_b32 s6, v220, 63
	s_nop 1
	v_mov_b32_e32 v228, s6
	v_mul_f32_e32 v228, 0x3a800000, v228
	v_sub_f32_e32 v116, v116, v228
	v_sub_f32_e32 v117, v117, v228
	v_sub_f32_e32 v118, v118, v228
	v_sub_f32_e32 v119, v119, v228
	v_sub_f32_e32 v120, v120, v228
	v_sub_f32_e32 v121, v121, v228
	v_sub_f32_e32 v122, v122, v228
	v_sub_f32_e32 v123, v123, v228
	v_sub_f32_e32 v124, v124, v228
	v_sub_f32_e32 v125, v125, v228
	v_sub_f32_e32 v126, v126, v228
	v_sub_f32_e32 v127, v127, v228
	v_sub_f32_e32 v128, v128, v228
	v_sub_f32_e32 v129, v129, v228
	v_sub_f32_e32 v130, v130, v228
	v_sub_f32_e32 v131, v131, v228
	v_mul_f32_e32 v222, v116, v116
	v_mul_f32_e32 v223, v117, v117
	v_fmac_f32_e32 v222, v118, v118
	v_fmac_f32_e32 v223, v119, v119
	v_fmac_f32_e32 v222, v120, v120
	v_fmac_f32_e32 v223, v121, v121
	v_fmac_f32_e32 v222, v122, v122
	v_fmac_f32_e32 v223, v123, v123
	v_fmac_f32_e32 v222, v124, v124
	v_fmac_f32_e32 v223, v125, v125
	v_fmac_f32_e32 v222, v126, v126
	v_fmac_f32_e32 v223, v127, v127
	v_fmac_f32_e32 v222, v128, v128
	v_fmac_f32_e32 v223, v129, v129
	v_fmac_f32_e32 v222, v130, v130
	v_fmac_f32_e32 v223, v131, v131
	v_add_f32_e32 v222, v222, v223
	s_nop 1
	v_add_f32_dpp v222, v222, v222 quad_perm:[1,0,3,2] row_mask:0xf bank_mask:0xf
	s_nop 1
	v_add_f32_dpp v222, v222, v222 quad_perm:[2,3,0,1] row_mask:0xf bank_mask:0xf
	s_nop 1
	v_add_f32_dpp v222, v222, v222 row_half_mirror row_mask:0xf bank_mask:0xf
	s_nop 1
	v_add_f32_dpp v222, v222, v222 row_mirror row_mask:0xf bank_mask:0xf
	s_nop 1
	v_add_f32_dpp v222, v222, v222 row_bcast:15 row_mask:0xa bank_mask:0xf
	s_nop 1
	v_add_f32_dpp v222, v222, v222 row_bcast:31 row_mask:0xc bank_mask:0xf
	s_nop 1
	v_readlane_b32 s6, v222, 63
	s_nop 1
	v_mov_b32_e32 v224, s6
	v_mov_b32_e32 v225, 0x3727c5ac
	v_fmac_f32_e32 v225, 0x3a800000, v224
	v_rsq_f32_e32 v229, v225
	s_nop 0
	s_mov_b64 exec, 1
	global_store_dwordx2 v3, v[228:229], s[62:63]
	s_mov_b64 exec, -1
	s_add_u32 s62, s62, 0x4000
	s_addc_u32 s63, s63, 0
	v_mul_f32_e32 v116, v116, v229
	v_mul_f32_e32 v117, v117, v229
	v_mul_f32_e32 v118, v118, v229
	v_mul_f32_e32 v119, v119, v229
	v_mul_f32_e32 v120, v120, v229
	v_mul_f32_e32 v121, v121, v229
	v_mul_f32_e32 v122, v122, v229
	v_mul_f32_e32 v123, v123, v229
	v_mul_f32_e32 v124, v124, v229
	v_mul_f32_e32 v125, v125, v229
	v_mul_f32_e32 v126, v126, v229
	v_mul_f32_e32 v127, v127, v229
	v_mul_f32_e32 v128, v128, v229
	v_mul_f32_e32 v129, v129, v229
	v_mul_f32_e32 v130, v130, v229
	v_mul_f32_e32 v131, v131, v229
	v_fma_f32 v116, v116, v188, v204
	v_fma_f32 v117, v117, v189, v205
	v_fma_f32 v118, v118, v190, v206
	v_fma_f32 v119, v119, v191, v207
	v_fma_f32 v120, v120, v192, v208
	v_fma_f32 v121, v121, v193, v209
	v_fma_f32 v122, v122, v194, v210
	v_fma_f32 v123, v123, v195, v211
	v_fma_f32 v124, v124, v196, v212
	v_fma_f32 v125, v125, v197, v213
	v_fma_f32 v126, v126, v198, v214
	v_fma_f32 v127, v127, v199, v215
	v_fma_f32 v128, v128, v200, v216
	v_fma_f32 v129, v129, v201, v217
	v_fma_f32 v130, v130, v202, v218
	v_fma_f32 v131, v131, v203, v219
	v_fma_f32 v116, v116, v52, v36
	v_fma_f32 v117, v117, v53, v37
	v_fma_f32 v118, v118, v54, v38
	v_fma_f32 v119, v119, v55, v39
	v_fma_f32 v120, v120, v56, v40
	v_fma_f32 v121, v121, v57, v41
	v_fma_f32 v122, v122, v58, v42
	v_fma_f32 v123, v123, v59, v43
	v_fma_f32 v124, v124, v60, v44
	v_fma_f32 v125, v125, v61, v45
	v_fma_f32 v126, v126, v62, v46
	v_fma_f32 v127, v127, v63, v47
	v_fma_f32 v128, v128, v64, v48
	v_fma_f32 v129, v129, v65, v49
	v_fma_f32 v130, v130, v66, v50
	v_fma_f32 v131, v131, v67, v51
	v_cvt_pk_bf16_f32 v116, v116, v117
	v_cvt_pk_bf16_f32 v117, v118, v119
	v_cvt_pk_bf16_f32 v120, v120, v121
	v_cvt_pk_bf16_f32 v121, v122, v123
	v_cvt_pk_bf16_f32 v124, v124, v125
	v_cvt_pk_bf16_f32 v125, v126, v127
	v_cvt_pk_bf16_f32 v128, v128, v129
	v_cvt_pk_bf16_f32 v129, v130, v131
	global_store_dwordx2 v2, v[116:117], s[60:61]
	global_store_dwordx2 v2, v[120:121], s[60:61] offset:512
	global_store_dwordx2 v2, v[124:125], s[60:61] offset:1024
	global_store_dwordx2 v2, v[128:129], s[60:61] offset:1536
	s_add_u32 s60, s60, 0x400000
	s_addc_u32 s61, s61, 0
	s_nop 0
	global_load_dwordx4 v[116:119], v0, s[56:57]
	global_load_dwordx4 v[120:123], v0, s[56:57] offset:1024
	global_load_dwordx4 v[124:127], v0, s[56:57] offset:2048
	global_load_dwordx4 v[128:131], v0, s[56:57] offset:3072
	s_add_u32 s56, s56, 0x800000
	s_addc_u32 s57, s57, 0
	s_waitcnt vmcnt(35)
	v_add_f32_e32 v220, v68, v69
	v_add_f32_e32 v221, v70, v71
	v_add_f32_e32 v222, v72, v73
	v_add_f32_e32 v223, v74, v75
	v_add_f32_e32 v224, v76, v77
	v_add_f32_e32 v225, v78, v79
	v_add_f32_e32 v226, v80, v81
	v_add_f32_e32 v227, v82, v83
	v_add_f32_e32 v220, v220, v221
	v_add_f32_e32 v222, v222, v223
	v_add_f32_e32 v224, v224, v225
	v_add_f32_e32 v226, v226, v227
	v_add_f32_e32 v220, v220, v222
	v_add_f32_e32 v224, v224, v226
	v_add_f32_e32 v220, v220, v224
	s_nop 1
	v_add_f32_dpp v220, v220, v220 quad_perm:[1,0,3,2] row_mask:0xf bank_mask:0xf
	s_nop 1
	v_add_f32_dpp v220, v220, v220 quad_perm:[2,3,0,1] row_mask:0xf bank_mask:0xf
	s_nop 1
	v_add_f32_dpp v220, v220, v220 row_half_mirror row_mask:0xf bank_mask:0xf
	s_nop 1
	v_add_f32_dpp v220, v220, v220 row_mirror row_mask:0xf bank_mask:0xf
	s_nop 1
	v_add_f32_dpp v220, v220, v220 row_bcast:15 row_mask:0xa bank_mask:0xf
	s_nop 1
	v_add_f32_dpp v220, v220, v220 row_bcast:31 row_mask:0xc bank_mask:0xf
	s_nop 1
	v_readlane_b32 s6, v220, 63
	s_nop 1
	v_mov_b32_e32 v228, s6
	v_mul_f32_e32 v228, 0x3a800000, v228
	v_sub_f32_e32 v68, v68, v228
	v_sub_f32_e32 v69, v69, v228
	v_sub_f32_e32 v70, v70, v228
	v_sub_f32_e32 v71, v71, v228
	v_sub_f32_e32 v72, v72, v228
	v_sub_f32_e32 v73, v73, v228
	v_sub_f32_e32 v74, v74, v228
	v_sub_f32_e32 v75, v75, v228
	v_sub_f32_e32 v76, v76, v228
	v_sub_f32_e32 v77, v77, v228
	v_sub_f32_e32 v78, v78, v228
	v_sub_f32_e32 v79, v79, v228
	v_sub_f32_e32 v80, v80, v228
	v_sub_f32_e32 v81, v81, v228
	v_sub_f32_e32 v82, v82, v228
	v_sub_f32_e32 v83, v83, v228
	v_mul_f32_e32 v222, v68, v68
	v_mul_f32_e32 v223, v69, v69
	v_fmac_f32_e32 v222, v70, v70
	v_fmac_f32_e32 v223, v71, v71
	v_fmac_f32_e32 v222, v72, v72
	v_fmac_f32_e32 v223, v73, v73
	v_fmac_f32_e32 v222, v74, v74
	v_fmac_f32_e32 v223, v75, v75
	v_fmac_f32_e32 v222, v76, v76
	v_fmac_f32_e32 v223, v77, v77
	v_fmac_f32_e32 v222, v78, v78
	v_fmac_f32_e32 v223, v79, v79
	v_fmac_f32_e32 v222, v80, v80
	v_fmac_f32_e32 v223, v81, v81
	v_fmac_f32_e32 v222, v82, v82
	v_fmac_f32_e32 v223, v83, v83
	v_add_f32_e32 v222, v222, v223
	s_nop 1
	v_add_f32_dpp v222, v222, v222 quad_perm:[1,0,3,2] row_mask:0xf bank_mask:0xf
	s_nop 1
	v_add_f32_dpp v222, v222, v222 quad_perm:[2,3,0,1] row_mask:0xf bank_mask:0xf
	s_nop 1
	v_add_f32_dpp v222, v222, v222 row_half_mirror row_mask:0xf bank_mask:0xf
	s_nop 1
	v_add_f32_dpp v222, v222, v222 row_mirror row_mask:0xf bank_mask:0xf
	s_nop 1
	v_add_f32_dpp v222, v222, v222 row_bcast:15 row_mask:0xa bank_mask:0xf
	s_nop 1
	v_add_f32_dpp v222, v222, v222 row_bcast:31 row_mask:0xc bank_mask:0xf
	s_nop 1
	v_readlane_b32 s6, v222, 63
	s_nop 1
	v_mov_b32_e32 v224, s6
	v_mov_b32_e32 v225, 0x3727c5ac
	v_fmac_f32_e32 v225, 0x3a800000, v224
	v_rsq_f32_e32 v229, v225
	global_load_dwordx4 v[36:39], v0, s[98:99]
	global_load_dwordx4 v[40:43], v0, s[98:99] offset:1024
	global_load_dwordx4 v[44:47], v0, s[98:99] offset:2048
	global_load_dwordx4 v[48:51], v0, s[98:99] offset:3072
	global_load_dwordx4 v[52:55], v0, s[100:101]
	global_load_dwordx4 v[56:59], v0, s[100:101] offset:1024
	global_load_dwordx4 v[60:63], v0, s[100:101] offset:2048
	global_load_dwordx4 v[64:67], v0, s[100:101] offset:3072
	s_add_u32 s98, s98, 0x3000
	s_addc_u32 s99, s99, 0
	s_add_u32 s100, s100, 0x3000
	s_addc_u32 s101, s101, 0
	s_waitcnt vmcnt(26)
	v_add_f32_e32 v20, 1.0, v20
	v_add_f32_e32 v21, 1.0, v21
	v_add_f32_e32 v22, 1.0, v22
	v_add_f32_e32 v23, 1.0, v23
	v_add_f32_e32 v24, 1.0, v24
	v_add_f32_e32 v25, 1.0, v25
	v_add_f32_e32 v26, 1.0, v26
	v_add_f32_e32 v27, 1.0, v27
	v_add_f32_e32 v28, 1.0, v28
	v_add_f32_e32 v29, 1.0, v29
	v_add_f32_e32 v30, 1.0, v30
	v_add_f32_e32 v31, 1.0, v31
	v_add_f32_e32 v32, 1.0, v32
	v_add_f32_e32 v33, 1.0, v33
	v_add_f32_e32 v34, 1.0, v34
	v_add_f32_e32 v35, 1.0, v35
	s_mov_b64 exec, 1
	global_store_dwordx2 v3, v[228:229], s[62:63]
	s_mov_b64 exec, -1
	s_add_u32 s62, s62, 0x4000
	s_addc_u32 s63, s63, 0
	v_mul_f32_e32 v68, v68, v229
	v_mul_f32_e32 v69, v69, v229
	v_mul_f32_e32 v70, v70, v229
	v_mul_f32_e32 v71, v71, v229
	v_mul_f32_e32 v72, v72, v229
	v_mul_f32_e32 v73, v73, v229
	v_mul_f32_e32 v74, v74, v229
	v_mul_f32_e32 v75, v75, v229
	v_mul_f32_e32 v76, v76, v229
	v_mul_f32_e32 v77, v77, v229
	v_mul_f32_e32 v78, v78, v229
	v_mul_f32_e32 v79, v79, v229
	v_mul_f32_e32 v80, v80, v229
	v_mul_f32_e32 v81, v81, v229
	v_mul_f32_e32 v82, v82, v229
	v_mul_f32_e32 v83, v83, v229
	v_fma_f32 v68, v68, v188, v204
	v_fma_f32 v69, v69, v189, v205
	v_fma_f32 v70, v70, v190, v206
	v_fma_f32 v71, v71, v191, v207
	v_fma_f32 v72, v72, v192, v208
	v_fma_f32 v73, v73, v193, v209
	v_fma_f32 v74, v74, v194, v210
	v_fma_f32 v75, v75, v195, v211
	v_fma_f32 v76, v76, v196, v212
	v_fma_f32 v77, v77, v197, v213
	v_fma_f32 v78, v78, v198, v214
	v_fma_f32 v79, v79, v199, v215
	v_fma_f32 v80, v80, v200, v216
	v_fma_f32 v81, v81, v201, v217
	v_fma_f32 v82, v82, v202, v218
	v_fma_f32 v83, v83, v203, v219
	v_fma_f32 v68, v68, v20, v4
	v_fma_f32 v69, v69, v21, v5
	v_fma_f32 v70, v70, v22, v6
	v_fma_f32 v71, v71, v23, v7
	v_fma_f32 v72, v72, v24, v8
	v_fma_f32 v73, v73, v25, v9
	v_fma_f32 v74, v74, v26, v10
	v_fma_f32 v75, v75, v27, v11
	v_fma_f32 v76, v76, v28, v12
	v_fma_f32 v77, v77, v29, v13
	v_fma_f32 v78, v78, v30, v14
	v_fma_f32 v79, v79, v31, v15
	v_fma_f32 v80, v80, v32, v16
	v_fma_f32 v81, v81, v33, v17
	v_fma_f32 v82, v82, v34, v18
	v_fma_f32 v83, v83, v35, v19
	v_cvt_pk_bf16_f32 v68, v68, v69
	v_cvt_pk_bf16_f32 v69, v70, v71
	v_cvt_pk_bf16_f32 v72, v72, v73
	v_cvt_pk_bf16_f32 v73, v74, v75
	v_cvt_pk_bf16_f32 v76, v76, v77
	v_cvt_pk_bf16_f32 v77, v78, v79
	v_cvt_pk_bf16_f32 v80, v80, v81
	v_cvt_pk_bf16_f32 v81, v82, v83
	global_store_dwordx2 v2, v[68:69], s[60:61]
	global_store_dwordx2 v2, v[72:73], s[60:61] offset:512
	global_store_dwordx2 v2, v[76:77], s[60:61] offset:1024
	global_store_dwordx2 v2, v[80:81], s[60:61] offset:1536
	s_add_u32 s60, s60, 0x400000
	s_addc_u32 s61, s61, 0
	s_waitcnt vmcnt(39)
	v_add_f32_e32 v220, v84, v85
	v_add_f32_e32 v221, v86, v87
	v_add_f32_e32 v222, v88, v89
	v_add_f32_e32 v223, v90, v91
	v_add_f32_e32 v224, v92, v93
	v_add_f32_e32 v225, v94, v95
	v_add_f32_e32 v226, v96, v97
	v_add_f32_e32 v227, v98, v99
	v_add_f32_e32 v220, v220, v221
	v_add_f32_e32 v222, v222, v223
	v_add_f32_e32 v224, v224, v225
	v_add_f32_e32 v226, v226, v227
	v_add_f32_e32 v220, v220, v222
	v_add_f32_e32 v224, v224, v226
	v_add_f32_e32 v220, v220, v224
	s_nop 1
	v_add_f32_dpp v220, v220, v220 quad_perm:[1,0,3,2] row_mask:0xf bank_mask:0xf
	s_nop 1
	v_add_f32_dpp v220, v220, v220 quad_perm:[2,3,0,1] row_mask:0xf bank_mask:0xf
	s_nop 1
	v_add_f32_dpp v220, v220, v220 row_half_mirror row_mask:0xf bank_mask:0xf
	s_nop 1
	v_add_f32_dpp v220, v220, v220 row_mirror row_mask:0xf bank_mask:0xf
	s_nop 1
	v_add_f32_dpp v220, v220, v220 row_bcast:15 row_mask:0xa bank_mask:0xf
	s_nop 1
	v_add_f32_dpp v220, v220, v220 row_bcast:31 row_mask:0xc bank_mask:0xf
	s_nop 1
	v_readlane_b32 s6, v220, 63
	s_nop 1
	v_mov_b32_e32 v228, s6
	v_mul_f32_e32 v228, 0x3a800000, v228
	v_sub_f32_e32 v84, v84, v228
	v_sub_f32_e32 v85, v85, v228
	v_sub_f32_e32 v86, v86, v228
	v_sub_f32_e32 v87, v87, v228
	v_sub_f32_e32 v88, v88, v228
	v_sub_f32_e32 v89, v89, v228
	v_sub_f32_e32 v90, v90, v228
	v_sub_f32_e32 v91, v91, v228
	v_sub_f32_e32 v92, v92, v228
	v_sub_f32_e32 v93, v93, v228
	v_sub_f32_e32 v94, v94, v228
	v_sub_f32_e32 v95, v95, v228
	v_sub_f32_e32 v96, v96, v228
	v_sub_f32_e32 v97, v97, v228
	v_sub_f32_e32 v98, v98, v228
	v_sub_f32_e32 v99, v99, v228
	v_mul_f32_e32 v222, v84, v84
	v_mul_f32_e32 v223, v85, v85
	v_fmac_f32_e32 v222, v86, v86
	v_fmac_f32_e32 v223, v87, v87
	v_fmac_f32_e32 v222, v88, v88
	v_fmac_f32_e32 v223, v89, v89
	v_fmac_f32_e32 v222, v90, v90
	v_fmac_f32_e32 v223, v91, v91
	v_fmac_f32_e32 v222, v92, v92
	v_fmac_f32_e32 v223, v93, v93
	v_fmac_f32_e32 v222, v94, v94
	v_fmac_f32_e32 v223, v95, v95
	v_fmac_f32_e32 v222, v96, v96
	v_fmac_f32_e32 v223, v97, v97
	v_fmac_f32_e32 v222, v98, v98
	v_fmac_f32_e32 v223, v99, v99
	v_add_f32_e32 v222, v222, v223
	s_nop 1
	v_add_f32_dpp v222, v222, v222 quad_perm:[1,0,3,2] row_mask:0xf bank_mask:0xf
	s_nop 1
	v_add_f32_dpp v222, v222, v222 quad_perm:[2,3,0,1] row_mask:0xf bank_mask:0xf
	s_nop 1
	v_add_f32_dpp v222, v222, v222 row_half_mirror row_mask:0xf bank_mask:0xf
	s_nop 1
	v_add_f32_dpp v222, v222, v222 row_mirror row_mask:0xf bank_mask:0xf
	s_nop 1
	v_add_f32_dpp v222, v222, v222 row_bcast:15 row_mask:0xa bank_mask:0xf
	s_nop 1
	v_add_f32_dpp v222, v222, v222 row_bcast:31 row_mask:0xc bank_mask:0xf
	s_nop 1
	v_readlane_b32 s6, v222, 63
	s_nop 1
	v_mov_b32_e32 v224, s6
	v_mov_b32_e32 v225, 0x3727c5ac
	v_fmac_f32_e32 v225, 0x3a800000, v224
	v_rsq_f32_e32 v229, v225
	s_nop 0
	s_mov_b64 exec, 1
	global_store_dwordx2 v3, v[228:229], s[62:63]
	s_mov_b64 exec, -1
	s_add_u32 s62, s62, 0x4000
	s_addc_u32 s63, s63, 0
	v_mul_f32_e32 v84, v84, v229
	v_mul_f32_e32 v85, v85, v229
	v_mul_f32_e32 v86, v86, v229
	v_mul_f32_e32 v87, v87, v229
	v_mul_f32_e32 v88, v88, v229
	v_mul_f32_e32 v89, v89, v229
	v_mul_f32_e32 v90, v90, v229
	v_mul_f32_e32 v91, v91, v229
	v_mul_f32_e32 v92, v92, v229
	v_mul_f32_e32 v93, v93, v229
	v_mul_f32_e32 v94, v94, v229
	v_mul_f32_e32 v95, v95, v229
	v_mul_f32_e32 v96, v96, v229
	v_mul_f32_e32 v97, v97, v229
	v_mul_f32_e32 v98, v98, v229
	v_mul_f32_e32 v99, v99, v229
	v_fma_f32 v84, v84, v188, v204
	v_fma_f32 v85, v85, v189, v205
	v_fma_f32 v86, v86, v190, v206
	v_fma_f32 v87, v87, v191, v207
	v_fma_f32 v88, v88, v192, v208
	v_fma_f32 v89, v89, v193, v209
	v_fma_f32 v90, v90, v194, v210
	v_fma_f32 v91, v91, v195, v211
	v_fma_f32 v92, v92, v196, v212
	v_fma_f32 v93, v93, v197, v213
	v_fma_f32 v94, v94, v198, v214
	v_fma_f32 v95, v95, v199, v215
	v_fma_f32 v96, v96, v200, v216
	v_fma_f32 v97, v97, v201, v217
	v_fma_f32 v98, v98, v202, v218
	v_fma_f32 v99, v99, v203, v219
	v_fma_f32 v84, v84, v20, v4
	v_fma_f32 v85, v85, v21, v5
	v_fma_f32 v86, v86, v22, v6
	v_fma_f32 v87, v87, v23, v7
	v_fma_f32 v88, v88, v24, v8
	v_fma_f32 v89, v89, v25, v9
	v_fma_f32 v90, v90, v26, v10
	v_fma_f32 v91, v91, v27, v11
	v_fma_f32 v92, v92, v28, v12
	v_fma_f32 v93, v93, v29, v13
	v_fma_f32 v94, v94, v30, v14
	v_fma_f32 v95, v95, v31, v15
	v_fma_f32 v96, v96, v32, v16
	v_fma_f32 v97, v97, v33, v17
	v_fma_f32 v98, v98, v34, v18
	v_fma_f32 v99, v99, v35, v19
	v_cvt_pk_bf16_f32 v84, v84, v85
	v_cvt_pk_bf16_f32 v85, v86, v87
	v_cvt_pk_bf16_f32 v88, v88, v89
	v_cvt_pk_bf16_f32 v89, v90, v91
	v_cvt_pk_bf16_f32 v92, v92, v93
	v_cvt_pk_bf16_f32 v93, v94, v95
	v_cvt_pk_bf16_f32 v96, v96, v97
	v_cvt_pk_bf16_f32 v97, v98, v99
	global_store_dwordx2 v2, v[84:85], s[60:61]
	global_store_dwordx2 v2, v[88:89], s[60:61] offset:512
	global_store_dwordx2 v2, v[92:93], s[60:61] offset:1024
	global_store_dwordx2 v2, v[96:97], s[60:61] offset:1536
	s_add_u32 s60, s60, 0x400000
	s_addc_u32 s61, s61, 0
	s_waitcnt vmcnt(27)
	v_add_f32_e32 v220, v100, v101
	v_add_f32_e32 v221, v102, v103
	v_add_f32_e32 v222, v104, v105
	v_add_f32_e32 v223, v106, v107
	v_add_f32_e32 v224, v108, v109
	v_add_f32_e32 v225, v110, v111
	v_add_f32_e32 v226, v112, v113
	v_add_f32_e32 v227, v114, v115
	v_add_f32_e32 v220, v220, v221
	v_add_f32_e32 v222, v222, v223
	v_add_f32_e32 v224, v224, v225
	v_add_f32_e32 v226, v226, v227
	v_add_f32_e32 v220, v220, v222
	v_add_f32_e32 v224, v224, v226
	v_add_f32_e32 v220, v220, v224
	s_nop 1
	v_add_f32_dpp v220, v220, v220 quad_perm:[1,0,3,2] row_mask:0xf bank_mask:0xf
	s_nop 1
	v_add_f32_dpp v220, v220, v220 quad_perm:[2,3,0,1] row_mask:0xf bank_mask:0xf
	s_nop 1
	v_add_f32_dpp v220, v220, v220 row_half_mirror row_mask:0xf bank_mask:0xf
	s_nop 1
	v_add_f32_dpp v220, v220, v220 row_mirror row_mask:0xf bank_mask:0xf
	s_nop 1
	v_add_f32_dpp v220, v220, v220 row_bcast:15 row_mask:0xa bank_mask:0xf
	s_nop 1
	v_add_f32_dpp v220, v220, v220 row_bcast:31 row_mask:0xc bank_mask:0xf
	s_nop 1
	v_readlane_b32 s6, v220, 63
	s_nop 1
	v_mov_b32_e32 v228, s6
	v_mul_f32_e32 v228, 0x3a800000, v228
	v_sub_f32_e32 v100, v100, v228
	v_sub_f32_e32 v101, v101, v228
	v_sub_f32_e32 v102, v102, v228
	v_sub_f32_e32 v103, v103, v228
	v_sub_f32_e32 v104, v104, v228
	v_sub_f32_e32 v105, v105, v228
	v_sub_f32_e32 v106, v106, v228
	v_sub_f32_e32 v107, v107, v228
	v_sub_f32_e32 v108, v108, v228
	v_sub_f32_e32 v109, v109, v228
	v_sub_f32_e32 v110, v110, v228
	v_sub_f32_e32 v111, v111, v228
	v_sub_f32_e32 v112, v112, v228
	v_sub_f32_e32 v113, v113, v228
	v_sub_f32_e32 v114, v114, v228
	v_sub_f32_e32 v115, v115, v228
	v_mul_f32_e32 v222, v100, v100
	v_mul_f32_e32 v223, v101, v101
	v_fmac_f32_e32 v222, v102, v102
	v_fmac_f32_e32 v223, v103, v103
	v_fmac_f32_e32 v222, v104, v104
	v_fmac_f32_e32 v223, v105, v105
	v_fmac_f32_e32 v222, v106, v106
	v_fmac_f32_e32 v223, v107, v107
	v_fmac_f32_e32 v222, v108, v108
	v_fmac_f32_e32 v223, v109, v109
	v_fmac_f32_e32 v222, v110, v110
	v_fmac_f32_e32 v223, v111, v111
	v_fmac_f32_e32 v222, v112, v112
	v_fmac_f32_e32 v223, v113, v113
	v_fmac_f32_e32 v222, v114, v114
	v_fmac_f32_e32 v223, v115, v115
	v_add_f32_e32 v222, v222, v223
	s_nop 1
	v_add_f32_dpp v222, v222, v222 quad_perm:[1,0,3,2] row_mask:0xf bank_mask:0xf
	s_nop 1
	v_add_f32_dpp v222, v222, v222 quad_perm:[2,3,0,1] row_mask:0xf bank_mask:0xf
	s_nop 1
	v_add_f32_dpp v222, v222, v222 row_half_mirror row_mask:0xf bank_mask:0xf
	s_nop 1
	v_add_f32_dpp v222, v222, v222 row_mirror row_mask:0xf bank_mask:0xf
	s_nop 1
	v_add_f32_dpp v222, v222, v222 row_bcast:15 row_mask:0xa bank_mask:0xf
	s_nop 1
	v_add_f32_dpp v222, v222, v222 row_bcast:31 row_mask:0xc bank_mask:0xf
	s_nop 1
	v_readlane_b32 s6, v222, 63
	s_nop 1
	v_mov_b32_e32 v224, s6
	v_mov_b32_e32 v225, 0x3727c5ac
	v_fmac_f32_e32 v225, 0x3a800000, v224
	v_rsq_f32_e32 v229, v225
	s_waitcnt vmcnt(10)
	v_add_f32_e32 v52, 1.0, v52
	v_add_f32_e32 v53, 1.0, v53
	v_add_f32_e32 v54, 1.0, v54
	v_add_f32_e32 v55, 1.0, v55
	v_add_f32_e32 v56, 1.0, v56
	v_add_f32_e32 v57, 1.0, v57
	v_add_f32_e32 v58, 1.0, v58
	v_add_f32_e32 v59, 1.0, v59
	v_add_f32_e32 v60, 1.0, v60
	v_add_f32_e32 v61, 1.0, v61
	v_add_f32_e32 v62, 1.0, v62
	v_add_f32_e32 v63, 1.0, v63
	v_add_f32_e32 v64, 1.0, v64
	v_add_f32_e32 v65, 1.0, v65
	v_add_f32_e32 v66, 1.0, v66
	v_add_f32_e32 v67, 1.0, v67
	s_mov_b64 exec, 1
	global_store_dwordx2 v3, v[228:229], s[62:63]
	s_mov_b64 exec, -1
	s_add_u32 s62, s62, 0x4000
	s_addc_u32 s63, s63, 0
	v_mul_f32_e32 v100, v100, v229
	v_mul_f32_e32 v101, v101, v229
	v_mul_f32_e32 v102, v102, v229
	v_mul_f32_e32 v103, v103, v229
	v_mul_f32_e32 v104, v104, v229
	v_mul_f32_e32 v105, v105, v229
	v_mul_f32_e32 v106, v106, v229
	v_mul_f32_e32 v107, v107, v229
	v_mul_f32_e32 v108, v108, v229
	v_mul_f32_e32 v109, v109, v229
	v_mul_f32_e32 v110, v110, v229
	v_mul_f32_e32 v111, v111, v229
	v_mul_f32_e32 v112, v112, v229
	v_mul_f32_e32 v113, v113, v229
	v_mul_f32_e32 v114, v114, v229
	v_mul_f32_e32 v115, v115, v229
	v_fma_f32 v100, v100, v188, v204
	v_fma_f32 v101, v101, v189, v205
	v_fma_f32 v102, v102, v190, v206
	v_fma_f32 v103, v103, v191, v207
	v_fma_f32 v104, v104, v192, v208
	v_fma_f32 v105, v105, v193, v209
	v_fma_f32 v106, v106, v194, v210
	v_fma_f32 v107, v107, v195, v211
	v_fma_f32 v108, v108, v196, v212
	v_fma_f32 v109, v109, v197, v213
	v_fma_f32 v110, v110, v198, v214
	v_fma_f32 v111, v111, v199, v215
	v_fma_f32 v112, v112, v200, v216
	v_fma_f32 v113, v113, v201, v217
	v_fma_f32 v114, v114, v202, v218
	v_fma_f32 v115, v115, v203, v219
	v_fma_f32 v100, v100, v52, v36
	v_fma_f32 v101, v101, v53, v37
	v_fma_f32 v102, v102, v54, v38
	v_fma_f32 v103, v103, v55, v39
	v_fma_f32 v104, v104, v56, v40
	v_fma_f32 v105, v105, v57, v41
	v_fma_f32 v106, v106, v58, v42
	v_fma_f32 v107, v107, v59, v43
	v_fma_f32 v108, v108, v60, v44
	v_fma_f32 v109, v109, v61, v45
	v_fma_f32 v110, v110, v62, v46
	v_fma_f32 v111, v111, v63, v47
	v_fma_f32 v112, v112, v64, v48
	v_fma_f32 v113, v113, v65, v49
	v_fma_f32 v114, v114, v66, v50
	v_fma_f32 v115, v115, v67, v51
	v_cvt_pk_bf16_f32 v100, v100, v101
	v_cvt_pk_bf16_f32 v101, v102, v103
	v_cvt_pk_bf16_f32 v104, v104, v105
	v_cvt_pk_bf16_f32 v105, v106, v107
	v_cvt_pk_bf16_f32 v108, v108, v109
	v_cvt_pk_bf16_f32 v109, v110, v111
	v_cvt_pk_bf16_f32 v112, v112, v113
	v_cvt_pk_bf16_f32 v113, v114, v115
	global_store_dwordx2 v2, v[100:101], s[60:61]
	global_store_dwordx2 v2, v[104:105], s[60:61] offset:512
	global_store_dwordx2 v2, v[108:109], s[60:61] offset:1024
	global_store_dwordx2 v2, v[112:113], s[60:61] offset:1536
	s_add_u32 s60, s60, 0x400000
	s_addc_u32 s61, s61, 0
	s_waitcnt vmcnt(23)
	v_add_f32_e32 v220, v116, v117
	v_add_f32_e32 v221, v118, v119
	v_add_f32_e32 v222, v120, v121
	v_add_f32_e32 v223, v122, v123
	v_add_f32_e32 v224, v124, v125
	v_add_f32_e32 v225, v126, v127
	v_add_f32_e32 v226, v128, v129
	v_add_f32_e32 v227, v130, v131
	v_add_f32_e32 v220, v220, v221
	v_add_f32_e32 v222, v222, v223
	v_add_f32_e32 v224, v224, v225
	v_add_f32_e32 v226, v226, v227
	v_add_f32_e32 v220, v220, v222
	v_add_f32_e32 v224, v224, v226
	v_add_f32_e32 v220, v220, v224
	s_nop 1
	v_add_f32_dpp v220, v220, v220 quad_perm:[1,0,3,2] row_mask:0xf bank_mask:0xf
	s_nop 1
	v_add_f32_dpp v220, v220, v220 quad_perm:[2,3,0,1] row_mask:0xf bank_mask:0xf
	s_nop 1
	v_add_f32_dpp v220, v220, v220 row_half_mirror row_mask:0xf bank_mask:0xf
	s_nop 1
	v_add_f32_dpp v220, v220, v220 row_mirror row_mask:0xf bank_mask:0xf
	s_nop 1
	v_add_f32_dpp v220, v220, v220 row_bcast:15 row_mask:0xa bank_mask:0xf
	s_nop 1
	v_add_f32_dpp v220, v220, v220 row_bcast:31 row_mask:0xc bank_mask:0xf
	s_nop 1
	v_readlane_b32 s6, v220, 63
	s_nop 1
	v_mov_b32_e32 v228, s6
	v_mul_f32_e32 v228, 0x3a800000, v228
	v_sub_f32_e32 v116, v116, v228
	v_sub_f32_e32 v117, v117, v228
	v_sub_f32_e32 v118, v118, v228
	v_sub_f32_e32 v119, v119, v228
	v_sub_f32_e32 v120, v120, v228
	v_sub_f32_e32 v121, v121, v228
	v_sub_f32_e32 v122, v122, v228
	v_sub_f32_e32 v123, v123, v228
	v_sub_f32_e32 v124, v124, v228
	v_sub_f32_e32 v125, v125, v228
	v_sub_f32_e32 v126, v126, v228
	v_sub_f32_e32 v127, v127, v228
	v_sub_f32_e32 v128, v128, v228
	v_sub_f32_e32 v129, v129, v228
	v_sub_f32_e32 v130, v130, v228
	v_sub_f32_e32 v131, v131, v228
	v_mul_f32_e32 v222, v116, v116
	v_mul_f32_e32 v223, v117, v117
	v_fmac_f32_e32 v222, v118, v118
	v_fmac_f32_e32 v223, v119, v119
	v_fmac_f32_e32 v222, v120, v120
	v_fmac_f32_e32 v223, v121, v121
	v_fmac_f32_e32 v222, v122, v122
	v_fmac_f32_e32 v223, v123, v123
	v_fmac_f32_e32 v222, v124, v124
	v_fmac_f32_e32 v223, v125, v125
	v_fmac_f32_e32 v222, v126, v126
	v_fmac_f32_e32 v223, v127, v127
	v_fmac_f32_e32 v222, v128, v128
	v_fmac_f32_e32 v223, v129, v129
	v_fmac_f32_e32 v222, v130, v130
	v_fmac_f32_e32 v223, v131, v131
	v_add_f32_e32 v222, v222, v223
	s_nop 1
	v_add_f32_dpp v222, v222, v222 quad_perm:[1,0,3,2] row_mask:0xf bank_mask:0xf
	s_nop 1
	v_add_f32_dpp v222, v222, v222 quad_perm:[2,3,0,1] row_mask:0xf bank_mask:0xf
	s_nop 1
	v_add_f32_dpp v222, v222, v222 row_half_mirror row_mask:0xf bank_mask:0xf
	s_nop 1
	v_add_f32_dpp v222, v222, v222 row_mirror row_mask:0xf bank_mask:0xf
	s_nop 1
	v_add_f32_dpp v222, v222, v222 row_bcast:15 row_mask:0xa bank_mask:0xf
	s_nop 1
	v_add_f32_dpp v222, v222, v222 row_bcast:31 row_mask:0xc bank_mask:0xf
	s_nop 1
	v_readlane_b32 s6, v222, 63
	s_nop 1
	v_mov_b32_e32 v224, s6
	v_mov_b32_e32 v225, 0x3727c5ac
	v_fmac_f32_e32 v225, 0x3a800000, v224
	v_rsq_f32_e32 v229, v225
	s_nop 0
	s_mov_b64 exec, 1
	global_store_dwordx2 v3, v[228:229], s[62:63]
	s_mov_b64 exec, -1
	s_add_u32 s62, s62, 0x4000
	s_addc_u32 s63, s63, 0
	v_mul_f32_e32 v116, v116, v229
	v_mul_f32_e32 v117, v117, v229
	v_mul_f32_e32 v118, v118, v229
	v_mul_f32_e32 v119, v119, v229
	v_mul_f32_e32 v120, v120, v229
	v_mul_f32_e32 v121, v121, v229
	v_mul_f32_e32 v122, v122, v229
	v_mul_f32_e32 v123, v123, v229
	v_mul_f32_e32 v124, v124, v229
	v_mul_f32_e32 v125, v125, v229
	v_mul_f32_e32 v126, v126, v229
	v_mul_f32_e32 v127, v127, v229
	v_mul_f32_e32 v128, v128, v229
	v_mul_f32_e32 v129, v129, v229
	v_mul_f32_e32 v130, v130, v229
	v_mul_f32_e32 v131, v131, v229
	v_fma_f32 v116, v116, v188, v204
	v_fma_f32 v117, v117, v189, v205
	v_fma_f32 v118, v118, v190, v206
	v_fma_f32 v119, v119, v191, v207
	v_fma_f32 v120, v120, v192, v208
	v_fma_f32 v121, v121, v193, v209
	v_fma_f32 v122, v122, v194, v210
	v_fma_f32 v123, v123, v195, v211
	v_fma_f32 v124, v124, v196, v212
	v_fma_f32 v125, v125, v197, v213
	v_fma_f32 v126, v126, v198, v214
	v_fma_f32 v127, v127, v199, v215
	v_fma_f32 v128, v128, v200, v216
	v_fma_f32 v129, v129, v201, v217
	v_fma_f32 v130, v130, v202, v218
	v_fma_f32 v131, v131, v203, v219
	v_fma_f32 v116, v116, v52, v36
	v_fma_f32 v117, v117, v53, v37
	v_fma_f32 v118, v118, v54, v38
	v_fma_f32 v119, v119, v55, v39
	v_fma_f32 v120, v120, v56, v40
	v_fma_f32 v121, v121, v57, v41
	v_fma_f32 v122, v122, v58, v42
	v_fma_f32 v123, v123, v59, v43
	v_fma_f32 v124, v124, v60, v44
	v_fma_f32 v125, v125, v61, v45
	v_fma_f32 v126, v126, v62, v46
	v_fma_f32 v127, v127, v63, v47
	v_fma_f32 v128, v128, v64, v48
	v_fma_f32 v129, v129, v65, v49
	v_fma_f32 v130, v130, v66, v50
	v_fma_f32 v131, v131, v67, v51
	v_cvt_pk_bf16_f32 v116, v116, v117
	v_cvt_pk_bf16_f32 v117, v118, v119
	v_cvt_pk_bf16_f32 v120, v120, v121
	v_cvt_pk_bf16_f32 v121, v122, v123
	v_cvt_pk_bf16_f32 v124, v124, v125
	v_cvt_pk_bf16_f32 v125, v126, v127
	v_cvt_pk_bf16_f32 v128, v128, v129
	v_cvt_pk_bf16_f32 v129, v130, v131
	global_store_dwordx2 v2, v[116:117], s[60:61]
	global_store_dwordx2 v2, v[120:121], s[60:61] offset:512
	global_store_dwordx2 v2, v[124:125], s[60:61] offset:1024
	global_store_dwordx2 v2, v[128:129], s[60:61] offset:1536
	s_add_u32 s60, s60, 0x400000
	s_addc_u32 s61, s61, 0
	s_branch .LBB0_550
.Lln5_orig:
	s_branch .LBB0_541

.LBB0_1022:
	s_or_b64 exec, exec, s[0:1]
	s_waitcnt lgkmcnt(0)
	s_barrier
	s_cmp_lg_u32 s30, 0x100
	s_cbranch_scc1 .Lln11_orig
	v_and_b32_e32 v0, 63, v254
	v_lshrrev_b32_e32 v1, 6, v254
	v_lshlrev_b32_e32 v2, 3, v0
	v_lshlrev_b32_e32 v0, 4, v0
	v_readfirstlane_b32 s7, v1
	v_mov_b32_e32 v3, 0
	s_nop 1
	s_add_i32 s7, s33, s7
	s_lshl_b32 s6, s7, 12
	s_add_u32 s56, s26, s6
	s_addc_u32 s57, s27, 0
	s_add_u32 s60, s46, 0x1000
	s_addc_u32 s61, s47, 0
	s_add_u32 s62, s48, 0x1000
	s_addc_u32 s63, s49, 0
	global_load_dwordx4 v[188:191], v0, s[60:61]
	global_load_dwordx4 v[192:195], v0, s[60:61] offset:1024
	global_load_dwordx4 v[196:199], v0, s[60:61] offset:2048
	global_load_dwordx4 v[200:203], v0, s[60:61] offset:3072
	global_load_dwordx4 v[204:207], v0, s[62:63]
	global_load_dwordx4 v[208:211], v0, s[62:63] offset:1024
	global_load_dwordx4 v[212:215], v0, s[62:63] offset:2048
	global_load_dwordx4 v[216:219], v0, s[62:63] offset:3072
	global_load_dwordx4 v[4:7], v0, s[56:57]
	global_load_dwordx4 v[8:11], v0, s[56:57] offset:1024
	global_load_dwordx4 v[12:15], v0, s[56:57] offset:2048
	global_load_dwordx4 v[16:19], v0, s[56:57] offset:3072
	s_add_u32 s56, s56, 0x800000
	s_addc_u32 s57, s57, 0
	global_load_dwordx4 v[20:23], v0, s[56:57]
	global_load_dwordx4 v[24:27], v0, s[56:57] offset:1024
	global_load_dwordx4 v[28:31], v0, s[56:57] offset:2048
	global_load_dwordx4 v[32:35], v0, s[56:57] offset:3072
	s_add_u32 s56, s56, 0x800000
	s_addc_u32 s57, s57, 0
	global_load_dwordx4 v[36:39], v0, s[56:57]
	global_load_dwordx4 v[40:43], v0, s[56:57] offset:1024
	global_load_dwordx4 v[44:47], v0, s[56:57] offset:2048
	global_load_dwordx4 v[48:51], v0, s[56:57] offset:3072
	s_add_u32 s56, s56, 0x800000
	s_addc_u32 s57, s57, 0
	global_load_dwordx4 v[52:55], v0, s[56:57]
	global_load_dwordx4 v[56:59], v0, s[56:57] offset:1024
	global_load_dwordx4 v[60:63], v0, s[56:57] offset:2048
	global_load_dwordx4 v[64:67], v0, s[56:57] offset:3072
	s_add_u32 s56, s56, 0x800000
	s_addc_u32 s57, s57, 0
	s_lshl_b32 s6, s7, 12
	s_add_u32 s98, s26, s6
	s_addc_u32 s99, s27, 0
	s_waitcnt vmcnt(12)
	v_add_f32_e32 v220, v4, v5
	v_add_f32_e32 v221, v6, v7
	v_add_f32_e32 v222, v8, v9
	v_add_f32_e32 v223, v10, v11
	v_add_f32_e32 v224, v12, v13
	v_add_f32_e32 v225, v14, v15
	v_add_f32_e32 v226, v16, v17
	v_add_f32_e32 v227, v18, v19
	v_add_f32_e32 v220, v220, v221
	v_add_f32_e32 v222, v222, v223
	v_add_f32_e32 v224, v224, v225
	v_add_f32_e32 v226, v226, v227
	v_add_f32_e32 v220, v220, v222
	v_add_f32_e32 v224, v224, v226
	v_add_f32_e32 v220, v220, v224
	s_nop 1
	v_add_f32_dpp v220, v220, v220 quad_perm:[1,0,3,2] row_mask:0xf bank_mask:0xf
	s_nop 1
	v_add_f32_dpp v220, v220, v220 quad_perm:[2,3,0,1] row_mask:0xf bank_mask:0xf
	s_nop 1
	v_add_f32_dpp v220, v220, v220 row_half_mirror row_mask:0xf bank_mask:0xf
	s_nop 1
	v_add_f32_dpp v220, v220, v220 row_mirror row_mask:0xf bank_mask:0xf
	s_nop 1
	v_add_f32_dpp v220, v220, v220 row_bcast:15 row_mask:0xa bank_mask:0xf
	s_nop 1
	v_add_f32_dpp v220, v220, v220 row_bcast:31 row_mask:0xc bank_mask:0xf
	s_nop 1
	v_readlane_b32 s6, v220, 63
	s_nop 1
	v_mov_b32_e32 v228, s6
	v_mul_f32_e32 v228, 0x3a800000, v228
	v_sub_f32_e32 v4, v4, v228
	v_sub_f32_e32 v5, v5, v228
	v_sub_f32_e32 v6, v6, v228
	v_sub_f32_e32 v7, v7, v228
	v_sub_f32_e32 v8, v8, v228
	v_sub_f32_e32 v9, v9, v228
	v_sub_f32_e32 v10, v10, v228
	v_sub_f32_e32 v11, v11, v228
	v_sub_f32_e32 v12, v12, v228
	v_sub_f32_e32 v13, v13, v228
	v_sub_f32_e32 v14, v14, v228
	v_sub_f32_e32 v15, v15, v228
	v_sub_f32_e32 v16, v16, v228
	v_sub_f32_e32 v17, v17, v228
	v_sub_f32_e32 v18, v18, v228
	v_sub_f32_e32 v19, v19, v228
	v_mul_f32_e32 v222, v4, v4
	v_mul_f32_e32 v223, v5, v5
	v_fmac_f32_e32 v222, v6, v6
	v_fmac_f32_e32 v223, v7, v7
	v_fmac_f32_e32 v222, v8, v8
	v_fmac_f32_e32 v223, v9, v9
	v_fmac_f32_e32 v222, v10, v10
	v_fmac_f32_e32 v223, v11, v11
	v_fmac_f32_e32 v222, v12, v12
	v_fmac_f32_e32 v223, v13, v13
	v_fmac_f32_e32 v222, v14, v14
	v_fmac_f32_e32 v223, v15, v15
	v_fmac_f32_e32 v222, v16, v16
	v_fmac_f32_e32 v223, v17, v17
	v_fmac_f32_e32 v222, v18, v18
	v_fmac_f32_e32 v223, v19, v19
	v_add_f32_e32 v222, v222, v223
	s_nop 1
	v_add_f32_dpp v222, v222, v222 quad_perm:[1,0,3,2] row_mask:0xf bank_mask:0xf
	s_nop 1
	v_add_f32_dpp v222, v222, v222 quad_perm:[2,3,0,1] row_mask:0xf bank_mask:0xf
	s_nop 1
	v_add_f32_dpp v222, v222, v222 row_half_mirror row_mask:0xf bank_mask:0xf
	s_nop 1
	v_add_f32_dpp v222, v222, v222 row_mirror row_mask:0xf bank_mask:0xf
	s_nop 1
	v_add_f32_dpp v222, v222, v222 row_bcast:15 row_mask:0xa bank_mask:0xf
	s_nop 1
	v_add_f32_dpp v222, v222, v222 row_bcast:31 row_mask:0xc bank_mask:0xf
	s_nop 1
	v_readlane_b32 s6, v222, 63
	s_nop 1
	v_mov_b32_e32 v224, s6
	v_mov_b32_e32 v225, 0x3727c5ac
	v_fmac_f32_e32 v225, 0x3a800000, v224
	v_rsq_f32_e32 v229, v225
	s_nop 0
	v_mul_f32_e32 v4, v4, v229
	v_mul_f32_e32 v5, v5, v229
	v_mul_f32_e32 v6, v6, v229
	v_mul_f32_e32 v7, v7, v229
	v_mul_f32_e32 v8, v8, v229
	v_mul_f32_e32 v9, v9, v229
	v_mul_f32_e32 v10, v10, v229
	v_mul_f32_e32 v11, v11, v229
	v_mul_f32_e32 v12, v12, v229
	v_mul_f32_e32 v13, v13, v229
	v_mul_f32_e32 v14, v14, v229
	v_mul_f32_e32 v15, v15, v229
	v_mul_f32_e32 v16, v16, v229
	v_mul_f32_e32 v17, v17, v229
	v_mul_f32_e32 v18, v18, v229
	v_mul_f32_e32 v19, v19, v229
	v_fma_f32 v4, v4, v188, v204
	v_fma_f32 v5, v5, v189, v205
	v_fma_f32 v6, v6, v190, v206
	v_fma_f32 v7, v7, v191, v207
	v_fma_f32 v8, v8, v192, v208
	v_fma_f32 v9, v9, v193, v209
	v_fma_f32 v10, v10, v194, v210
	v_fma_f32 v11, v11, v195, v211
	v_fma_f32 v12, v12, v196, v212
	v_fma_f32 v13, v13, v197, v213
	v_fma_f32 v14, v14, v198, v214
	v_fma_f32 v15, v15, v199, v215
	v_fma_f32 v16, v16, v200, v216
	v_fma_f32 v17, v17, v201, v217
	v_fma_f32 v18, v18, v202, v218
	v_fma_f32 v19, v19, v203, v219
	global_store_dwordx4 v0, v[4:7], s[98:99] nt
	global_store_dwordx4 v0, v[8:11], s[98:99] offset:1024 nt
	global_store_dwordx4 v0, v[12:15], s[98:99] offset:2048 nt
	global_store_dwordx4 v0, v[16:19], s[98:99] offset:3072 nt
	s_add_u32 s98, s98, 0x800000
	s_addc_u32 s99, s99, 0
	s_nop 0
	global_load_dwordx4 v[4:7], v0, s[56:57]
	global_load_dwordx4 v[8:11], v0, s[56:57] offset:1024
	global_load_dwordx4 v[12:15], v0, s[56:57] offset:2048
	global_load_dwordx4 v[16:19], v0, s[56:57] offset:3072
	s_add_u32 s56, s56, 0x800000
	s_addc_u32 s57, s57, 0
	s_waitcnt vmcnt(16)
	v_add_f32_e32 v220, v20, v21
	v_add_f32_e32 v221, v22, v23
	v_add_f32_e32 v222, v24, v25
	v_add_f32_e32 v223, v26, v27
	v_add_f32_e32 v224, v28, v29
	v_add_f32_e32 v225, v30, v31
	v_add_f32_e32 v226, v32, v33
	v_add_f32_e32 v227, v34, v35
	v_add_f32_e32 v220, v220, v221
	v_add_f32_e32 v222, v222, v223
	v_add_f32_e32 v224, v224, v225
	v_add_f32_e32 v226, v226, v227
	v_add_f32_e32 v220, v220, v222
	v_add_f32_e32 v224, v224, v226
	v_add_f32_e32 v220, v220, v224
	s_nop 1
	v_add_f32_dpp v220, v220, v220 quad_perm:[1,0,3,2] row_mask:0xf bank_mask:0xf
	s_nop 1
	v_add_f32_dpp v220, v220, v220 quad_perm:[2,3,0,1] row_mask:0xf bank_mask:0xf
	s_nop 1
	v_add_f32_dpp v220, v220, v220 row_half_mirror row_mask:0xf bank_mask:0xf
	s_nop 1
	v_add_f32_dpp v220, v220, v220 row_mirror row_mask:0xf bank_mask:0xf
	s_nop 1
	v_add_f32_dpp v220, v220, v220 row_bcast:15 row_mask:0xa bank_mask:0xf
	s_nop 1
	v_add_f32_dpp v220, v220, v220 row_bcast:31 row_mask:0xc bank_mask:0xf
	s_nop 1
	v_readlane_b32 s6, v220, 63
	s_nop 1
	v_mov_b32_e32 v228, s6
	v_mul_f32_e32 v228, 0x3a800000, v228
	v_sub_f32_e32 v20, v20, v228
	v_sub_f32_e32 v21, v21, v228
	v_sub_f32_e32 v22, v22, v228
	v_sub_f32_e32 v23, v23, v228
	v_sub_f32_e32 v24, v24, v228
	v_sub_f32_e32 v25, v25, v228
	v_sub_f32_e32 v26, v26, v228
	v_sub_f32_e32 v27, v27, v228
	v_sub_f32_e32 v28, v28, v228
	v_sub_f32_e32 v29, v29, v228
	v_sub_f32_e32 v30, v30, v228
	v_sub_f32_e32 v31, v31, v228
	v_sub_f32_e32 v32, v32, v228
	v_sub_f32_e32 v33, v33, v228
	v_sub_f32_e32 v34, v34, v228
	v_sub_f32_e32 v35, v35, v228
	v_mul_f32_e32 v222, v20, v20
	v_mul_f32_e32 v223, v21, v21
	v_fmac_f32_e32 v222, v22, v22
	v_fmac_f32_e32 v223, v23, v23
	v_fmac_f32_e32 v222, v24, v24
	v_fmac_f32_e32 v223, v25, v25
	v_fmac_f32_e32 v222, v26, v26
	v_fmac_f32_e32 v223, v27, v27
	v_fmac_f32_e32 v222, v28, v28
	v_fmac_f32_e32 v223, v29, v29
	v_fmac_f32_e32 v222, v30, v30
	v_fmac_f32_e32 v223, v31, v31
	v_fmac_f32_e32 v222, v32, v32
	v_fmac_f32_e32 v223, v33, v33
	v_fmac_f32_e32 v222, v34, v34
	v_fmac_f32_e32 v223, v35, v35
	v_add_f32_e32 v222, v222, v223
	s_nop 1
	v_add_f32_dpp v222, v222, v222 quad_perm:[1,0,3,2] row_mask:0xf bank_mask:0xf
	s_nop 1
	v_add_f32_dpp v222, v222, v222 quad_perm:[2,3,0,1] row_mask:0xf bank_mask:0xf
	s_nop 1
	v_add_f32_dpp v222, v222, v222 row_half_mirror row_mask:0xf bank_mask:0xf
	s_nop 1
	v_add_f32_dpp v222, v222, v222 row_mirror row_mask:0xf bank_mask:0xf
	s_nop 1
	v_add_f32_dpp v222, v222, v222 row_bcast:15 row_mask:0xa bank_mask:0xf
	s_nop 1
	v_add_f32_dpp v222, v222, v222 row_bcast:31 row_mask:0xc bank_mask:0xf
	s_nop 1
	v_readlane_b32 s6, v222, 63
	s_nop 1
	v_mov_b32_e32 v224, s6
	v_mov_b32_e32 v225, 0x3727c5ac
	v_fmac_f32_e32 v225, 0x3a800000, v224
	v_rsq_f32_e32 v229, v225
	s_nop 0
	v_mul_f32_e32 v20, v20, v229
	v_mul_f32_e32 v21, v21, v229
	v_mul_f32_e32 v22, v22, v229
	v_mul_f32_e32 v23, v23, v229
	v_mul_f32_e32 v24, v24, v229
	v_mul_f32_e32 v25, v25, v229
	v_mul_f32_e32 v26, v26, v229
	v_mul_f32_e32 v27, v27, v229
	v_mul_f32_e32 v28, v28, v229
	v_mul_f32_e32 v29, v29, v229
	v_mul_f32_e32 v30, v30, v229
	v_mul_f32_e32 v31, v31, v229
	v_mul_f32_e32 v32, v32, v229
	v_mul_f32_e32 v33, v33, v229
	v_mul_f32_e32 v34, v34, v229
	v_mul_f32_e32 v35, v35, v229
	v_fma_f32 v20, v20, v188, v204
	v_fma_f32 v21, v21, v189, v205
	v_fma_f32 v22, v22, v190, v206
	v_fma_f32 v23, v23, v191, v207
	v_fma_f32 v24, v24, v192, v208
	v_fma_f32 v25, v25, v193, v209
	v_fma_f32 v26, v26, v194, v210
	v_fma_f32 v27, v27, v195, v211
	v_fma_f32 v28, v28, v196, v212
	v_fma_f32 v29, v29, v197, v213
	v_fma_f32 v30, v30, v198, v214
	v_fma_f32 v31, v31, v199, v215
	v_fma_f32 v32, v32, v200, v216
	v_fma_f32 v33, v33, v201, v217
	v_fma_f32 v34, v34, v202, v218
	v_fma_f32 v35, v35, v203, v219
	global_store_dwordx4 v0, v[20:23], s[98:99] nt
	global_store_dwordx4 v0, v[24:27], s[98:99] offset:1024 nt
	global_store_dwordx4 v0, v[28:31], s[98:99] offset:2048 nt
	global_store_dwordx4 v0, v[32:35], s[98:99] offset:3072 nt
	s_add_u32 s98, s98, 0x800000
	s_addc_u32 s99, s99, 0
	s_nop 0
	global_load_dwordx4 v[20:23], v0, s[56:57]
	global_load_dwordx4 v[24:27], v0, s[56:57] offset:1024
	global_load_dwordx4 v[28:31], v0, s[56:57] offset:2048
	global_load_dwordx4 v[32:35], v0, s[56:57] offset:3072
	s_add_u32 s56, s56, 0x800000
	s_addc_u32 s57, s57, 0
	s_waitcnt vmcnt(20)
	v_add_f32_e32 v220, v36, v37
	v_add_f32_e32 v221, v38, v39
	v_add_f32_e32 v222, v40, v41
	v_add_f32_e32 v223, v42, v43
	v_add_f32_e32 v224, v44, v45
	v_add_f32_e32 v225, v46, v47
	v_add_f32_e32 v226, v48, v49
	v_add_f32_e32 v227, v50, v51
	v_add_f32_e32 v220, v220, v221
	v_add_f32_e32 v222, v222, v223
	v_add_f32_e32 v224, v224, v225
	v_add_f32_e32 v226, v226, v227
	v_add_f32_e32 v220, v220, v222
	v_add_f32_e32 v224, v224, v226
	v_add_f32_e32 v220, v220, v224
	s_nop 1
	v_add_f32_dpp v220, v220, v220 quad_perm:[1,0,3,2] row_mask:0xf bank_mask:0xf
	s_nop 1
	v_add_f32_dpp v220, v220, v220 quad_perm:[2,3,0,1] row_mask:0xf bank_mask:0xf
	s_nop 1
	v_add_f32_dpp v220, v220, v220 row_half_mirror row_mask:0xf bank_mask:0xf
	s_nop 1
	v_add_f32_dpp v220, v220, v220 row_mirror row_mask:0xf bank_mask:0xf
	s_nop 1
	v_add_f32_dpp v220, v220, v220 row_bcast:15 row_mask:0xa bank_mask:0xf
	s_nop 1
	v_add_f32_dpp v220, v220, v220 row_bcast:31 row_mask:0xc bank_mask:0xf
	s_nop 1
	v_readlane_b32 s6, v220, 63
	s_nop 1
	v_mov_b32_e32 v228, s6
	v_mul_f32_e32 v228, 0x3a800000, v228
	v_sub_f32_e32 v36, v36, v228
	v_sub_f32_e32 v37, v37, v228
	v_sub_f32_e32 v38, v38, v228
	v_sub_f32_e32 v39, v39, v228
	v_sub_f32_e32 v40, v40, v228
	v_sub_f32_e32 v41, v41, v228
	v_sub_f32_e32 v42, v42, v228
	v_sub_f32_e32 v43, v43, v228
	v_sub_f32_e32 v44, v44, v228
	v_sub_f32_e32 v45, v45, v228
	v_sub_f32_e32 v46, v46, v228
	v_sub_f32_e32 v47, v47, v228
	v_sub_f32_e32 v48, v48, v228
	v_sub_f32_e32 v49, v49, v228
	v_sub_f32_e32 v50, v50, v228
	v_sub_f32_e32 v51, v51, v228
	v_mul_f32_e32 v222, v36, v36
	v_mul_f32_e32 v223, v37, v37
	v_fmac_f32_e32 v222, v38, v38
	v_fmac_f32_e32 v223, v39, v39
	v_fmac_f32_e32 v222, v40, v40
	v_fmac_f32_e32 v223, v41, v41
	v_fmac_f32_e32 v222, v42, v42
	v_fmac_f32_e32 v223, v43, v43
	v_fmac_f32_e32 v222, v44, v44
	v_fmac_f32_e32 v223, v45, v45
	v_fmac_f32_e32 v222, v46, v46
	v_fmac_f32_e32 v223, v47, v47
	v_fmac_f32_e32 v222, v48, v48
	v_fmac_f32_e32 v223, v49, v49
	v_fmac_f32_e32 v222, v50, v50
	v_fmac_f32_e32 v223, v51, v51
	v_add_f32_e32 v222, v222, v223
	s_nop 1
	v_add_f32_dpp v222, v222, v222 quad_perm:[1,0,3,2] row_mask:0xf bank_mask:0xf
	s_nop 1
	v_add_f32_dpp v222, v222, v222 quad_perm:[2,3,0,1] row_mask:0xf bank_mask:0xf
	s_nop 1
	v_add_f32_dpp v222, v222, v222 row_half_mirror row_mask:0xf bank_mask:0xf
	s_nop 1
	v_add_f32_dpp v222, v222, v222 row_mirror row_mask:0xf bank_mask:0xf
	s_nop 1
	v_add_f32_dpp v222, v222, v222 row_bcast:15 row_mask:0xa bank_mask:0xf
	s_nop 1
	v_add_f32_dpp v222, v222, v222 row_bcast:31 row_mask:0xc bank_mask:0xf
	s_nop 1
	v_readlane_b32 s6, v222, 63
	s_nop 1
	v_mov_b32_e32 v224, s6
	v_mov_b32_e32 v225, 0x3727c5ac
	v_fmac_f32_e32 v225, 0x3a800000, v224
	v_rsq_f32_e32 v229, v225
	s_nop 0
	v_mul_f32_e32 v36, v36, v229
	v_mul_f32_e32 v37, v37, v229
	v_mul_f32_e32 v38, v38, v229
	v_mul_f32_e32 v39, v39, v229
	v_mul_f32_e32 v40, v40, v229
	v_mul_f32_e32 v41, v41, v229
	v_mul_f32_e32 v42, v42, v229
	v_mul_f32_e32 v43, v43, v229
	v_mul_f32_e32 v44, v44, v229
	v_mul_f32_e32 v45, v45, v229
	v_mul_f32_e32 v46, v46, v229
	v_mul_f32_e32 v47, v47, v229
	v_mul_f32_e32 v48, v48, v229
	v_mul_f32_e32 v49, v49, v229
	v_mul_f32_e32 v50, v50, v229
	v_mul_f32_e32 v51, v51, v229
	v_fma_f32 v36, v36, v188, v204
	v_fma_f32 v37, v37, v189, v205
	v_fma_f32 v38, v38, v190, v206
	v_fma_f32 v39, v39, v191, v207
	v_fma_f32 v40, v40, v192, v208
	v_fma_f32 v41, v41, v193, v209
	v_fma_f32 v42, v42, v194, v210
	v_fma_f32 v43, v43, v195, v211
	v_fma_f32 v44, v44, v196, v212
	v_fma_f32 v45, v45, v197, v213
	v_fma_f32 v46, v46, v198, v214
	v_fma_f32 v47, v47, v199, v215
	v_fma_f32 v48, v48, v200, v216
	v_fma_f32 v49, v49, v201, v217
	v_fma_f32 v50, v50, v202, v218
	v_fma_f32 v51, v51, v203, v219
	global_store_dwordx4 v0, v[36:39], s[98:99] nt
	global_store_dwordx4 v0, v[40:43], s[98:99] offset:1024 nt
	global_store_dwordx4 v0, v[44:47], s[98:99] offset:2048 nt
	global_store_dwordx4 v0, v[48:51], s[98:99] offset:3072 nt
	s_add_u32 s98, s98, 0x800000
	s_addc_u32 s99, s99, 0
	s_nop 0
	global_load_dwordx4 v[36:39], v0, s[56:57]
	global_load_dwordx4 v[40:43], v0, s[56:57] offset:1024
	global_load_dwordx4 v[44:47], v0, s[56:57] offset:2048
	global_load_dwordx4 v[48:51], v0, s[56:57] offset:3072
	s_add_u32 s56, s56, 0x800000
	s_addc_u32 s57, s57, 0
	s_waitcnt vmcnt(24)
	v_add_f32_e32 v220, v52, v53
	v_add_f32_e32 v221, v54, v55
	v_add_f32_e32 v222, v56, v57
	v_add_f32_e32 v223, v58, v59
	v_add_f32_e32 v224, v60, v61
	v_add_f32_e32 v225, v62, v63
	v_add_f32_e32 v226, v64, v65
	v_add_f32_e32 v227, v66, v67
	v_add_f32_e32 v220, v220, v221
	v_add_f32_e32 v222, v222, v223
	v_add_f32_e32 v224, v224, v225
	v_add_f32_e32 v226, v226, v227
	v_add_f32_e32 v220, v220, v222
	v_add_f32_e32 v224, v224, v226
	v_add_f32_e32 v220, v220, v224
	s_nop 1
	v_add_f32_dpp v220, v220, v220 quad_perm:[1,0,3,2] row_mask:0xf bank_mask:0xf
	s_nop 1
	v_add_f32_dpp v220, v220, v220 quad_perm:[2,3,0,1] row_mask:0xf bank_mask:0xf
	s_nop 1
	v_add_f32_dpp v220, v220, v220 row_half_mirror row_mask:0xf bank_mask:0xf
	s_nop 1
	v_add_f32_dpp v220, v220, v220 row_mirror row_mask:0xf bank_mask:0xf
	s_nop 1
	v_add_f32_dpp v220, v220, v220 row_bcast:15 row_mask:0xa bank_mask:0xf
	s_nop 1
	v_add_f32_dpp v220, v220, v220 row_bcast:31 row_mask:0xc bank_mask:0xf
	s_nop 1
	v_readlane_b32 s6, v220, 63
	s_nop 1
	v_mov_b32_e32 v228, s6
	v_mul_f32_e32 v228, 0x3a800000, v228
	v_sub_f32_e32 v52, v52, v228
	v_sub_f32_e32 v53, v53, v228
	v_sub_f32_e32 v54, v54, v228
	v_sub_f32_e32 v55, v55, v228
	v_sub_f32_e32 v56, v56, v228
	v_sub_f32_e32 v57, v57, v228
	v_sub_f32_e32 v58, v58, v228
	v_sub_f32_e32 v59, v59, v228
	v_sub_f32_e32 v60, v60, v228
	v_sub_f32_e32 v61, v61, v228
	v_sub_f32_e32 v62, v62, v228
	v_sub_f32_e32 v63, v63, v228
	v_sub_f32_e32 v64, v64, v228
	v_sub_f32_e32 v65, v65, v228
	v_sub_f32_e32 v66, v66, v228
	v_sub_f32_e32 v67, v67, v228
	v_mul_f32_e32 v222, v52, v52
	v_mul_f32_e32 v223, v53, v53
	v_fmac_f32_e32 v222, v54, v54
	v_fmac_f32_e32 v223, v55, v55
	v_fmac_f32_e32 v222, v56, v56
	v_fmac_f32_e32 v223, v57, v57
	v_fmac_f32_e32 v222, v58, v58
	v_fmac_f32_e32 v223, v59, v59
	v_fmac_f32_e32 v222, v60, v60
	v_fmac_f32_e32 v223, v61, v61
	v_fmac_f32_e32 v222, v62, v62
	v_fmac_f32_e32 v223, v63, v63
	v_fmac_f32_e32 v222, v64, v64
	v_fmac_f32_e32 v223, v65, v65
	v_fmac_f32_e32 v222, v66, v66
	v_fmac_f32_e32 v223, v67, v67
	v_add_f32_e32 v222, v222, v223
	s_nop 1
	v_add_f32_dpp v222, v222, v222 quad_perm:[1,0,3,2] row_mask:0xf bank_mask:0xf
	s_nop 1
	v_add_f32_dpp v222, v222, v222 quad_perm:[2,3,0,1] row_mask:0xf bank_mask:0xf
	s_nop 1
	v_add_f32_dpp v222, v222, v222 row_half_mirror row_mask:0xf bank_mask:0xf
	s_nop 1
	v_add_f32_dpp v222, v222, v222 row_mirror row_mask:0xf bank_mask:0xf
	s_nop 1
	v_add_f32_dpp v222, v222, v222 row_bcast:15 row_mask:0xa bank_mask:0xf
	s_nop 1
	v_add_f32_dpp v222, v222, v222 row_bcast:31 row_mask:0xc bank_mask:0xf
	s_nop 1
	v_readlane_b32 s6, v222, 63
	s_nop 1
	v_mov_b32_e32 v224, s6
	v_mov_b32_e32 v225, 0x3727c5ac
	v_fmac_f32_e32 v225, 0x3a800000, v224
	v_rsq_f32_e32 v229, v225
	s_nop 0
	v_mul_f32_e32 v52, v52, v229
	v_mul_f32_e32 v53, v53, v229
	v_mul_f32_e32 v54, v54, v229
	v_mul_f32_e32 v55, v55, v229
	v_mul_f32_e32 v56, v56, v229
	v_mul_f32_e32 v57, v57, v229
	v_mul_f32_e32 v58, v58, v229
	v_mul_f32_e32 v59, v59, v229
	v_mul_f32_e32 v60, v60, v229
	v_mul_f32_e32 v61, v61, v229
	v_mul_f32_e32 v62, v62, v229
	v_mul_f32_e32 v63, v63, v229
	v_mul_f32_e32 v64, v64, v229
	v_mul_f32_e32 v65, v65, v229
	v_mul_f32_e32 v66, v66, v229
	v_mul_f32_e32 v67, v67, v229
	v_fma_f32 v52, v52, v188, v204
	v_fma_f32 v53, v53, v189, v205
	v_fma_f32 v54, v54, v190, v206
	v_fma_f32 v55, v55, v191, v207
	v_fma_f32 v56, v56, v192, v208
	v_fma_f32 v57, v57, v193, v209
	v_fma_f32 v58, v58, v194, v210
	v_fma_f32 v59, v59, v195, v211
	v_fma_f32 v60, v60, v196, v212
	v_fma_f32 v61, v61, v197, v213
	v_fma_f32 v62, v62, v198, v214
	v_fma_f32 v63, v63, v199, v215
	v_fma_f32 v64, v64, v200, v216
	v_fma_f32 v65, v65, v201, v217
	v_fma_f32 v66, v66, v202, v218
	v_fma_f32 v67, v67, v203, v219
	global_store_dwordx4 v0, v[52:55], s[98:99] nt
	global_store_dwordx4 v0, v[56:59], s[98:99] offset:1024 nt
	global_store_dwordx4 v0, v[60:63], s[98:99] offset:2048 nt
	global_store_dwordx4 v0, v[64:67], s[98:99] offset:3072 nt
	s_add_u32 s98, s98, 0x800000
	s_addc_u32 s99, s99, 0
	s_nop 0
	global_load_dwordx4 v[52:55], v0, s[56:57]
	global_load_dwordx4 v[56:59], v0, s[56:57] offset:1024
	global_load_dwordx4 v[60:63], v0, s[56:57] offset:2048
	global_load_dwordx4 v[64:67], v0, s[56:57] offset:3072
	s_add_u32 s56, s56, 0x800000
	s_addc_u32 s57, s57, 0
	s_waitcnt vmcnt(24)
	v_add_f32_e32 v220, v4, v5
	v_add_f32_e32 v221, v6, v7
	v_add_f32_e32 v222, v8, v9
	v_add_f32_e32 v223, v10, v11
	v_add_f32_e32 v224, v12, v13
	v_add_f32_e32 v225, v14, v15
	v_add_f32_e32 v226, v16, v17
	v_add_f32_e32 v227, v18, v19
	v_add_f32_e32 v220, v220, v221
	v_add_f32_e32 v222, v222, v223
	v_add_f32_e32 v224, v224, v225
	v_add_f32_e32 v226, v226, v227
	v_add_f32_e32 v220, v220, v222
	v_add_f32_e32 v224, v224, v226
	v_add_f32_e32 v220, v220, v224
	s_nop 1
	v_add_f32_dpp v220, v220, v220 quad_perm:[1,0,3,2] row_mask:0xf bank_mask:0xf
	s_nop 1
	v_add_f32_dpp v220, v220, v220 quad_perm:[2,3,0,1] row_mask:0xf bank_mask:0xf
	s_nop 1
	v_add_f32_dpp v220, v220, v220 row_half_mirror row_mask:0xf bank_mask:0xf
	s_nop 1
	v_add_f32_dpp v220, v220, v220 row_mirror row_mask:0xf bank_mask:0xf
	s_nop 1
	v_add_f32_dpp v220, v220, v220 row_bcast:15 row_mask:0xa bank_mask:0xf
	s_nop 1
	v_add_f32_dpp v220, v220, v220 row_bcast:31 row_mask:0xc bank_mask:0xf
	s_nop 1
	v_readlane_b32 s6, v220, 63
	s_nop 1
	v_mov_b32_e32 v228, s6
	v_mul_f32_e32 v228, 0x3a800000, v228
	v_sub_f32_e32 v4, v4, v228
	v_sub_f32_e32 v5, v5, v228
	v_sub_f32_e32 v6, v6, v228
	v_sub_f32_e32 v7, v7, v228
	v_sub_f32_e32 v8, v8, v228
	v_sub_f32_e32 v9, v9, v228
	v_sub_f32_e32 v10, v10, v228
	v_sub_f32_e32 v11, v11, v228
	v_sub_f32_e32 v12, v12, v228
	v_sub_f32_e32 v13, v13, v228
	v_sub_f32_e32 v14, v14, v228
	v_sub_f32_e32 v15, v15, v228
	v_sub_f32_e32 v16, v16, v228
	v_sub_f32_e32 v17, v17, v228
	v_sub_f32_e32 v18, v18, v228
	v_sub_f32_e32 v19, v19, v228
	v_mul_f32_e32 v222, v4, v4
	v_mul_f32_e32 v223, v5, v5
	v_fmac_f32_e32 v222, v6, v6
	v_fmac_f32_e32 v223, v7, v7
	v_fmac_f32_e32 v222, v8, v8
	v_fmac_f32_e32 v223, v9, v9
	v_fmac_f32_e32 v222, v10, v10
	v_fmac_f32_e32 v223, v11, v11
	v_fmac_f32_e32 v222, v12, v12
	v_fmac_f32_e32 v223, v13, v13
	v_fmac_f32_e32 v222, v14, v14
	v_fmac_f32_e32 v223, v15, v15
	v_fmac_f32_e32 v222, v16, v16
	v_fmac_f32_e32 v223, v17, v17
	v_fmac_f32_e32 v222, v18, v18
	v_fmac_f32_e32 v223, v19, v19
	v_add_f32_e32 v222, v222, v223
	s_nop 1
	v_add_f32_dpp v222, v222, v222 quad_perm:[1,0,3,2] row_mask:0xf bank_mask:0xf
	s_nop 1
	v_add_f32_dpp v222, v222, v222 quad_perm:[2,3,0,1] row_mask:0xf bank_mask:0xf
	s_nop 1
	v_add_f32_dpp v222, v222, v222 row_half_mirror row_mask:0xf bank_mask:0xf
	s_nop 1
	v_add_f32_dpp v222, v222, v222 row_mirror row_mask:0xf bank_mask:0xf
	s_nop 1
	v_add_f32_dpp v222, v222, v222 row_bcast:15 row_mask:0xa bank_mask:0xf
	s_nop 1
	v_add_f32_dpp v222, v222, v222 row_bcast:31 row_mask:0xc bank_mask:0xf
	s_nop 1
	v_readlane_b32 s6, v222, 63
	s_nop 1
	v_mov_b32_e32 v224, s6
	v_mov_b32_e32 v225, 0x3727c5ac
	v_fmac_f32_e32 v225, 0x3a800000, v224
	v_rsq_f32_e32 v229, v225
	s_nop 0
	v_mul_f32_e32 v4, v4, v229
	v_mul_f32_e32 v5, v5, v229
	v_mul_f32_e32 v6, v6, v229
	v_mul_f32_e32 v7, v7, v229
	v_mul_f32_e32 v8, v8, v229
	v_mul_f32_e32 v9, v9, v229
	v_mul_f32_e32 v10, v10, v229
	v_mul_f32_e32 v11, v11, v229
	v_mul_f32_e32 v12, v12, v229
	v_mul_f32_e32 v13, v13, v229
	v_mul_f32_e32 v14, v14, v229
	v_mul_f32_e32 v15, v15, v229
	v_mul_f32_e32 v16, v16, v229
	v_mul_f32_e32 v17, v17, v229
	v_mul_f32_e32 v18, v18, v229
	v_mul_f32_e32 v19, v19, v229
	v_fma_f32 v4, v4, v188, v204
	v_fma_f32 v5, v5, v189, v205
	v_fma_f32 v6, v6, v190, v206
	v_fma_f32 v7, v7, v191, v207
	v_fma_f32 v8, v8, v192, v208
	v_fma_f32 v9, v9, v193, v209
	v_fma_f32 v10, v10, v194, v210
	v_fma_f32 v11, v11, v195, v211
	v_fma_f32 v12, v12, v196, v212
	v_fma_f32 v13, v13, v197, v213
	v_fma_f32 v14, v14, v198, v214
	v_fma_f32 v15, v15, v199, v215
	v_fma_f32 v16, v16, v200, v216
	v_fma_f32 v17, v17, v201, v217
	v_fma_f32 v18, v18, v202, v218
	v_fma_f32 v19, v19, v203, v219
	global_store_dwordx4 v0, v[4:7], s[98:99] nt
	global_store_dwordx4 v0, v[8:11], s[98:99] offset:1024 nt
	global_store_dwordx4 v0, v[12:15], s[98:99] offset:2048 nt
	global_store_dwordx4 v0, v[16:19], s[98:99] offset:3072 nt
	s_add_u32 s98, s98, 0x800000
	s_addc_u32 s99, s99, 0
	s_nop 0
	global_load_dwordx4 v[4:7], v0, s[56:57]
	global_load_dwordx4 v[8:11], v0, s[56:57] offset:1024
	global_load_dwordx4 v[12:15], v0, s[56:57] offset:2048
	global_load_dwordx4 v[16:19], v0, s[56:57] offset:3072
	s_add_u32 s56, s56, 0x800000
	s_addc_u32 s57, s57, 0
	s_waitcnt vmcnt(24)
	v_add_f32_e32 v220, v20, v21
	v_add_f32_e32 v221, v22, v23
	v_add_f32_e32 v222, v24, v25
	v_add_f32_e32 v223, v26, v27
	v_add_f32_e32 v224, v28, v29
	v_add_f32_e32 v225, v30, v31
	v_add_f32_e32 v226, v32, v33
	v_add_f32_e32 v227, v34, v35
	v_add_f32_e32 v220, v220, v221
	v_add_f32_e32 v222, v222, v223
	v_add_f32_e32 v224, v224, v225
	v_add_f32_e32 v226, v226, v227
	v_add_f32_e32 v220, v220, v222
	v_add_f32_e32 v224, v224, v226
	v_add_f32_e32 v220, v220, v224
	s_nop 1
	v_add_f32_dpp v220, v220, v220 quad_perm:[1,0,3,2] row_mask:0xf bank_mask:0xf
	s_nop 1
	v_add_f32_dpp v220, v220, v220 quad_perm:[2,3,0,1] row_mask:0xf bank_mask:0xf
	s_nop 1
	v_add_f32_dpp v220, v220, v220 row_half_mirror row_mask:0xf bank_mask:0xf
	s_nop 1
	v_add_f32_dpp v220, v220, v220 row_mirror row_mask:0xf bank_mask:0xf
	s_nop 1
	v_add_f32_dpp v220, v220, v220 row_bcast:15 row_mask:0xa bank_mask:0xf
	s_nop 1
	v_add_f32_dpp v220, v220, v220 row_bcast:31 row_mask:0xc bank_mask:0xf
	s_nop 1
	v_readlane_b32 s6, v220, 63
	s_nop 1
	v_mov_b32_e32 v228, s6
	v_mul_f32_e32 v228, 0x3a800000, v228
	v_sub_f32_e32 v20, v20, v228
	v_sub_f32_e32 v21, v21, v228
	v_sub_f32_e32 v22, v22, v228
	v_sub_f32_e32 v23, v23, v228
	v_sub_f32_e32 v24, v24, v228
	v_sub_f32_e32 v25, v25, v228
	v_sub_f32_e32 v26, v26, v228
	v_sub_f32_e32 v27, v27, v228
	v_sub_f32_e32 v28, v28, v228
	v_sub_f32_e32 v29, v29, v228
	v_sub_f32_e32 v30, v30, v228
	v_sub_f32_e32 v31, v31, v228
	v_sub_f32_e32 v32, v32, v228
	v_sub_f32_e32 v33, v33, v228
	v_sub_f32_e32 v34, v34, v228
	v_sub_f32_e32 v35, v35, v228
	v_mul_f32_e32 v222, v20, v20
	v_mul_f32_e32 v223, v21, v21
	v_fmac_f32_e32 v222, v22, v22
	v_fmac_f32_e32 v223, v23, v23
	v_fmac_f32_e32 v222, v24, v24
	v_fmac_f32_e32 v223, v25, v25
	v_fmac_f32_e32 v222, v26, v26
	v_fmac_f32_e32 v223, v27, v27
	v_fmac_f32_e32 v222, v28, v28
	v_fmac_f32_e32 v223, v29, v29
	v_fmac_f32_e32 v222, v30, v30
	v_fmac_f32_e32 v223, v31, v31
	v_fmac_f32_e32 v222, v32, v32
	v_fmac_f32_e32 v223, v33, v33
	v_fmac_f32_e32 v222, v34, v34
	v_fmac_f32_e32 v223, v35, v35
	v_add_f32_e32 v222, v222, v223
	s_nop 1
	v_add_f32_dpp v222, v222, v222 quad_perm:[1,0,3,2] row_mask:0xf bank_mask:0xf
	s_nop 1
	v_add_f32_dpp v222, v222, v222 quad_perm:[2,3,0,1] row_mask:0xf bank_mask:0xf
	s_nop 1
	v_add_f32_dpp v222, v222, v222 row_half_mirror row_mask:0xf bank_mask:0xf
	s_nop 1
	v_add_f32_dpp v222, v222, v222 row_mirror row_mask:0xf bank_mask:0xf
	s_nop 1
	v_add_f32_dpp v222, v222, v222 row_bcast:15 row_mask:0xa bank_mask:0xf
	s_nop 1
	v_add_f32_dpp v222, v222, v222 row_bcast:31 row_mask:0xc bank_mask:0xf
	s_nop 1
	v_readlane_b32 s6, v222, 63
	s_nop 1
	v_mov_b32_e32 v224, s6
	v_mov_b32_e32 v225, 0x3727c5ac
	v_fmac_f32_e32 v225, 0x3a800000, v224
	v_rsq_f32_e32 v229, v225
	s_nop 0
	v_mul_f32_e32 v20, v20, v229
	v_mul_f32_e32 v21, v21, v229
	v_mul_f32_e32 v22, v22, v229
	v_mul_f32_e32 v23, v23, v229
	v_mul_f32_e32 v24, v24, v229
	v_mul_f32_e32 v25, v25, v229
	v_mul_f32_e32 v26, v26, v229
	v_mul_f32_e32 v27, v27, v229
	v_mul_f32_e32 v28, v28, v229
	v_mul_f32_e32 v29, v29, v229
	v_mul_f32_e32 v30, v30, v229
	v_mul_f32_e32 v31, v31, v229
	v_mul_f32_e32 v32, v32, v229
	v_mul_f32_e32 v33, v33, v229
	v_mul_f32_e32 v34, v34, v229
	v_mul_f32_e32 v35, v35, v229
	v_fma_f32 v20, v20, v188, v204
	v_fma_f32 v21, v21, v189, v205
	v_fma_f32 v22, v22, v190, v206
	v_fma_f32 v23, v23, v191, v207
	v_fma_f32 v24, v24, v192, v208
	v_fma_f32 v25, v25, v193, v209
	v_fma_f32 v26, v26, v194, v210
	v_fma_f32 v27, v27, v195, v211
	v_fma_f32 v28, v28, v196, v212
	v_fma_f32 v29, v29, v197, v213
	v_fma_f32 v30, v30, v198, v214
	v_fma_f32 v31, v31, v199, v215
	v_fma_f32 v32, v32, v200, v216
	v_fma_f32 v33, v33, v201, v217
	v_fma_f32 v34, v34, v202, v218
	v_fma_f32 v35, v35, v203, v219
	global_store_dwordx4 v0, v[20:23], s[98:99] nt
	global_store_dwordx4 v0, v[24:27], s[98:99] offset:1024 nt
	global_store_dwordx4 v0, v[28:31], s[98:99] offset:2048 nt
	global_store_dwordx4 v0, v[32:35], s[98:99] offset:3072 nt
	s_add_u32 s98, s98, 0x800000
	s_addc_u32 s99, s99, 0
	s_nop 0
	global_load_dwordx4 v[20:23], v0, s[56:57]
	global_load_dwordx4 v[24:27], v0, s[56:57] offset:1024
	global_load_dwordx4 v[28:31], v0, s[56:57] offset:2048
	global_load_dwordx4 v[32:35], v0, s[56:57] offset:3072
	s_add_u32 s56, s56, 0x800000
	s_addc_u32 s57, s57, 0
	s_waitcnt vmcnt(24)
	v_add_f32_e32 v220, v36, v37
	v_add_f32_e32 v221, v38, v39
	v_add_f32_e32 v222, v40, v41
	v_add_f32_e32 v223, v42, v43
	v_add_f32_e32 v224, v44, v45
	v_add_f32_e32 v225, v46, v47
	v_add_f32_e32 v226, v48, v49
	v_add_f32_e32 v227, v50, v51
	v_add_f32_e32 v220, v220, v221
	v_add_f32_e32 v222, v222, v223
	v_add_f32_e32 v224, v224, v225
	v_add_f32_e32 v226, v226, v227
	v_add_f32_e32 v220, v220, v222
	v_add_f32_e32 v224, v224, v226
	v_add_f32_e32 v220, v220, v224
	s_nop 1
	v_add_f32_dpp v220, v220, v220 quad_perm:[1,0,3,2] row_mask:0xf bank_mask:0xf
	s_nop 1
	v_add_f32_dpp v220, v220, v220 quad_perm:[2,3,0,1] row_mask:0xf bank_mask:0xf
	s_nop 1
	v_add_f32_dpp v220, v220, v220 row_half_mirror row_mask:0xf bank_mask:0xf
	s_nop 1
	v_add_f32_dpp v220, v220, v220 row_mirror row_mask:0xf bank_mask:0xf
	s_nop 1
	v_add_f32_dpp v220, v220, v220 row_bcast:15 row_mask:0xa bank_mask:0xf
	s_nop 1
	v_add_f32_dpp v220, v220, v220 row_bcast:31 row_mask:0xc bank_mask:0xf
	s_nop 1
	v_readlane_b32 s6, v220, 63
	s_nop 1
	v_mov_b32_e32 v228, s6
	v_mul_f32_e32 v228, 0x3a800000, v228
	v_sub_f32_e32 v36, v36, v228
	v_sub_f32_e32 v37, v37, v228
	v_sub_f32_e32 v38, v38, v228
	v_sub_f32_e32 v39, v39, v228
	v_sub_f32_e32 v40, v40, v228
	v_sub_f32_e32 v41, v41, v228
	v_sub_f32_e32 v42, v42, v228
	v_sub_f32_e32 v43, v43, v228
	v_sub_f32_e32 v44, v44, v228
	v_sub_f32_e32 v45, v45, v228
	v_sub_f32_e32 v46, v46, v228
	v_sub_f32_e32 v47, v47, v228
	v_sub_f32_e32 v48, v48, v228
	v_sub_f32_e32 v49, v49, v228
	v_sub_f32_e32 v50, v50, v228
	v_sub_f32_e32 v51, v51, v228
	v_mul_f32_e32 v222, v36, v36
	v_mul_f32_e32 v223, v37, v37
	v_fmac_f32_e32 v222, v38, v38
	v_fmac_f32_e32 v223, v39, v39
	v_fmac_f32_e32 v222, v40, v40
	v_fmac_f32_e32 v223, v41, v41
	v_fmac_f32_e32 v222, v42, v42
	v_fmac_f32_e32 v223, v43, v43
	v_fmac_f32_e32 v222, v44, v44
	v_fmac_f32_e32 v223, v45, v45
	v_fmac_f32_e32 v222, v46, v46
	v_fmac_f32_e32 v223, v47, v47
	v_fmac_f32_e32 v222, v48, v48
	v_fmac_f32_e32 v223, v49, v49
	v_fmac_f32_e32 v222, v50, v50
	v_fmac_f32_e32 v223, v51, v51
	v_add_f32_e32 v222, v222, v223
	s_nop 1
	v_add_f32_dpp v222, v222, v222 quad_perm:[1,0,3,2] row_mask:0xf bank_mask:0xf
	s_nop 1
	v_add_f32_dpp v222, v222, v222 quad_perm:[2,3,0,1] row_mask:0xf bank_mask:0xf
	s_nop 1
	v_add_f32_dpp v222, v222, v222 row_half_mirror row_mask:0xf bank_mask:0xf
	s_nop 1
	v_add_f32_dpp v222, v222, v222 row_mirror row_mask:0xf bank_mask:0xf
	s_nop 1
	v_add_f32_dpp v222, v222, v222 row_bcast:15 row_mask:0xa bank_mask:0xf
	s_nop 1
	v_add_f32_dpp v222, v222, v222 row_bcast:31 row_mask:0xc bank_mask:0xf
	s_nop 1
	v_readlane_b32 s6, v222, 63
	s_nop 1
	v_mov_b32_e32 v224, s6
	v_mov_b32_e32 v225, 0x3727c5ac
	v_fmac_f32_e32 v225, 0x3a800000, v224
	v_rsq_f32_e32 v229, v225
	s_nop 0
	v_mul_f32_e32 v36, v36, v229
	v_mul_f32_e32 v37, v37, v229
	v_mul_f32_e32 v38, v38, v229
	v_mul_f32_e32 v39, v39, v229
	v_mul_f32_e32 v40, v40, v229
	v_mul_f32_e32 v41, v41, v229
	v_mul_f32_e32 v42, v42, v229
	v_mul_f32_e32 v43, v43, v229
	v_mul_f32_e32 v44, v44, v229
	v_mul_f32_e32 v45, v45, v229
	v_mul_f32_e32 v46, v46, v229
	v_mul_f32_e32 v47, v47, v229
	v_mul_f32_e32 v48, v48, v229
	v_mul_f32_e32 v49, v49, v229
	v_mul_f32_e32 v50, v50, v229
	v_mul_f32_e32 v51, v51, v229
	v_fma_f32 v36, v36, v188, v204
	v_fma_f32 v37, v37, v189, v205
	v_fma_f32 v38, v38, v190, v206
	v_fma_f32 v39, v39, v191, v207
	v_fma_f32 v40, v40, v192, v208
	v_fma_f32 v41, v41, v193, v209
	v_fma_f32 v42, v42, v194, v210
	v_fma_f32 v43, v43, v195, v211
	v_fma_f32 v44, v44, v196, v212
	v_fma_f32 v45, v45, v197, v213
	v_fma_f32 v46, v46, v198, v214
	v_fma_f32 v47, v47, v199, v215
	v_fma_f32 v48, v48, v200, v216
	v_fma_f32 v49, v49, v201, v217
	v_fma_f32 v50, v50, v202, v218
	v_fma_f32 v51, v51, v203, v219
	global_store_dwordx4 v0, v[36:39], s[98:99] nt
	global_store_dwordx4 v0, v[40:43], s[98:99] offset:1024 nt
	global_store_dwordx4 v0, v[44:47], s[98:99] offset:2048 nt
	global_store_dwordx4 v0, v[48:51], s[98:99] offset:3072 nt
	s_add_u32 s98, s98, 0x800000
	s_addc_u32 s99, s99, 0
	s_nop 0
	global_load_dwordx4 v[36:39], v0, s[56:57]
	global_load_dwordx4 v[40:43], v0, s[56:57] offset:1024
	global_load_dwordx4 v[44:47], v0, s[56:57] offset:2048
	global_load_dwordx4 v[48:51], v0, s[56:57] offset:3072
	s_add_u32 s56, s56, 0x800000
	s_addc_u32 s57, s57, 0
	s_waitcnt vmcnt(24)
	v_add_f32_e32 v220, v52, v53
	v_add_f32_e32 v221, v54, v55
	v_add_f32_e32 v222, v56, v57
	v_add_f32_e32 v223, v58, v59
	v_add_f32_e32 v224, v60, v61
	v_add_f32_e32 v225, v62, v63
	v_add_f32_e32 v226, v64, v65
	v_add_f32_e32 v227, v66, v67
	v_add_f32_e32 v220, v220, v221
	v_add_f32_e32 v222, v222, v223
	v_add_f32_e32 v224, v224, v225
	v_add_f32_e32 v226, v226, v227
	v_add_f32_e32 v220, v220, v222
	v_add_f32_e32 v224, v224, v226
	v_add_f32_e32 v220, v220, v224
	s_nop 1
	v_add_f32_dpp v220, v220, v220 quad_perm:[1,0,3,2] row_mask:0xf bank_mask:0xf
	s_nop 1
	v_add_f32_dpp v220, v220, v220 quad_perm:[2,3,0,1] row_mask:0xf bank_mask:0xf
	s_nop 1
	v_add_f32_dpp v220, v220, v220 row_half_mirror row_mask:0xf bank_mask:0xf
	s_nop 1
	v_add_f32_dpp v220, v220, v220 row_mirror row_mask:0xf bank_mask:0xf
	s_nop 1
	v_add_f32_dpp v220, v220, v220 row_bcast:15 row_mask:0xa bank_mask:0xf
	s_nop 1
	v_add_f32_dpp v220, v220, v220 row_bcast:31 row_mask:0xc bank_mask:0xf
	s_nop 1
	v_readlane_b32 s6, v220, 63
	s_nop 1
	v_mov_b32_e32 v228, s6
	v_mul_f32_e32 v228, 0x3a800000, v228
	v_sub_f32_e32 v52, v52, v228
	v_sub_f32_e32 v53, v53, v228
	v_sub_f32_e32 v54, v54, v228
	v_sub_f32_e32 v55, v55, v228
	v_sub_f32_e32 v56, v56, v228
	v_sub_f32_e32 v57, v57, v228
	v_sub_f32_e32 v58, v58, v228
	v_sub_f32_e32 v59, v59, v228
	v_sub_f32_e32 v60, v60, v228
	v_sub_f32_e32 v61, v61, v228
	v_sub_f32_e32 v62, v62, v228
	v_sub_f32_e32 v63, v63, v228
	v_sub_f32_e32 v64, v64, v228
	v_sub_f32_e32 v65, v65, v228
	v_sub_f32_e32 v66, v66, v228
	v_sub_f32_e32 v67, v67, v228
	v_mul_f32_e32 v222, v52, v52
	v_mul_f32_e32 v223, v53, v53
	v_fmac_f32_e32 v222, v54, v54
	v_fmac_f32_e32 v223, v55, v55
	v_fmac_f32_e32 v222, v56, v56
	v_fmac_f32_e32 v223, v57, v57
	v_fmac_f32_e32 v222, v58, v58
	v_fmac_f32_e32 v223, v59, v59
	v_fmac_f32_e32 v222, v60, v60
	v_fmac_f32_e32 v223, v61, v61
	v_fmac_f32_e32 v222, v62, v62
	v_fmac_f32_e32 v223, v63, v63
	v_fmac_f32_e32 v222, v64, v64
	v_fmac_f32_e32 v223, v65, v65
	v_fmac_f32_e32 v222, v66, v66
	v_fmac_f32_e32 v223, v67, v67
	v_add_f32_e32 v222, v222, v223
	s_nop 1
	v_add_f32_dpp v222, v222, v222 quad_perm:[1,0,3,2] row_mask:0xf bank_mask:0xf
	s_nop 1
	v_add_f32_dpp v222, v222, v222 quad_perm:[2,3,0,1] row_mask:0xf bank_mask:0xf
	s_nop 1
	v_add_f32_dpp v222, v222, v222 row_half_mirror row_mask:0xf bank_mask:0xf
	s_nop 1
	v_add_f32_dpp v222, v222, v222 row_mirror row_mask:0xf bank_mask:0xf
	s_nop 1
	v_add_f32_dpp v222, v222, v222 row_bcast:15 row_mask:0xa bank_mask:0xf
	s_nop 1
	v_add_f32_dpp v222, v222, v222 row_bcast:31 row_mask:0xc bank_mask:0xf
	s_nop 1
	v_readlane_b32 s6, v222, 63
	s_nop 1
	v_mov_b32_e32 v224, s6
	v_mov_b32_e32 v225, 0x3727c5ac
	v_fmac_f32_e32 v225, 0x3a800000, v224
	v_rsq_f32_e32 v229, v225
	s_nop 0
	v_mul_f32_e32 v52, v52, v229
	v_mul_f32_e32 v53, v53, v229
	v_mul_f32_e32 v54, v54, v229
	v_mul_f32_e32 v55, v55, v229
	v_mul_f32_e32 v56, v56, v229
	v_mul_f32_e32 v57, v57, v229
	v_mul_f32_e32 v58, v58, v229
	v_mul_f32_e32 v59, v59, v229
	v_mul_f32_e32 v60, v60, v229
	v_mul_f32_e32 v61, v61, v229
	v_mul_f32_e32 v62, v62, v229
	v_mul_f32_e32 v63, v63, v229
	v_mul_f32_e32 v64, v64, v229
	v_mul_f32_e32 v65, v65, v229
	v_mul_f32_e32 v66, v66, v229
	v_mul_f32_e32 v67, v67, v229
	v_fma_f32 v52, v52, v188, v204
	v_fma_f32 v53, v53, v189, v205
	v_fma_f32 v54, v54, v190, v206
	v_fma_f32 v55, v55, v191, v207
	v_fma_f32 v56, v56, v192, v208
	v_fma_f32 v57, v57, v193, v209
	v_fma_f32 v58, v58, v194, v210
	v_fma_f32 v59, v59, v195, v211
	v_fma_f32 v60, v60, v196, v212
	v_fma_f32 v61, v61, v197, v213
	v_fma_f32 v62, v62, v198, v214
	v_fma_f32 v63, v63, v199, v215
	v_fma_f32 v64, v64, v200, v216
	v_fma_f32 v65, v65, v201, v217
	v_fma_f32 v66, v66, v202, v218
	v_fma_f32 v67, v67, v203, v219
	global_store_dwordx4 v0, v[52:55], s[98:99] nt
	global_store_dwordx4 v0, v[56:59], s[98:99] offset:1024 nt
	global_store_dwordx4 v0, v[60:63], s[98:99] offset:2048 nt
	global_store_dwordx4 v0, v[64:67], s[98:99] offset:3072 nt
	s_add_u32 s98, s98, 0x800000
	s_addc_u32 s99, s99, 0
	s_nop 0
	global_load_dwordx4 v[52:55], v0, s[56:57]
	global_load_dwordx4 v[56:59], v0, s[56:57] offset:1024
	global_load_dwordx4 v[60:63], v0, s[56:57] offset:2048
	global_load_dwordx4 v[64:67], v0, s[56:57] offset:3072
	s_add_u32 s56, s56, 0x800000
	s_addc_u32 s57, s57, 0
	s_waitcnt vmcnt(24)
	v_add_f32_e32 v220, v4, v5
	v_add_f32_e32 v221, v6, v7
	v_add_f32_e32 v222, v8, v9
	v_add_f32_e32 v223, v10, v11
	v_add_f32_e32 v224, v12, v13
	v_add_f32_e32 v225, v14, v15
	v_add_f32_e32 v226, v16, v17
	v_add_f32_e32 v227, v18, v19
	v_add_f32_e32 v220, v220, v221
	v_add_f32_e32 v222, v222, v223
	v_add_f32_e32 v224, v224, v225
	v_add_f32_e32 v226, v226, v227
	v_add_f32_e32 v220, v220, v222
	v_add_f32_e32 v224, v224, v226
	v_add_f32_e32 v220, v220, v224
	s_nop 1
	v_add_f32_dpp v220, v220, v220 quad_perm:[1,0,3,2] row_mask:0xf bank_mask:0xf
	s_nop 1
	v_add_f32_dpp v220, v220, v220 quad_perm:[2,3,0,1] row_mask:0xf bank_mask:0xf
	s_nop 1
	v_add_f32_dpp v220, v220, v220 row_half_mirror row_mask:0xf bank_mask:0xf
	s_nop 1
	v_add_f32_dpp v220, v220, v220 row_mirror row_mask:0xf bank_mask:0xf
	s_nop 1
	v_add_f32_dpp v220, v220, v220 row_bcast:15 row_mask:0xa bank_mask:0xf
	s_nop 1
	v_add_f32_dpp v220, v220, v220 row_bcast:31 row_mask:0xc bank_mask:0xf
	s_nop 1
	v_readlane_b32 s6, v220, 63
	s_nop 1
	v_mov_b32_e32 v228, s6
	v_mul_f32_e32 v228, 0x3a800000, v228
	v_sub_f32_e32 v4, v4, v228
	v_sub_f32_e32 v5, v5, v228
	v_sub_f32_e32 v6, v6, v228
	v_sub_f32_e32 v7, v7, v228
	v_sub_f32_e32 v8, v8, v228
	v_sub_f32_e32 v9, v9, v228
	v_sub_f32_e32 v10, v10, v228
	v_sub_f32_e32 v11, v11, v228
	v_sub_f32_e32 v12, v12, v228
	v_sub_f32_e32 v13, v13, v228
	v_sub_f32_e32 v14, v14, v228
	v_sub_f32_e32 v15, v15, v228
	v_sub_f32_e32 v16, v16, v228
	v_sub_f32_e32 v17, v17, v228
	v_sub_f32_e32 v18, v18, v228
	v_sub_f32_e32 v19, v19, v228
	v_mul_f32_e32 v222, v4, v4
	v_mul_f32_e32 v223, v5, v5
	v_fmac_f32_e32 v222, v6, v6
	v_fmac_f32_e32 v223, v7, v7
	v_fmac_f32_e32 v222, v8, v8
	v_fmac_f32_e32 v223, v9, v9
	v_fmac_f32_e32 v222, v10, v10
	v_fmac_f32_e32 v223, v11, v11
	v_fmac_f32_e32 v222, v12, v12
	v_fmac_f32_e32 v223, v13, v13
	v_fmac_f32_e32 v222, v14, v14
	v_fmac_f32_e32 v223, v15, v15
	v_fmac_f32_e32 v222, v16, v16
	v_fmac_f32_e32 v223, v17, v17
	v_fmac_f32_e32 v222, v18, v18
	v_fmac_f32_e32 v223, v19, v19
	v_add_f32_e32 v222, v222, v223
	s_nop 1
	v_add_f32_dpp v222, v222, v222 quad_perm:[1,0,3,2] row_mask:0xf bank_mask:0xf
	s_nop 1
	v_add_f32_dpp v222, v222, v222 quad_perm:[2,3,0,1] row_mask:0xf bank_mask:0xf
	s_nop 1
	v_add_f32_dpp v222, v222, v222 row_half_mirror row_mask:0xf bank_mask:0xf
	s_nop 1
	v_add_f32_dpp v222, v222, v222 row_mirror row_mask:0xf bank_mask:0xf
	s_nop 1
	v_add_f32_dpp v222, v222, v222 row_bcast:15 row_mask:0xa bank_mask:0xf
	s_nop 1
	v_add_f32_dpp v222, v222, v222 row_bcast:31 row_mask:0xc bank_mask:0xf
	s_nop 1
	v_readlane_b32 s6, v222, 63
	s_nop 1
	v_mov_b32_e32 v224, s6
	v_mov_b32_e32 v225, 0x3727c5ac
	v_fmac_f32_e32 v225, 0x3a800000, v224
	v_rsq_f32_e32 v229, v225
	s_nop 0
	v_mul_f32_e32 v4, v4, v229
	v_mul_f32_e32 v5, v5, v229
	v_mul_f32_e32 v6, v6, v229
	v_mul_f32_e32 v7, v7, v229
	v_mul_f32_e32 v8, v8, v229
	v_mul_f32_e32 v9, v9, v229
	v_mul_f32_e32 v10, v10, v229
	v_mul_f32_e32 v11, v11, v229
	v_mul_f32_e32 v12, v12, v229
	v_mul_f32_e32 v13, v13, v229
	v_mul_f32_e32 v14, v14, v229
	v_mul_f32_e32 v15, v15, v229
	v_mul_f32_e32 v16, v16, v229
	v_mul_f32_e32 v17, v17, v229
	v_mul_f32_e32 v18, v18, v229
	v_mul_f32_e32 v19, v19, v229
	v_fma_f32 v4, v4, v188, v204
	v_fma_f32 v5, v5, v189, v205
	v_fma_f32 v6, v6, v190, v206
	v_fma_f32 v7, v7, v191, v207
	v_fma_f32 v8, v8, v192, v208
	v_fma_f32 v9, v9, v193, v209
	v_fma_f32 v10, v10, v194, v210
	v_fma_f32 v11, v11, v195, v211
	v_fma_f32 v12, v12, v196, v212
	v_fma_f32 v13, v13, v197, v213
	v_fma_f32 v14, v14, v198, v214
	v_fma_f32 v15, v15, v199, v215
	v_fma_f32 v16, v16, v200, v216
	v_fma_f32 v17, v17, v201, v217
	v_fma_f32 v18, v18, v202, v218
	v_fma_f32 v19, v19, v203, v219
	global_store_dwordx4 v0, v[4:7], s[98:99] nt
	global_store_dwordx4 v0, v[8:11], s[98:99] offset:1024 nt
	global_store_dwordx4 v0, v[12:15], s[98:99] offset:2048 nt
	global_store_dwordx4 v0, v[16:19], s[98:99] offset:3072 nt
	s_add_u32 s98, s98, 0x800000
	s_addc_u32 s99, s99, 0
	s_nop 0
	global_load_dwordx4 v[4:7], v0, s[56:57]
	global_load_dwordx4 v[8:11], v0, s[56:57] offset:1024
	global_load_dwordx4 v[12:15], v0, s[56:57] offset:2048
	global_load_dwordx4 v[16:19], v0, s[56:57] offset:3072
	s_add_u32 s56, s56, 0x800000
	s_addc_u32 s57, s57, 0
	s_waitcnt vmcnt(24)
	v_add_f32_e32 v220, v20, v21
	v_add_f32_e32 v221, v22, v23
	v_add_f32_e32 v222, v24, v25
	v_add_f32_e32 v223, v26, v27
	v_add_f32_e32 v224, v28, v29
	v_add_f32_e32 v225, v30, v31
	v_add_f32_e32 v226, v32, v33
	v_add_f32_e32 v227, v34, v35
	v_add_f32_e32 v220, v220, v221
	v_add_f32_e32 v222, v222, v223
	v_add_f32_e32 v224, v224, v225
	v_add_f32_e32 v226, v226, v227
	v_add_f32_e32 v220, v220, v222
	v_add_f32_e32 v224, v224, v226
	v_add_f32_e32 v220, v220, v224
	s_nop 1
	v_add_f32_dpp v220, v220, v220 quad_perm:[1,0,3,2] row_mask:0xf bank_mask:0xf
	s_nop 1
	v_add_f32_dpp v220, v220, v220 quad_perm:[2,3,0,1] row_mask:0xf bank_mask:0xf
	s_nop 1
	v_add_f32_dpp v220, v220, v220 row_half_mirror row_mask:0xf bank_mask:0xf
	s_nop 1
	v_add_f32_dpp v220, v220, v220 row_mirror row_mask:0xf bank_mask:0xf
	s_nop 1
	v_add_f32_dpp v220, v220, v220 row_bcast:15 row_mask:0xa bank_mask:0xf
	s_nop 1
	v_add_f32_dpp v220, v220, v220 row_bcast:31 row_mask:0xc bank_mask:0xf
	s_nop 1
	v_readlane_b32 s6, v220, 63
	s_nop 1
	v_mov_b32_e32 v228, s6
	v_mul_f32_e32 v228, 0x3a800000, v228
	v_sub_f32_e32 v20, v20, v228
	v_sub_f32_e32 v21, v21, v228
	v_sub_f32_e32 v22, v22, v228
	v_sub_f32_e32 v23, v23, v228
	v_sub_f32_e32 v24, v24, v228
	v_sub_f32_e32 v25, v25, v228
	v_sub_f32_e32 v26, v26, v228
	v_sub_f32_e32 v27, v27, v228
	v_sub_f32_e32 v28, v28, v228
	v_sub_f32_e32 v29, v29, v228
	v_sub_f32_e32 v30, v30, v228
	v_sub_f32_e32 v31, v31, v228
	v_sub_f32_e32 v32, v32, v228
	v_sub_f32_e32 v33, v33, v228
	v_sub_f32_e32 v34, v34, v228
	v_sub_f32_e32 v35, v35, v228
	v_mul_f32_e32 v222, v20, v20
	v_mul_f32_e32 v223, v21, v21
	v_fmac_f32_e32 v222, v22, v22
	v_fmac_f32_e32 v223, v23, v23
	v_fmac_f32_e32 v222, v24, v24
	v_fmac_f32_e32 v223, v25, v25
	v_fmac_f32_e32 v222, v26, v26
	v_fmac_f32_e32 v223, v27, v27
	v_fmac_f32_e32 v222, v28, v28
	v_fmac_f32_e32 v223, v29, v29
	v_fmac_f32_e32 v222, v30, v30
	v_fmac_f32_e32 v223, v31, v31
	v_fmac_f32_e32 v222, v32, v32
	v_fmac_f32_e32 v223, v33, v33
	v_fmac_f32_e32 v222, v34, v34
	v_fmac_f32_e32 v223, v35, v35
	v_add_f32_e32 v222, v222, v223
	s_nop 1
	v_add_f32_dpp v222, v222, v222 quad_perm:[1,0,3,2] row_mask:0xf bank_mask:0xf
	s_nop 1
	v_add_f32_dpp v222, v222, v222 quad_perm:[2,3,0,1] row_mask:0xf bank_mask:0xf
	s_nop 1
	v_add_f32_dpp v222, v222, v222 row_half_mirror row_mask:0xf bank_mask:0xf
	s_nop 1
	v_add_f32_dpp v222, v222, v222 row_mirror row_mask:0xf bank_mask:0xf
	s_nop 1
	v_add_f32_dpp v222, v222, v222 row_bcast:15 row_mask:0xa bank_mask:0xf
	s_nop 1
	v_add_f32_dpp v222, v222, v222 row_bcast:31 row_mask:0xc bank_mask:0xf
	s_nop 1
	v_readlane_b32 s6, v222, 63
	s_nop 1
	v_mov_b32_e32 v224, s6
	v_mov_b32_e32 v225, 0x3727c5ac
	v_fmac_f32_e32 v225, 0x3a800000, v224
	v_rsq_f32_e32 v229, v225
	s_nop 0
	v_mul_f32_e32 v20, v20, v229
	v_mul_f32_e32 v21, v21, v229
	v_mul_f32_e32 v22, v22, v229
	v_mul_f32_e32 v23, v23, v229
	v_mul_f32_e32 v24, v24, v229
	v_mul_f32_e32 v25, v25, v229
	v_mul_f32_e32 v26, v26, v229
	v_mul_f32_e32 v27, v27, v229
	v_mul_f32_e32 v28, v28, v229
	v_mul_f32_e32 v29, v29, v229
	v_mul_f32_e32 v30, v30, v229
	v_mul_f32_e32 v31, v31, v229
	v_mul_f32_e32 v32, v32, v229
	v_mul_f32_e32 v33, v33, v229
	v_mul_f32_e32 v34, v34, v229
	v_mul_f32_e32 v35, v35, v229
	v_fma_f32 v20, v20, v188, v204
	v_fma_f32 v21, v21, v189, v205
	v_fma_f32 v22, v22, v190, v206
	v_fma_f32 v23, v23, v191, v207
	v_fma_f32 v24, v24, v192, v208
	v_fma_f32 v25, v25, v193, v209
	v_fma_f32 v26, v26, v194, v210
	v_fma_f32 v27, v27, v195, v211
	v_fma_f32 v28, v28, v196, v212
	v_fma_f32 v29, v29, v197, v213
	v_fma_f32 v30, v30, v198, v214
	v_fma_f32 v31, v31, v199, v215
	v_fma_f32 v32, v32, v200, v216
	v_fma_f32 v33, v33, v201, v217
	v_fma_f32 v34, v34, v202, v218
	v_fma_f32 v35, v35, v203, v219
	global_store_dwordx4 v0, v[20:23], s[98:99] nt
	global_store_dwordx4 v0, v[24:27], s[98:99] offset:1024 nt
	global_store_dwordx4 v0, v[28:31], s[98:99] offset:2048 nt
	global_store_dwordx4 v0, v[32:35], s[98:99] offset:3072 nt
	s_add_u32 s98, s98, 0x800000
	s_addc_u32 s99, s99, 0
	s_nop 0
	global_load_dwordx4 v[20:23], v0, s[56:57]
	global_load_dwordx4 v[24:27], v0, s[56:57] offset:1024
	global_load_dwordx4 v[28:31], v0, s[56:57] offset:2048
	global_load_dwordx4 v[32:35], v0, s[56:57] offset:3072
	s_add_u32 s56, s56, 0x800000
	s_addc_u32 s57, s57, 0
	s_waitcnt vmcnt(24)
	v_add_f32_e32 v220, v36, v37
	v_add_f32_e32 v221, v38, v39
	v_add_f32_e32 v222, v40, v41
	v_add_f32_e32 v223, v42, v43
	v_add_f32_e32 v224, v44, v45
	v_add_f32_e32 v225, v46, v47
	v_add_f32_e32 v226, v48, v49
	v_add_f32_e32 v227, v50, v51
	v_add_f32_e32 v220, v220, v221
	v_add_f32_e32 v222, v222, v223
	v_add_f32_e32 v224, v224, v225
	v_add_f32_e32 v226, v226, v227
	v_add_f32_e32 v220, v220, v222
	v_add_f32_e32 v224, v224, v226
	v_add_f32_e32 v220, v220, v224
	s_nop 1
	v_add_f32_dpp v220, v220, v220 quad_perm:[1,0,3,2] row_mask:0xf bank_mask:0xf
	s_nop 1
	v_add_f32_dpp v220, v220, v220 quad_perm:[2,3,0,1] row_mask:0xf bank_mask:0xf
	s_nop 1
	v_add_f32_dpp v220, v220, v220 row_half_mirror row_mask:0xf bank_mask:0xf
	s_nop 1
	v_add_f32_dpp v220, v220, v220 row_mirror row_mask:0xf bank_mask:0xf
	s_nop 1
	v_add_f32_dpp v220, v220, v220 row_bcast:15 row_mask:0xa bank_mask:0xf
	s_nop 1
	v_add_f32_dpp v220, v220, v220 row_bcast:31 row_mask:0xc bank_mask:0xf
	s_nop 1
	v_readlane_b32 s6, v220, 63
	s_nop 1
	v_mov_b32_e32 v228, s6
	v_mul_f32_e32 v228, 0x3a800000, v228
	v_sub_f32_e32 v36, v36, v228
	v_sub_f32_e32 v37, v37, v228
	v_sub_f32_e32 v38, v38, v228
	v_sub_f32_e32 v39, v39, v228
	v_sub_f32_e32 v40, v40, v228
	v_sub_f32_e32 v41, v41, v228
	v_sub_f32_e32 v42, v42, v228
	v_sub_f32_e32 v43, v43, v228
	v_sub_f32_e32 v44, v44, v228
	v_sub_f32_e32 v45, v45, v228
	v_sub_f32_e32 v46, v46, v228
	v_sub_f32_e32 v47, v47, v228
	v_sub_f32_e32 v48, v48, v228
	v_sub_f32_e32 v49, v49, v228
	v_sub_f32_e32 v50, v50, v228
	v_sub_f32_e32 v51, v51, v228
	v_mul_f32_e32 v222, v36, v36
	v_mul_f32_e32 v223, v37, v37
	v_fmac_f32_e32 v222, v38, v38
	v_fmac_f32_e32 v223, v39, v39
	v_fmac_f32_e32 v222, v40, v40
	v_fmac_f32_e32 v223, v41, v41
	v_fmac_f32_e32 v222, v42, v42
	v_fmac_f32_e32 v223, v43, v43
	v_fmac_f32_e32 v222, v44, v44
	v_fmac_f32_e32 v223, v45, v45
	v_fmac_f32_e32 v222, v46, v46
	v_fmac_f32_e32 v223, v47, v47
	v_fmac_f32_e32 v222, v48, v48
	v_fmac_f32_e32 v223, v49, v49
	v_fmac_f32_e32 v222, v50, v50
	v_fmac_f32_e32 v223, v51, v51
	v_add_f32_e32 v222, v222, v223
	s_nop 1
	v_add_f32_dpp v222, v222, v222 quad_perm:[1,0,3,2] row_mask:0xf bank_mask:0xf
	s_nop 1
	v_add_f32_dpp v222, v222, v222 quad_perm:[2,3,0,1] row_mask:0xf bank_mask:0xf
	s_nop 1
	v_add_f32_dpp v222, v222, v222 row_half_mirror row_mask:0xf bank_mask:0xf
	s_nop 1
	v_add_f32_dpp v222, v222, v222 row_mirror row_mask:0xf bank_mask:0xf
	s_nop 1
	v_add_f32_dpp v222, v222, v222 row_bcast:15 row_mask:0xa bank_mask:0xf
	s_nop 1
	v_add_f32_dpp v222, v222, v222 row_bcast:31 row_mask:0xc bank_mask:0xf
	s_nop 1
	v_readlane_b32 s6, v222, 63
	s_nop 1
	v_mov_b32_e32 v224, s6
	v_mov_b32_e32 v225, 0x3727c5ac
	v_fmac_f32_e32 v225, 0x3a800000, v224
	v_rsq_f32_e32 v229, v225
	s_nop 0
	v_mul_f32_e32 v36, v36, v229
	v_mul_f32_e32 v37, v37, v229
	v_mul_f32_e32 v38, v38, v229
	v_mul_f32_e32 v39, v39, v229
	v_mul_f32_e32 v40, v40, v229
	v_mul_f32_e32 v41, v41, v229
	v_mul_f32_e32 v42, v42, v229
	v_mul_f32_e32 v43, v43, v229
	v_mul_f32_e32 v44, v44, v229
	v_mul_f32_e32 v45, v45, v229
	v_mul_f32_e32 v46, v46, v229
	v_mul_f32_e32 v47, v47, v229
	v_mul_f32_e32 v48, v48, v229
	v_mul_f32_e32 v49, v49, v229
	v_mul_f32_e32 v50, v50, v229
	v_mul_f32_e32 v51, v51, v229
	v_fma_f32 v36, v36, v188, v204
	v_fma_f32 v37, v37, v189, v205
	v_fma_f32 v38, v38, v190, v206
	v_fma_f32 v39, v39, v191, v207
	v_fma_f32 v40, v40, v192, v208
	v_fma_f32 v41, v41, v193, v209
	v_fma_f32 v42, v42, v194, v210
	v_fma_f32 v43, v43, v195, v211
	v_fma_f32 v44, v44, v196, v212
	v_fma_f32 v45, v45, v197, v213
	v_fma_f32 v46, v46, v198, v214
	v_fma_f32 v47, v47, v199, v215
	v_fma_f32 v48, v48, v200, v216
	v_fma_f32 v49, v49, v201, v217
	v_fma_f32 v50, v50, v202, v218
	v_fma_f32 v51, v51, v203, v219
	global_store_dwordx4 v0, v[36:39], s[98:99] nt
	global_store_dwordx4 v0, v[40:43], s[98:99] offset:1024 nt
	global_store_dwordx4 v0, v[44:47], s[98:99] offset:2048 nt
	global_store_dwordx4 v0, v[48:51], s[98:99] offset:3072 nt
	s_add_u32 s98, s98, 0x800000
	s_addc_u32 s99, s99, 0
	s_nop 0
	global_load_dwordx4 v[36:39], v0, s[56:57]
	global_load_dwordx4 v[40:43], v0, s[56:57] offset:1024
	global_load_dwordx4 v[44:47], v0, s[56:57] offset:2048
	global_load_dwordx4 v[48:51], v0, s[56:57] offset:3072
	s_add_u32 s56, s56, 0x800000
	s_addc_u32 s57, s57, 0
	s_waitcnt vmcnt(24)
	v_add_f32_e32 v220, v52, v53
	v_add_f32_e32 v221, v54, v55
	v_add_f32_e32 v222, v56, v57
	v_add_f32_e32 v223, v58, v59
	v_add_f32_e32 v224, v60, v61
	v_add_f32_e32 v225, v62, v63
	v_add_f32_e32 v226, v64, v65
	v_add_f32_e32 v227, v66, v67
	v_add_f32_e32 v220, v220, v221
	v_add_f32_e32 v222, v222, v223
	v_add_f32_e32 v224, v224, v225
	v_add_f32_e32 v226, v226, v227
	v_add_f32_e32 v220, v220, v222
	v_add_f32_e32 v224, v224, v226
	v_add_f32_e32 v220, v220, v224
	s_nop 1
	v_add_f32_dpp v220, v220, v220 quad_perm:[1,0,3,2] row_mask:0xf bank_mask:0xf
	s_nop 1
	v_add_f32_dpp v220, v220, v220 quad_perm:[2,3,0,1] row_mask:0xf bank_mask:0xf
	s_nop 1
	v_add_f32_dpp v220, v220, v220 row_half_mirror row_mask:0xf bank_mask:0xf
	s_nop 1
	v_add_f32_dpp v220, v220, v220 row_mirror row_mask:0xf bank_mask:0xf
	s_nop 1
	v_add_f32_dpp v220, v220, v220 row_bcast:15 row_mask:0xa bank_mask:0xf
	s_nop 1
	v_add_f32_dpp v220, v220, v220 row_bcast:31 row_mask:0xc bank_mask:0xf
	s_nop 1
	v_readlane_b32 s6, v220, 63
	s_nop 1
	v_mov_b32_e32 v228, s6
	v_mul_f32_e32 v228, 0x3a800000, v228
	v_sub_f32_e32 v52, v52, v228
	v_sub_f32_e32 v53, v53, v228
	v_sub_f32_e32 v54, v54, v228
	v_sub_f32_e32 v55, v55, v228
	v_sub_f32_e32 v56, v56, v228
	v_sub_f32_e32 v57, v57, v228
	v_sub_f32_e32 v58, v58, v228
	v_sub_f32_e32 v59, v59, v228
	v_sub_f32_e32 v60, v60, v228
	v_sub_f32_e32 v61, v61, v228
	v_sub_f32_e32 v62, v62, v228
	v_sub_f32_e32 v63, v63, v228
	v_sub_f32_e32 v64, v64, v228
	v_sub_f32_e32 v65, v65, v228
	v_sub_f32_e32 v66, v66, v228
	v_sub_f32_e32 v67, v67, v228
	v_mul_f32_e32 v222, v52, v52
	v_mul_f32_e32 v223, v53, v53
	v_fmac_f32_e32 v222, v54, v54
	v_fmac_f32_e32 v223, v55, v55
	v_fmac_f32_e32 v222, v56, v56
	v_fmac_f32_e32 v223, v57, v57
	v_fmac_f32_e32 v222, v58, v58
	v_fmac_f32_e32 v223, v59, v59
	v_fmac_f32_e32 v222, v60, v60
	v_fmac_f32_e32 v223, v61, v61
	v_fmac_f32_e32 v222, v62, v62
	v_fmac_f32_e32 v223, v63, v63
	v_fmac_f32_e32 v222, v64, v64
	v_fmac_f32_e32 v223, v65, v65
	v_fmac_f32_e32 v222, v66, v66
	v_fmac_f32_e32 v223, v67, v67
	v_add_f32_e32 v222, v222, v223
	s_nop 1
	v_add_f32_dpp v222, v222, v222 quad_perm:[1,0,3,2] row_mask:0xf bank_mask:0xf
	s_nop 1
	v_add_f32_dpp v222, v222, v222 quad_perm:[2,3,0,1] row_mask:0xf bank_mask:0xf
	s_nop 1
	v_add_f32_dpp v222, v222, v222 row_half_mirror row_mask:0xf bank_mask:0xf
	s_nop 1
	v_add_f32_dpp v222, v222, v222 row_mirror row_mask:0xf bank_mask:0xf
	s_nop 1
	v_add_f32_dpp v222, v222, v222 row_bcast:15 row_mask:0xa bank_mask:0xf
	s_nop 1
	v_add_f32_dpp v222, v222, v222 row_bcast:31 row_mask:0xc bank_mask:0xf
	s_nop 1
	v_readlane_b32 s6, v222, 63
	s_nop 1
	v_mov_b32_e32 v224, s6
	v_mov_b32_e32 v225, 0x3727c5ac
	v_fmac_f32_e32 v225, 0x3a800000, v224
	v_rsq_f32_e32 v229, v225
	s_nop 0
	v_mul_f32_e32 v52, v52, v229
	v_mul_f32_e32 v53, v53, v229
	v_mul_f32_e32 v54, v54, v229
	v_mul_f32_e32 v55, v55, v229
	v_mul_f32_e32 v56, v56, v229
	v_mul_f32_e32 v57, v57, v229
	v_mul_f32_e32 v58, v58, v229
	v_mul_f32_e32 v59, v59, v229
	v_mul_f32_e32 v60, v60, v229
	v_mul_f32_e32 v61, v61, v229
	v_mul_f32_e32 v62, v62, v229
	v_mul_f32_e32 v63, v63, v229
	v_mul_f32_e32 v64, v64, v229
	v_mul_f32_e32 v65, v65, v229
	v_mul_f32_e32 v66, v66, v229
	v_mul_f32_e32 v67, v67, v229
	v_fma_f32 v52, v52, v188, v204
	v_fma_f32 v53, v53, v189, v205
	v_fma_f32 v54, v54, v190, v206
	v_fma_f32 v55, v55, v191, v207
	v_fma_f32 v56, v56, v192, v208
	v_fma_f32 v57, v57, v193, v209
	v_fma_f32 v58, v58, v194, v210
	v_fma_f32 v59, v59, v195, v211
	v_fma_f32 v60, v60, v196, v212
	v_fma_f32 v61, v61, v197, v213
	v_fma_f32 v62, v62, v198, v214
	v_fma_f32 v63, v63, v199, v215
	v_fma_f32 v64, v64, v200, v216
	v_fma_f32 v65, v65, v201, v217
	v_fma_f32 v66, v66, v202, v218
	v_fma_f32 v67, v67, v203, v219
	global_store_dwordx4 v0, v[52:55], s[98:99] nt
	global_store_dwordx4 v0, v[56:59], s[98:99] offset:1024 nt
	global_store_dwordx4 v0, v[60:63], s[98:99] offset:2048 nt
	global_store_dwordx4 v0, v[64:67], s[98:99] offset:3072 nt
	s_add_u32 s98, s98, 0x800000
	s_addc_u32 s99, s99, 0
	s_nop 0
	global_load_dwordx4 v[52:55], v0, s[56:57]
	global_load_dwordx4 v[56:59], v0, s[56:57] offset:1024
	global_load_dwordx4 v[60:63], v0, s[56:57] offset:2048
	global_load_dwordx4 v[64:67], v0, s[56:57] offset:3072
	s_add_u32 s56, s56, 0x800000
	s_addc_u32 s57, s57, 0
	s_waitcnt vmcnt(24)
	v_add_f32_e32 v220, v4, v5
	v_add_f32_e32 v221, v6, v7
	v_add_f32_e32 v222, v8, v9
	v_add_f32_e32 v223, v10, v11
	v_add_f32_e32 v224, v12, v13
	v_add_f32_e32 v225, v14, v15
	v_add_f32_e32 v226, v16, v17
	v_add_f32_e32 v227, v18, v19
	v_add_f32_e32 v220, v220, v221
	v_add_f32_e32 v222, v222, v223
	v_add_f32_e32 v224, v224, v225
	v_add_f32_e32 v226, v226, v227
	v_add_f32_e32 v220, v220, v222
	v_add_f32_e32 v224, v224, v226
	v_add_f32_e32 v220, v220, v224
	s_nop 1
	v_add_f32_dpp v220, v220, v220 quad_perm:[1,0,3,2] row_mask:0xf bank_mask:0xf
	s_nop 1
	v_add_f32_dpp v220, v220, v220 quad_perm:[2,3,0,1] row_mask:0xf bank_mask:0xf
	s_nop 1
	v_add_f32_dpp v220, v220, v220 row_half_mirror row_mask:0xf bank_mask:0xf
	s_nop 1
	v_add_f32_dpp v220, v220, v220 row_mirror row_mask:0xf bank_mask:0xf
	s_nop 1
	v_add_f32_dpp v220, v220, v220 row_bcast:15 row_mask:0xa bank_mask:0xf
	s_nop 1
	v_add_f32_dpp v220, v220, v220 row_bcast:31 row_mask:0xc bank_mask:0xf
	s_nop 1
	v_readlane_b32 s6, v220, 63
	s_nop 1
	v_mov_b32_e32 v228, s6
	v_mul_f32_e32 v228, 0x3a800000, v228
	v_sub_f32_e32 v4, v4, v228
	v_sub_f32_e32 v5, v5, v228
	v_sub_f32_e32 v6, v6, v228
	v_sub_f32_e32 v7, v7, v228
	v_sub_f32_e32 v8, v8, v228
	v_sub_f32_e32 v9, v9, v228
	v_sub_f32_e32 v10, v10, v228
	v_sub_f32_e32 v11, v11, v228
	v_sub_f32_e32 v12, v12, v228
	v_sub_f32_e32 v13, v13, v228
	v_sub_f32_e32 v14, v14, v228
	v_sub_f32_e32 v15, v15, v228
	v_sub_f32_e32 v16, v16, v228
	v_sub_f32_e32 v17, v17, v228
	v_sub_f32_e32 v18, v18, v228
	v_sub_f32_e32 v19, v19, v228
	v_mul_f32_e32 v222, v4, v4
	v_mul_f32_e32 v223, v5, v5
	v_fmac_f32_e32 v222, v6, v6
	v_fmac_f32_e32 v223, v7, v7
	v_fmac_f32_e32 v222, v8, v8
	v_fmac_f32_e32 v223, v9, v9
	v_fmac_f32_e32 v222, v10, v10
	v_fmac_f32_e32 v223, v11, v11
	v_fmac_f32_e32 v222, v12, v12
	v_fmac_f32_e32 v223, v13, v13
	v_fmac_f32_e32 v222, v14, v14
	v_fmac_f32_e32 v223, v15, v15
	v_fmac_f32_e32 v222, v16, v16
	v_fmac_f32_e32 v223, v17, v17
	v_fmac_f32_e32 v222, v18, v18
	v_fmac_f32_e32 v223, v19, v19
	v_add_f32_e32 v222, v222, v223
	s_nop 1
	v_add_f32_dpp v222, v222, v222 quad_perm:[1,0,3,2] row_mask:0xf bank_mask:0xf
	s_nop 1
	v_add_f32_dpp v222, v222, v222 quad_perm:[2,3,0,1] row_mask:0xf bank_mask:0xf
	s_nop 1
	v_add_f32_dpp v222, v222, v222 row_half_mirror row_mask:0xf bank_mask:0xf
	s_nop 1
	v_add_f32_dpp v222, v222, v222 row_mirror row_mask:0xf bank_mask:0xf
	s_nop 1
	v_add_f32_dpp v222, v222, v222 row_bcast:15 row_mask:0xa bank_mask:0xf
	s_nop 1
	v_add_f32_dpp v222, v222, v222 row_bcast:31 row_mask:0xc bank_mask:0xf
	s_nop 1
	v_readlane_b32 s6, v222, 63
	s_nop 1
	v_mov_b32_e32 v224, s6
	v_mov_b32_e32 v225, 0x3727c5ac
	v_fmac_f32_e32 v225, 0x3a800000, v224
	v_rsq_f32_e32 v229, v225
	s_nop 0
	v_mul_f32_e32 v4, v4, v229
	v_mul_f32_e32 v5, v5, v229
	v_mul_f32_e32 v6, v6, v229
	v_mul_f32_e32 v7, v7, v229
	v_mul_f32_e32 v8, v8, v229
	v_mul_f32_e32 v9, v9, v229
	v_mul_f32_e32 v10, v10, v229
	v_mul_f32_e32 v11, v11, v229
	v_mul_f32_e32 v12, v12, v229
	v_mul_f32_e32 v13, v13, v229
	v_mul_f32_e32 v14, v14, v229
	v_mul_f32_e32 v15, v15, v229
	v_mul_f32_e32 v16, v16, v229
	v_mul_f32_e32 v17, v17, v229
	v_mul_f32_e32 v18, v18, v229
	v_mul_f32_e32 v19, v19, v229
	v_fma_f32 v4, v4, v188, v204
	v_fma_f32 v5, v5, v189, v205
	v_fma_f32 v6, v6, v190, v206
	v_fma_f32 v7, v7, v191, v207
	v_fma_f32 v8, v8, v192, v208
	v_fma_f32 v9, v9, v193, v209
	v_fma_f32 v10, v10, v194, v210
	v_fma_f32 v11, v11, v195, v211
	v_fma_f32 v12, v12, v196, v212
	v_fma_f32 v13, v13, v197, v213
	v_fma_f32 v14, v14, v198, v214
	v_fma_f32 v15, v15, v199, v215
	v_fma_f32 v16, v16, v200, v216
	v_fma_f32 v17, v17, v201, v217
	v_fma_f32 v18, v18, v202, v218
	v_fma_f32 v19, v19, v203, v219
	global_store_dwordx4 v0, v[4:7], s[98:99] nt
	global_store_dwordx4 v0, v[8:11], s[98:99] offset:1024 nt
	global_store_dwordx4 v0, v[12:15], s[98:99] offset:2048 nt
	global_store_dwordx4 v0, v[16:19], s[98:99] offset:3072 nt
	s_add_u32 s98, s98, 0x800000
	s_addc_u32 s99, s99, 0
	s_waitcnt vmcnt(20)
	v_add_f32_e32 v220, v20, v21
	v_add_f32_e32 v221, v22, v23
	v_add_f32_e32 v222, v24, v25
	v_add_f32_e32 v223, v26, v27
	v_add_f32_e32 v224, v28, v29
	v_add_f32_e32 v225, v30, v31
	v_add_f32_e32 v226, v32, v33
	v_add_f32_e32 v227, v34, v35
	v_add_f32_e32 v220, v220, v221
	v_add_f32_e32 v222, v222, v223
	v_add_f32_e32 v224, v224, v225
	v_add_f32_e32 v226, v226, v227
	v_add_f32_e32 v220, v220, v222
	v_add_f32_e32 v224, v224, v226
	v_add_f32_e32 v220, v220, v224
	s_nop 1
	v_add_f32_dpp v220, v220, v220 quad_perm:[1,0,3,2] row_mask:0xf bank_mask:0xf
	s_nop 1
	v_add_f32_dpp v220, v220, v220 quad_perm:[2,3,0,1] row_mask:0xf bank_mask:0xf
	s_nop 1
	v_add_f32_dpp v220, v220, v220 row_half_mirror row_mask:0xf bank_mask:0xf
	s_nop 1
	v_add_f32_dpp v220, v220, v220 row_mirror row_mask:0xf bank_mask:0xf
	s_nop 1
	v_add_f32_dpp v220, v220, v220 row_bcast:15 row_mask:0xa bank_mask:0xf
	s_nop 1
	v_add_f32_dpp v220, v220, v220 row_bcast:31 row_mask:0xc bank_mask:0xf
	s_nop 1
	v_readlane_b32 s6, v220, 63
	s_nop 1
	v_mov_b32_e32 v228, s6
	v_mul_f32_e32 v228, 0x3a800000, v228
	v_sub_f32_e32 v20, v20, v228
	v_sub_f32_e32 v21, v21, v228
	v_sub_f32_e32 v22, v22, v228
	v_sub_f32_e32 v23, v23, v228
	v_sub_f32_e32 v24, v24, v228
	v_sub_f32_e32 v25, v25, v228
	v_sub_f32_e32 v26, v26, v228
	v_sub_f32_e32 v27, v27, v228
	v_sub_f32_e32 v28, v28, v228
	v_sub_f32_e32 v29, v29, v228
	v_sub_f32_e32 v30, v30, v228
	v_sub_f32_e32 v31, v31, v228
	v_sub_f32_e32 v32, v32, v228
	v_sub_f32_e32 v33, v33, v228
	v_sub_f32_e32 v34, v34, v228
	v_sub_f32_e32 v35, v35, v228
	v_mul_f32_e32 v222, v20, v20
	v_mul_f32_e32 v223, v21, v21
	v_fmac_f32_e32 v222, v22, v22
	v_fmac_f32_e32 v223, v23, v23
	v_fmac_f32_e32 v222, v24, v24
	v_fmac_f32_e32 v223, v25, v25
	v_fmac_f32_e32 v222, v26, v26
	v_fmac_f32_e32 v223, v27, v27
	v_fmac_f32_e32 v222, v28, v28
	v_fmac_f32_e32 v223, v29, v29
	v_fmac_f32_e32 v222, v30, v30
	v_fmac_f32_e32 v223, v31, v31
	v_fmac_f32_e32 v222, v32, v32
	v_fmac_f32_e32 v223, v33, v33
	v_fmac_f32_e32 v222, v34, v34
	v_fmac_f32_e32 v223, v35, v35
	v_add_f32_e32 v222, v222, v223
	s_nop 1
	v_add_f32_dpp v222, v222, v222 quad_perm:[1,0,3,2] row_mask:0xf bank_mask:0xf
	s_nop 1
	v_add_f32_dpp v222, v222, v222 quad_perm:[2,3,0,1] row_mask:0xf bank_mask:0xf
	s_nop 1
	v_add_f32_dpp v222, v222, v222 row_half_mirror row_mask:0xf bank_mask:0xf
	s_nop 1
	v_add_f32_dpp v222, v222, v222 row_mirror row_mask:0xf bank_mask:0xf
	s_nop 1
	v_add_f32_dpp v222, v222, v222 row_bcast:15 row_mask:0xa bank_mask:0xf
	s_nop 1
	v_add_f32_dpp v222, v222, v222 row_bcast:31 row_mask:0xc bank_mask:0xf
	s_nop 1
	v_readlane_b32 s6, v222, 63
	s_nop 1
	v_mov_b32_e32 v224, s6
	v_mov_b32_e32 v225, 0x3727c5ac
	v_fmac_f32_e32 v225, 0x3a800000, v224
	v_rsq_f32_e32 v229, v225
	s_nop 0
	v_mul_f32_e32 v20, v20, v229
	v_mul_f32_e32 v21, v21, v229
	v_mul_f32_e32 v22, v22, v229
	v_mul_f32_e32 v23, v23, v229
	v_mul_f32_e32 v24, v24, v229
	v_mul_f32_e32 v25, v25, v229
	v_mul_f32_e32 v26, v26, v229
	v_mul_f32_e32 v27, v27, v229
	v_mul_f32_e32 v28, v28, v229
	v_mul_f32_e32 v29, v29, v229
	v_mul_f32_e32 v30, v30, v229
	v_mul_f32_e32 v31, v31, v229
	v_mul_f32_e32 v32, v32, v229
	v_mul_f32_e32 v33, v33, v229
	v_mul_f32_e32 v34, v34, v229
	v_mul_f32_e32 v35, v35, v229
	v_fma_f32 v20, v20, v188, v204
	v_fma_f32 v21, v21, v189, v205
	v_fma_f32 v22, v22, v190, v206
	v_fma_f32 v23, v23, v191, v207
	v_fma_f32 v24, v24, v192, v208
	v_fma_f32 v25, v25, v193, v209
	v_fma_f32 v26, v26, v194, v210
	v_fma_f32 v27, v27, v195, v211
	v_fma_f32 v28, v28, v196, v212
	v_fma_f32 v29, v29, v197, v213
	v_fma_f32 v30, v30, v198, v214
	v_fma_f32 v31, v31, v199, v215
	v_fma_f32 v32, v32, v200, v216
	v_fma_f32 v33, v33, v201, v217
	v_fma_f32 v34, v34, v202, v218
	v_fma_f32 v35, v35, v203, v219
	global_store_dwordx4 v0, v[20:23], s[98:99] nt
	global_store_dwordx4 v0, v[24:27], s[98:99] offset:1024 nt
	global_store_dwordx4 v0, v[28:31], s[98:99] offset:2048 nt
	global_store_dwordx4 v0, v[32:35], s[98:99] offset:3072 nt
	s_add_u32 s98, s98, 0x800000
	s_addc_u32 s99, s99, 0
	s_waitcnt vmcnt(16)
	v_add_f32_e32 v220, v36, v37
	v_add_f32_e32 v221, v38, v39
	v_add_f32_e32 v222, v40, v41
	v_add_f32_e32 v223, v42, v43
	v_add_f32_e32 v224, v44, v45
	v_add_f32_e32 v225, v46, v47
	v_add_f32_e32 v226, v48, v49
	v_add_f32_e32 v227, v50, v51
	v_add_f32_e32 v220, v220, v221
	v_add_f32_e32 v222, v222, v223
	v_add_f32_e32 v224, v224, v225
	v_add_f32_e32 v226, v226, v227
	v_add_f32_e32 v220, v220, v222
	v_add_f32_e32 v224, v224, v226
	v_add_f32_e32 v220, v220, v224
	s_nop 1
	v_add_f32_dpp v220, v220, v220 quad_perm:[1,0,3,2] row_mask:0xf bank_mask:0xf
	s_nop 1
	v_add_f32_dpp v220, v220, v220 quad_perm:[2,3,0,1] row_mask:0xf bank_mask:0xf
	s_nop 1
	v_add_f32_dpp v220, v220, v220 row_half_mirror row_mask:0xf bank_mask:0xf
	s_nop 1
	v_add_f32_dpp v220, v220, v220 row_mirror row_mask:0xf bank_mask:0xf
	s_nop 1
	v_add_f32_dpp v220, v220, v220 row_bcast:15 row_mask:0xa bank_mask:0xf
	s_nop 1
	v_add_f32_dpp v220, v220, v220 row_bcast:31 row_mask:0xc bank_mask:0xf
	s_nop 1
	v_readlane_b32 s6, v220, 63
	s_nop 1
	v_mov_b32_e32 v228, s6
	v_mul_f32_e32 v228, 0x3a800000, v228
	v_sub_f32_e32 v36, v36, v228
	v_sub_f32_e32 v37, v37, v228
	v_sub_f32_e32 v38, v38, v228
	v_sub_f32_e32 v39, v39, v228
	v_sub_f32_e32 v40, v40, v228
	v_sub_f32_e32 v41, v41, v228
	v_sub_f32_e32 v42, v42, v228
	v_sub_f32_e32 v43, v43, v228
	v_sub_f32_e32 v44, v44, v228
	v_sub_f32_e32 v45, v45, v228
	v_sub_f32_e32 v46, v46, v228
	v_sub_f32_e32 v47, v47, v228
	v_sub_f32_e32 v48, v48, v228
	v_sub_f32_e32 v49, v49, v228
	v_sub_f32_e32 v50, v50, v228
	v_sub_f32_e32 v51, v51, v228
	v_mul_f32_e32 v222, v36, v36
	v_mul_f32_e32 v223, v37, v37
	v_fmac_f32_e32 v222, v38, v38
	v_fmac_f32_e32 v223, v39, v39
	v_fmac_f32_e32 v222, v40, v40
	v_fmac_f32_e32 v223, v41, v41
	v_fmac_f32_e32 v222, v42, v42
	v_fmac_f32_e32 v223, v43, v43
	v_fmac_f32_e32 v222, v44, v44
	v_fmac_f32_e32 v223, v45, v45
	v_fmac_f32_e32 v222, v46, v46
	v_fmac_f32_e32 v223, v47, v47
	v_fmac_f32_e32 v222, v48, v48
	v_fmac_f32_e32 v223, v49, v49
	v_fmac_f32_e32 v222, v50, v50
	v_fmac_f32_e32 v223, v51, v51
	v_add_f32_e32 v222, v222, v223
	s_nop 1
	v_add_f32_dpp v222, v222, v222 quad_perm:[1,0,3,2] row_mask:0xf bank_mask:0xf
	s_nop 1
	v_add_f32_dpp v222, v222, v222 quad_perm:[2,3,0,1] row_mask:0xf bank_mask:0xf
	s_nop 1
	v_add_f32_dpp v222, v222, v222 row_half_mirror row_mask:0xf bank_mask:0xf
	s_nop 1
	v_add_f32_dpp v222, v222, v222 row_mirror row_mask:0xf bank_mask:0xf
	s_nop 1
	v_add_f32_dpp v222, v222, v222 row_bcast:15 row_mask:0xa bank_mask:0xf
	s_nop 1
	v_add_f32_dpp v222, v222, v222 row_bcast:31 row_mask:0xc bank_mask:0xf
	s_nop 1
	v_readlane_b32 s6, v222, 63
	s_nop 1
	v_mov_b32_e32 v224, s6
	v_mov_b32_e32 v225, 0x3727c5ac
	v_fmac_f32_e32 v225, 0x3a800000, v224
	v_rsq_f32_e32 v229, v225
	s_nop 0
	v_mul_f32_e32 v36, v36, v229
	v_mul_f32_e32 v37, v37, v229
	v_mul_f32_e32 v38, v38, v229
	v_mul_f32_e32 v39, v39, v229
	v_mul_f32_e32 v40, v40, v229
	v_mul_f32_e32 v41, v41, v229
	v_mul_f32_e32 v42, v42, v229
	v_mul_f32_e32 v43, v43, v229
	v_mul_f32_e32 v44, v44, v229
	v_mul_f32_e32 v45, v45, v229
	v_mul_f32_e32 v46, v46, v229
	v_mul_f32_e32 v47, v47, v229
	v_mul_f32_e32 v48, v48, v229
	v_mul_f32_e32 v49, v49, v229
	v_mul_f32_e32 v50, v50, v229
	v_mul_f32_e32 v51, v51, v229
	v_fma_f32 v36, v36, v188, v204
	v_fma_f32 v37, v37, v189, v205
	v_fma_f32 v38, v38, v190, v206
	v_fma_f32 v39, v39, v191, v207
	v_fma_f32 v40, v40, v192, v208
	v_fma_f32 v41, v41, v193, v209
	v_fma_f32 v42, v42, v194, v210
	v_fma_f32 v43, v43, v195, v211
	v_fma_f32 v44, v44, v196, v212
	v_fma_f32 v45, v45, v197, v213
	v_fma_f32 v46, v46, v198, v214
	v_fma_f32 v47, v47, v199, v215
	v_fma_f32 v48, v48, v200, v216
	v_fma_f32 v49, v49, v201, v217
	v_fma_f32 v50, v50, v202, v218
	v_fma_f32 v51, v51, v203, v219
	global_store_dwordx4 v0, v[36:39], s[98:99] nt
	global_store_dwordx4 v0, v[40:43], s[98:99] offset:1024 nt
	global_store_dwordx4 v0, v[44:47], s[98:99] offset:2048 nt
	global_store_dwordx4 v0, v[48:51], s[98:99] offset:3072 nt
	s_add_u32 s98, s98, 0x800000
	s_addc_u32 s99, s99, 0
	s_waitcnt vmcnt(12)
	v_add_f32_e32 v220, v52, v53
	v_add_f32_e32 v221, v54, v55
	v_add_f32_e32 v222, v56, v57
	v_add_f32_e32 v223, v58, v59
	v_add_f32_e32 v224, v60, v61
	v_add_f32_e32 v225, v62, v63
	v_add_f32_e32 v226, v64, v65
	v_add_f32_e32 v227, v66, v67
	v_add_f32_e32 v220, v220, v221
	v_add_f32_e32 v222, v222, v223
	v_add_f32_e32 v224, v224, v225
	v_add_f32_e32 v226, v226, v227
	v_add_f32_e32 v220, v220, v222
	v_add_f32_e32 v224, v224, v226
	v_add_f32_e32 v220, v220, v224
	s_nop 1
	v_add_f32_dpp v220, v220, v220 quad_perm:[1,0,3,2] row_mask:0xf bank_mask:0xf
	s_nop 1
	v_add_f32_dpp v220, v220, v220 quad_perm:[2,3,0,1] row_mask:0xf bank_mask:0xf
	s_nop 1
	v_add_f32_dpp v220, v220, v220 row_half_mirror row_mask:0xf bank_mask:0xf
	s_nop 1
	v_add_f32_dpp v220, v220, v220 row_mirror row_mask:0xf bank_mask:0xf
	s_nop 1
	v_add_f32_dpp v220, v220, v220 row_bcast:15 row_mask:0xa bank_mask:0xf
	s_nop 1
	v_add_f32_dpp v220, v220, v220 row_bcast:31 row_mask:0xc bank_mask:0xf
	s_nop 1
	v_readlane_b32 s6, v220, 63
	s_nop 1
	v_mov_b32_e32 v228, s6
	v_mul_f32_e32 v228, 0x3a800000, v228
	v_sub_f32_e32 v52, v52, v228
	v_sub_f32_e32 v53, v53, v228
	v_sub_f32_e32 v54, v54, v228
	v_sub_f32_e32 v55, v55, v228
	v_sub_f32_e32 v56, v56, v228
	v_sub_f32_e32 v57, v57, v228
	v_sub_f32_e32 v58, v58, v228
	v_sub_f32_e32 v59, v59, v228
	v_sub_f32_e32 v60, v60, v228
	v_sub_f32_e32 v61, v61, v228
	v_sub_f32_e32 v62, v62, v228
	v_sub_f32_e32 v63, v63, v228
	v_sub_f32_e32 v64, v64, v228
	v_sub_f32_e32 v65, v65, v228
	v_sub_f32_e32 v66, v66, v228
	v_sub_f32_e32 v67, v67, v228
	v_mul_f32_e32 v222, v52, v52
	v_mul_f32_e32 v223, v53, v53
	v_fmac_f32_e32 v222, v54, v54
	v_fmac_f32_e32 v223, v55, v55
	v_fmac_f32_e32 v222, v56, v56
	v_fmac_f32_e32 v223, v57, v57
	v_fmac_f32_e32 v222, v58, v58
	v_fmac_f32_e32 v223, v59, v59
	v_fmac_f32_e32 v222, v60, v60
	v_fmac_f32_e32 v223, v61, v61
	v_fmac_f32_e32 v222, v62, v62
	v_fmac_f32_e32 v223, v63, v63
	v_fmac_f32_e32 v222, v64, v64
	v_fmac_f32_e32 v223, v65, v65
	v_fmac_f32_e32 v222, v66, v66
	v_fmac_f32_e32 v223, v67, v67
	v_add_f32_e32 v222, v222, v223
	s_nop 1
	v_add_f32_dpp v222, v222, v222 quad_perm:[1,0,3,2] row_mask:0xf bank_mask:0xf
	s_nop 1
	v_add_f32_dpp v222, v222, v222 quad_perm:[2,3,0,1] row_mask:0xf bank_mask:0xf
	s_nop 1
	v_add_f32_dpp v222, v222, v222 row_half_mirror row_mask:0xf bank_mask:0xf
	s_nop 1
	v_add_f32_dpp v222, v222, v222 row_mirror row_mask:0xf bank_mask:0xf
	s_nop 1
	v_add_f32_dpp v222, v222, v222 row_bcast:15 row_mask:0xa bank_mask:0xf
	s_nop 1
	v_add_f32_dpp v222, v222, v222 row_bcast:31 row_mask:0xc bank_mask:0xf
	s_nop 1
	v_readlane_b32 s6, v222, 63
	s_nop 1
	v_mov_b32_e32 v224, s6
	v_mov_b32_e32 v225, 0x3727c5ac
	v_fmac_f32_e32 v225, 0x3a800000, v224
	v_rsq_f32_e32 v229, v225
	s_nop 0
	v_mul_f32_e32 v52, v52, v229
	v_mul_f32_e32 v53, v53, v229
	v_mul_f32_e32 v54, v54, v229
	v_mul_f32_e32 v55, v55, v229
	v_mul_f32_e32 v56, v56, v229
	v_mul_f32_e32 v57, v57, v229
	v_mul_f32_e32 v58, v58, v229
	v_mul_f32_e32 v59, v59, v229
	v_mul_f32_e32 v60, v60, v229
	v_mul_f32_e32 v61, v61, v229
	v_mul_f32_e32 v62, v62, v229
	v_mul_f32_e32 v63, v63, v229
	v_mul_f32_e32 v64, v64, v229
	v_mul_f32_e32 v65, v65, v229
	v_mul_f32_e32 v66, v66, v229
	v_mul_f32_e32 v67, v67, v229
	v_fma_f32 v52, v52, v188, v204
	v_fma_f32 v53, v53, v189, v205
	v_fma_f32 v54, v54, v190, v206
	v_fma_f32 v55, v55, v191, v207
	v_fma_f32 v56, v56, v192, v208
	v_fma_f32 v57, v57, v193, v209
	v_fma_f32 v58, v58, v194, v210
	v_fma_f32 v59, v59, v195, v211
	v_fma_f32 v60, v60, v196, v212
	v_fma_f32 v61, v61, v197, v213
	v_fma_f32 v62, v62, v198, v214
	v_fma_f32 v63, v63, v199, v215
	v_fma_f32 v64, v64, v200, v216
	v_fma_f32 v65, v65, v201, v217
	v_fma_f32 v66, v66, v202, v218
	v_fma_f32 v67, v67, v203, v219
	global_store_dwordx4 v0, v[52:55], s[98:99] nt
	global_store_dwordx4 v0, v[56:59], s[98:99] offset:1024 nt
	global_store_dwordx4 v0, v[60:63], s[98:99] offset:2048 nt
	global_store_dwordx4 v0, v[64:67], s[98:99] offset:3072 nt
	s_add_u32 s98, s98, 0x800000
	s_addc_u32 s99, s99, 0
	s_endpgm
.Lln11_orig:
	s_mov_b32 s3, 0x8000
	v_ashrrev_i32_e32 v90, 6, v254
	v_and_b32_e32 v2, 63, v254
	v_add_u32_e32 v0, s33, v90
	v_cmp_gt_i32_e32 vcc, s3, v0
	v_ashrrev_i32_e32 v1, 31, v0
	v_lshlrev_b32_e32 v64, 4, v2
	s_and_saveexec_b64 s[0:1], vcc
	s_cbranch_execz .LBB0_1024
	v_lshlrev_b64 v[2:3], 12, v[0:1]
	v_lshl_add_u64 v[2:3], s[26:27], 0, v[2:3]
	v_mov_b32_e32 v65, 0
	v_lshl_add_u64 v[2:3], v[2:3], 0, v[64:65]
	global_load_dwordx4 v[60:63], v[2:3], off
	global_load_dwordx4 v[56:59], v[2:3], off offset:1024
	global_load_dwordx4 v[52:55], v[2:3], off offset:2048
	global_load_dwordx4 v[48:51], v[2:3], off offset:3072

	.amdhsa_kernel _Z14fwd_megakernel6Params
		.amdhsa_group_segment_fixed_size 0
		.amdhsa_private_segment_fixed_size 0
		.amdhsa_kernarg_size 456
		.amdhsa_user_sgpr_count 2
		.amdhsa_user_sgpr_dispatch_ptr 0
		.amdhsa_user_sgpr_queue_ptr 0
		.amdhsa_user_sgpr_kernarg_segment_ptr 1
		.amdhsa_user_sgpr_dispatch_id 0
		.amdhsa_user_sgpr_kernarg_preload_length 0
		.amdhsa_user_sgpr_kernarg_preload_offset 0
		.amdhsa_user_sgpr_private_segment_size 0
		.amdhsa_uses_dynamic_stack 0
		.amdhsa_enable_private_segment 0
		.amdhsa_system_sgpr_workgroup_id_x 1
		.amdhsa_system_sgpr_workgroup_id_y 0
		.amdhsa_system_sgpr_workgroup_id_z 0
		.amdhsa_system_sgpr_workgroup_info 0
		.amdhsa_system_vgpr_workitem_id 2
		.amdhsa_next_free_vgpr 256
		.amdhsa_next_free_sgpr 102
		.amdhsa_accum_offset 256
		.amdhsa_reserve_vcc 1
		.amdhsa_float_round_mode_32 0
		.amdhsa_float_round_mode_16_64 0
		.amdhsa_float_denorm_mode_32 3
		.amdhsa_float_denorm_mode_16_64 3
		.amdhsa_dx10_clamp 1
		.amdhsa_ieee_mode 1
		.amdhsa_fp16_overflow 0
		.amdhsa_tg_split 0
		.amdhsa_exception_fp_ieee_invalid_op 0
		.amdhsa_exception_fp_denorm_src 0
		.amdhsa_exception_fp_ieee_div_zero 0
		.amdhsa_exception_fp_ieee_overflow 0
		.amdhsa_exception_fp_ieee_underflow 0
		.amdhsa_exception_fp_ieee_inexact 0
		.amdhsa_exception_int_div_zero 0
	.end_amdhsa_kernel

amdhsa.kernels:
  - .agpr_count:     0
    .args:
      - .offset:         0
        .size:           200
        .value_kind:     by_value
      - .offset:         200
        .size:           4
        .value_kind:     hidden_block_count_x
      - .offset:         204
        .size:           4
        .value_kind:     hidden_block_count_y
      - .offset:         208
        .size:           4
        .value_kind:     hidden_block_count_z
      - .offset:         212
        .size:           2
        .value_kind:     hidden_group_size_x
      - .offset:         214
        .size:           2
        .value_kind:     hidden_group_size_y
      - .offset:         216
        .size:           2
        .value_kind:     hidden_group_size_z
      - .offset:         218
        .size:           2
        .value_kind:     hidden_remainder_x
      - .offset:         220
        .size:           2
        .value_kind:     hidden_remainder_y
      - .offset:         222
        .size:           2
        .value_kind:     hidden_remainder_z
      - .offset:         240
        .size:           8
        .value_kind:     hidden_global_offset_x
      - .offset:         248
        .size:           8
        .value_kind:     hidden_global_offset_y
      - .offset:         256
        .size:           8
        .value_kind:     hidden_global_offset_z
      - .offset:         264
        .size:           2
        .value_kind:     hidden_grid_dims
      - .offset:         288
        .size:           8
        .value_kind:     hidden_multigrid_sync_arg
      - .offset:         320
        .size:           4
        .value_kind:     hidden_dynamic_lds_size
    .group_segment_fixed_size: 0
    .kernarg_segment_align: 8
    .kernarg_segment_size: 456
    .language:       OpenCL C
    .language_version:
      - 2
      - 0
    .max_flat_workgroup_size: 512
    .name:           _Z14fwd_megakernel6Params
    .private_segment_fixed_size: 0
    .sgpr_count:     108
    .sgpr_spill_count: 3
    .symbol:         _Z14fwd_megakernel6Params.kd
    .uniform_work_group_size: 1
    .uses_dynamic_stack: false
    .vgpr_count:     256
    .vgpr_spill_count: 0
    .wavefront_size: 64
